# also own the split-K sample-row tile bodies (de-serialized residual loads) and store w_o/w_xo/w_down interleaved so every GEMM B operand is fetched as full 128-B lines
# speedup vs baseline: 1.1214x; 1.0341x over previous
; #define LAS __attribute__((address_space(3)))
; DEVI int tidx() { int t = threadIdx.x; asm volatile("" : "+v"(t)); return t; }
;   const int tid = tidx(), lane = tid & 63, wid = tid >> 6;
;   const int wm = wid >> 1, wn = wid & 1, r16 = lane & 15, quad = lane >> 4;
;   f32x4 acc[4][8];
; #pragma unroll
;   for (int i = 0; i < 4; i++)
; #pragma unroll
;     for (int j = 0; j < 8; j++) acc[i][j] = (f32x4){0.f, 0.f, 0.f, 0.f};
;   const int nk = (nk_part < 0) ? (K >> 5) : nk_part;
;   const int lrow = tid >> 2, lpc = tid & 3;
;   const int lch = lpc ^ ((0x78 >> (((lrow >> 2) & 3) * 2)) & 3);
;   const u16* ga = A + (size_t)(m0 + lrow) * lda + kbeg + lch * 8;
;   const u16* gb = Bt + (size_t)(n0 + lrow) * K + kbeg + lch * 8;
;   const size_t ga1 = (size_t)64 * lda, gb1 = (size_t)64 * K;
;   const unsigned lds0 = (unsigned)(uintptr_t)(LAS char*)smem + (unsigned)__builtin_amdgcn_readfirstlane(wid) * 1024u;
;     ...
;   __syncthreads();
;   G2_STAGE(0); G2_STAGE(1);
;   const int fsw = (0x78 >> (((r16 >> 2) & 3) * 2)) & 3;
;   const int aoff = (wm * 128 + r16) * 64 + ((quad ^ fsw) << 4);
;   const int boff = 16384 + (wn * 64 + r16) * 64 + ((quad ^ fsw) << 4);
; DEVI void run_phase(const Params& p, int ph, char* smem) {
;     ...
;           const int u_ = t - 512, tl_ = u_ / 11, q_ = u_ - tl_ * 11;
;           gemm_tile256<EPI_RESID_ATOMIC>(p, hb, DFF, Bt, DFF, (64 + (tl_ & 1)) * 256, (tl_ >> 1) * 128, nullptr, 0, smem, q_ * 256, 8, q_);
.LBB0_42:
	s_cmpk_gt_i32 s38, 0x1ff
	s_mov_b64 s[2:3], -1
	s_cbranch_scc0 .LBB0_116
	s_sub_i32 s46, s38, 512
	s_mul_i32 s45, s46, 373
	s_lshr_b32 s45, s45, 12
	s_mul_i32 s47, s45, 11
	s_sub_i32 s47, s46, s47
	s_lshr_b32 s42, s45, 1
	s_and_b32 s45, s45, 1
	s_add_i32 s45, s45, 64
	s_cmp_lt_u32 s45, 64
	s_cselect_b32 s44, 1, 0
	v_readlane_b32 s2, v250, 5
	v_readlane_b32 s3, v250, 6
	v_readlane_b32 s46, v254, 62
	s_mul_i32 s40, s45, 0x160000
	s_add_u32 s4, s2, s40
	s_addc_u32 s5, s3, 0
	s_add_u32 s4, s4, 0xef40000
	s_addc_u32 s5, s5, 0
	s_mul_i32 s40, s46, 0x580000
	s_mul_i32 s41, s42, 0xb0000
	s_add_i32 s40, s40, s41
	s_add_u32 s10, s2, s40
	s_addc_u32 s11, s3, 0
	s_add_u32 s10, s10, 0x19a00000
	s_addc_u32 s11, s11, 0
	s_mul_i32 s40, s47, 512
	s_add_u32 s4, s4, s40
	s_addc_u32 s5, s5, 0
	s_mul_i32 s40, s47, 1024
	s_add_u32 s10, s10, s40
	s_addc_u32 s11, s11, 0
	s_movk_i32 s39, 0x78
	v_lshrrev_b32_e32 v0, 2, v145
	v_and_b32_e32 v131, 3, v145
	v_bfe_u32 v136, v145, 4, 2
	v_lshlrev_b32_e32 v136, 1, v136
	v_lshrrev_b32_e64 v136, v136, s39
	v_and_b32_e32 v136, 3, v136
	v_xor_b32_e32 v131, v131, v136
	v_lshlrev_b32_e32 v131, 4, v131
	s_movk_i32 s41, 0x1600
	v_mad_u32_u24 v0, v0, s41, v131
	v_bfe_u32 v137, v145, 2, 1
	s_movk_i32 s41, 0x15c0
	v_mul_u32_u24_e32 v136, s41, v137
	v_sub_u32_e32 v136, v0, v136
	v_mov_b32_e32 v137, 0
	v_lshl_add_u64 v[134:135], s[10:11], 0, v[136:137]
	v_bfe_u32 v137, v145, 2, 1
	s_mul_i32 s41, s44, 0x15c0
	v_mul_u32_u24_e32 v136, s41, v137
	v_sub_u32_e32 v0, v0, v136
	s_lshl_b32 s12, s44, 6
	s_add_i32 s12, s12, 64
	s_mov_b32 s13, 0
	v_lshl_add_u64 v[132:133], s[4:5], 0, v[0:1]
	v_bfe_u32 v136, v145, 2, 2
	v_lshlrev_b32_e32 v136, 1, v136
	v_lshrrev_b32_e64 v136, v136, s39
	v_and_b32_e32 v136, 3, v136
	v_bfe_u32 v137, v145, 4, 2
	v_xor_b32_e32 v136, v136, v137
	v_lshlrev_b32_e32 v136, 4, v136
	v_and_b32_e32 v131, 15, v145
	v_lshl_or_b32 v136, v131, 6, v136
	v_bfe_u32 v137, v145, 6, 1
	v_lshl_or_b32 v137, v137, 12, v136
	v_lshrrev_b32_e32 v0, 7, v145
	v_lshl_or_b32 v136, v0, 13, v136
	v_and_b32_e32 v140, 1, v131
	v_lshl_or_b32 v131, v0, 7, v131
	v_bfe_u32 v0, v145, 4, 2
	v_lshlrev_b32_e32 v0, 3, v0
	v_bfe_u32 v141, v145, 6, 1
	s_lshl_b32 s40, s45, 19
	s_lshl_b32 s41, s42, 8
	s_add_i32 s40, s40, s41
	s_add_u32 s4, s2, s40
	s_addc_u32 s5, s3, 0
	s_add_u32 s4, s4, 0x4200000
	s_addc_u32 s5, s5, 0
	v_lshlrev_b32_e32 v138, 11, v131
	v_lshl_add_u32 v138, v141, 7, v138
	v_add_u32_e32 v138, v138, v0
	v_mov_b32_e32 v139, 0
	v_lshl_add_u64 v[138:139], s[4:5], 0, v[138:139]
	s_and_b32 s40, s45, 1
	s_lshl_b32 s40, s40, 20
	s_lshl_b32 s41, s47, 21
	s_add_i32 s40, s40, s41
	s_lshl_b32 s41, s42, 9
	s_add_i32 s40, s40, s41
	s_add_u32 s10, s2, s40
	s_addc_u32 s11, s3, 0
	s_add_u32 s10, s10, 0x1dcc0000
	s_addc_u32 s11, s11, 0
	v_lshlrev_b32_e32 v140, 12, v131
	v_lshl_add_u32 v140, v141, 8, v140
	v_lshl_add_u32 v140, v0, 1, v140
	v_mov_b32_e32 v141, 0
	v_lshl_add_u64 v[140:141], s[10:11], 0, v[140:141]
	s_mov_b32 s2, 0x58000
	s_mov_b32 s3, 0
	v_lshrrev_b32_e32 v0, 6, v145
	v_lshlrev_b32_e32 v0, 10, v0
	s_nop 0
	v_readfirstlane_b32 s46, v0
	s_mov_b32 s43, m0
	s_mov_b32 s4, 128
	s_mov_b32 s5, 0
	v_mov_b32_e32 v2, 0
	v_mov_b32_e32 v3, 0
	v_mov_b32_e32 v4, 0
	v_mov_b32_e32 v5, 0
	v_mov_b32_e32 v6, 0
	v_mov_b32_e32 v7, 0
	v_mov_b32_e32 v8, 0
	v_mov_b32_e32 v9, 0
	v_mov_b32_e32 v10, 0
	v_mov_b32_e32 v11, 0
	v_mov_b32_e32 v12, 0
	v_mov_b32_e32 v13, 0
	v_mov_b32_e32 v14, 0
	v_mov_b32_e32 v15, 0
	v_mov_b32_e32 v16, 0
	v_mov_b32_e32 v17, 0
	v_mov_b32_e32 v18, 0
	v_mov_b32_e32 v19, 0
	v_mov_b32_e32 v20, 0
	v_mov_b32_e32 v21, 0
	v_mov_b32_e32 v22, 0
	v_mov_b32_e32 v23, 0
	v_mov_b32_e32 v24, 0
	v_mov_b32_e32 v25, 0
	v_mov_b32_e32 v26, 0
	v_mov_b32_e32 v27, 0
	v_mov_b32_e32 v28, 0
	v_mov_b32_e32 v29, 0
	v_mov_b32_e32 v30, 0
	v_mov_b32_e32 v31, 0
	v_mov_b32_e32 v32, 0
	v_mov_b32_e32 v33, 0
	v_mov_b32_e32 v34, 0
	v_mov_b32_e32 v35, 0
	v_mov_b32_e32 v36, 0
	v_mov_b32_e32 v37, 0
	v_mov_b32_e32 v38, 0
	v_mov_b32_e32 v39, 0
	v_mov_b32_e32 v40, 0
	v_mov_b32_e32 v41, 0
	v_mov_b32_e32 v42, 0
	v_mov_b32_e32 v43, 0
	v_mov_b32_e32 v44, 0
	v_mov_b32_e32 v45, 0
	v_mov_b32_e32 v46, 0
	v_mov_b32_e32 v47, 0
	v_mov_b32_e32 v48, 0
	v_mov_b32_e32 v49, 0
	v_mov_b32_e32 v50, 0
	v_mov_b32_e32 v51, 0
	v_mov_b32_e32 v52, 0
	v_mov_b32_e32 v53, 0
	v_mov_b32_e32 v54, 0
	v_mov_b32_e32 v55, 0
	v_mov_b32_e32 v56, 0
	v_mov_b32_e32 v57, 0
	v_mov_b32_e32 v58, 0
	v_mov_b32_e32 v59, 0
	v_mov_b32_e32 v60, 0
	v_mov_b32_e32 v61, 0
	v_mov_b32_e32 v62, 0
	v_mov_b32_e32 v63, 0
	v_mov_b32_e32 v64, 0
	v_mov_b32_e32 v65, 0
	v_mov_b32_e32 v66, 0
	v_mov_b32_e32 v67, 0
	v_mov_b32_e32 v68, 0
	v_mov_b32_e32 v69, 0
	v_mov_b32_e32 v70, 0
	v_mov_b32_e32 v71, 0
	v_mov_b32_e32 v72, 0
	v_mov_b32_e32 v73, 0
	v_mov_b32_e32 v74, 0
	v_mov_b32_e32 v75, 0
	v_mov_b32_e32 v76, 0
	v_mov_b32_e32 v77, 0
	v_mov_b32_e32 v78, 0
	v_mov_b32_e32 v79, 0
	v_mov_b32_e32 v80, 0
	v_mov_b32_e32 v81, 0
	v_mov_b32_e32 v82, 0
	v_mov_b32_e32 v83, 0
	v_mov_b32_e32 v84, 0
	v_mov_b32_e32 v85, 0
	v_mov_b32_e32 v86, 0
	v_mov_b32_e32 v87, 0
	v_mov_b32_e32 v88, 0
	v_mov_b32_e32 v89, 0
	v_mov_b32_e32 v90, 0
	v_mov_b32_e32 v91, 0
	v_mov_b32_e32 v92, 0
	v_mov_b32_e32 v93, 0
	v_mov_b32_e32 v94, 0
	v_mov_b32_e32 v95, 0
	v_mov_b32_e32 v96, 0
	v_mov_b32_e32 v97, 0
	v_mov_b32_e32 v98, 0
	v_mov_b32_e32 v99, 0
	v_mov_b32_e32 v100, 0
	v_mov_b32_e32 v101, 0
	v_mov_b32_e32 v102, 0
	v_mov_b32_e32 v103, 0
	v_mov_b32_e32 v104, 0
	v_mov_b32_e32 v105, 0
	v_mov_b32_e32 v106, 0
	v_mov_b32_e32 v107, 0
	v_mov_b32_e32 v108, 0
	v_mov_b32_e32 v109, 0
	v_mov_b32_e32 v110, 0
	v_mov_b32_e32 v111, 0
	v_mov_b32_e32 v112, 0
	v_mov_b32_e32 v113, 0
	v_mov_b32_e32 v114, 0
	v_mov_b32_e32 v115, 0
	v_mov_b32_e32 v116, 0
	v_mov_b32_e32 v117, 0
	v_mov_b32_e32 v118, 0
	v_mov_b32_e32 v119, 0
	v_mov_b32_e32 v120, 0
	v_mov_b32_e32 v121, 0
	v_mov_b32_e32 v122, 0
	v_mov_b32_e32 v123, 0
	v_mov_b32_e32 v124, 0
	v_mov_b32_e32 v125, 0
	v_mov_b32_e32 v126, 0
	v_mov_b32_e32 v127, 0
	v_mov_b32_e32 v128, 0
	v_mov_b32_e32 v129, 0
	s_barrier
;     ...
;   __syncthreads();
;   G2_STAGE(0); G2_STAGE(1);
;   const int fsw = (0x78 >> (((r16 >> 2) & 3) * 2)) & 3;
;   const int aoff = (wm * 128 + r16) * 64 + ((quad ^ fsw) << 4);
;   const int boff = 16384 + (wn * 64 + r16) * 64 + ((quad ^ fsw) << 4);
;   for (int kt = 0; kt < nk; kt++) {
;     if (kt + 1 < nk) asm volatile("s_waitcnt vmcnt(6)" ::: "memory");
;     else asm volatile("s_waitcnt vmcnt(0)" ::: "memory");
;     __builtin_amdgcn_s_barrier();
;     asm volatile("" ::: "memory");
;     if (kt + 2 < nk) G2_STAGE(kt + 2);
;     const char* cS = smem + (kt % 3) * 24576;
;     bf16x8 xa[8], wb[4];
; #pragma unroll
;     for (int f = 0; f < 8; f++) xa[f] = *(const bf16x8*)(cS + aoff + f * 1024);
; #pragma unroll
;     for (int f = 0; f < 4; f++) wb[f] = *(const bf16x8*)(cS + boff + f * 1024);
; #pragma unroll
;     for (int nf = 0; nf < 4; nf++)
; #pragma unroll
;       for (int mf = 0; mf < 8; mf++)
;         acc[nf][mf] = __builtin_amdgcn_mfma_f32_16x16x32_bf16(wb[nf], xa[mf], acc[nf][mf], 0, 0, 0);
;   }
	s_add_i32 s42, s46, 0x0
	s_mov_b32 m0, s42
	v_lshl_add_u64 v[142:143], v[132:133], 0, s[2:3]
	global_load_lds_dwordx4 v[132:133], off
	s_addk_i32 m0, 0x1000
	s_nop 0
	global_load_lds_dwordx4 v[142:143], off
	v_lshl_add_u64 v[142:143], v[142:143], 0, s[2:3]
	s_addk_i32 m0, 0x1000
	s_nop 0
	global_load_lds_dwordx4 v[142:143], off
	v_lshl_add_u64 v[142:143], v[142:143], 0, s[2:3]
	s_addk_i32 m0, 0x1000
	s_nop 0
	global_load_lds_dwordx4 v[142:143], off
	s_addk_i32 m0, 0x1000
	v_lshl_add_u64 v[142:143], v[134:135], 0, s[2:3]
	s_nop 0
	global_load_lds_dwordx4 v[134:135], off
	s_addk_i32 m0, 0x1000
	v_lshl_add_u64 v[132:133], v[132:133], 0, s[12:13]
	s_nop 0
	global_load_lds_dwordx4 v[142:143], off
	v_lshl_add_u64 v[134:135], v[134:135], 0, s[4:5]
	s_nop 0
	s_add_i32 s42, s46, 0x6000
	s_mov_b32 m0, s42
	v_lshl_add_u64 v[142:143], v[132:133], 0, s[2:3]
	global_load_lds_dwordx4 v[132:133], off
	s_addk_i32 m0, 0x1000
	s_nop 0
	global_load_lds_dwordx4 v[142:143], off
	v_lshl_add_u64 v[142:143], v[142:143], 0, s[2:3]
	s_addk_i32 m0, 0x1000
	s_nop 0
	global_load_lds_dwordx4 v[142:143], off
	v_lshl_add_u64 v[142:143], v[142:143], 0, s[2:3]
	s_addk_i32 m0, 0x1000
	s_nop 0
	global_load_lds_dwordx4 v[142:143], off
	s_addk_i32 m0, 0x1000
	v_lshl_add_u64 v[142:143], v[134:135], 0, s[2:3]
	s_nop 0
	global_load_lds_dwordx4 v[134:135], off
	s_addk_i32 m0, 0x1000
	v_lshl_add_u64 v[132:133], v[132:133], 0, s[12:13]
	s_nop 0
	global_load_lds_dwordx4 v[142:143], off
	v_lshl_add_u64 v[134:135], v[134:135], 0, s[4:5]
	s_nop 0
	s_add_i32 s42, s46, 0xc000
	s_mov_b32 m0, s42
	v_lshl_add_u64 v[142:143], v[132:133], 0, s[2:3]
	global_load_lds_dwordx4 v[132:133], off
	s_addk_i32 m0, 0x1000
	s_nop 0
	global_load_lds_dwordx4 v[142:143], off
	v_lshl_add_u64 v[142:143], v[142:143], 0, s[2:3]
	s_addk_i32 m0, 0x1000
	s_nop 0
	global_load_lds_dwordx4 v[142:143], off
	v_lshl_add_u64 v[142:143], v[142:143], 0, s[2:3]
	s_addk_i32 m0, 0x1000
	s_nop 0
	global_load_lds_dwordx4 v[142:143], off
	s_addk_i32 m0, 0x1000
	v_lshl_add_u64 v[142:143], v[134:135], 0, s[2:3]
	s_nop 0
	global_load_lds_dwordx4 v[134:135], off
	s_addk_i32 m0, 0x1000
	v_lshl_add_u64 v[132:133], v[132:133], 0, s[12:13]
	s_nop 0
	global_load_lds_dwordx4 v[142:143], off
	v_lshl_add_u64 v[134:135], v[134:135], 0, s[4:5]
	s_nop 0
	s_waitcnt vmcnt(12)
	s_barrier
	ds_read_b128 v[146:149], v136 offset:0
	ds_read_b128 v[152:155], v136 offset:1024
	ds_read_b128 v[156:159], v136 offset:2048
	ds_read_b128 v[162:165], v136 offset:3072
	ds_read_b128 v[166:169], v136 offset:4096
	ds_read_b128 v[170:173], v136 offset:5120
	ds_read_b128 v[176:179], v136 offset:6144
	ds_read_b128 v[180:183], v136 offset:7168
	ds_read_b128 v[184:187], v137 offset:16384
	ds_read_b128 v[188:191], v137 offset:17408
	ds_read_b128 v[192:195], v137 offset:18432
	ds_read_b128 v[196:199], v137 offset:19456
	s_movk_i32 s40, 0x6000
	s_mov_b32 s41, 0
	s_movk_i32 s39, 2
.Lta11_loop:
	s_waitcnt vmcnt(6) lgkmcnt(0)
	s_barrier
	v_add_u32_e32 v144, s40, v136
	v_mfma_f32_16x16x32_bf16 v[126:129], v[184:187], v[146:149], v[126:129]
	ds_read_b128 v[200:203], v144 offset:0
	v_mfma_f32_16x16x32_bf16 v[122:125], v[184:187], v[152:155], v[122:125]
	ds_read_b128 v[204:207], v144 offset:1024
	v_mfma_f32_16x16x32_bf16 v[118:121], v[184:187], v[156:159], v[118:121]
	ds_read_b128 v[208:211], v144 offset:2048
	v_mfma_f32_16x16x32_bf16 v[114:117], v[184:187], v[162:165], v[114:117]
	ds_read_b128 v[212:215], v144 offset:3072
	v_mfma_f32_16x16x32_bf16 v[110:113], v[184:187], v[166:169], v[110:113]
	ds_read_b128 v[216:219], v144 offset:4096
	v_mfma_f32_16x16x32_bf16 v[106:109], v[184:187], v[170:173], v[106:109]
	ds_read_b128 v[220:223], v144 offset:5120
	v_mfma_f32_16x16x32_bf16 v[102:105], v[184:187], v[176:179], v[102:105]
	ds_read_b128 v[224:227], v144 offset:6144
	v_mfma_f32_16x16x32_bf16 v[98:101], v[184:187], v[180:183], v[98:101]
	ds_read_b128 v[228:231], v144 offset:7168
	v_mfma_f32_16x16x32_bf16 v[94:97], v[188:191], v[146:149], v[94:97]
	v_add_u32_e32 v144, s40, v137
	v_mfma_f32_16x16x32_bf16 v[90:93], v[188:191], v[152:155], v[90:93]
	v_mfma_f32_16x16x32_bf16 v[86:89], v[188:191], v[156:159], v[86:89]
	ds_read_b128 v[232:235], v144 offset:16384
	v_mfma_f32_16x16x32_bf16 v[82:85], v[188:191], v[162:165], v[82:85]
	ds_read_b128 v[236:239], v144 offset:17408
	v_mfma_f32_16x16x32_bf16 v[78:81], v[188:191], v[166:169], v[78:81]
	ds_read_b128 v[240:243], v144 offset:18432
	v_mfma_f32_16x16x32_bf16 v[74:77], v[188:191], v[170:173], v[74:77]
	ds_read_b128 v[244:247], v144 offset:19456
	s_add_i32 s42, s46, s41
	v_mfma_f32_16x16x32_bf16 v[70:73], v[188:191], v[176:179], v[70:73]
	s_mov_b32 m0, s42
	v_lshl_add_u64 v[142:143], v[132:133], 0, s[2:3]
	v_mfma_f32_16x16x32_bf16 v[66:69], v[188:191], v[180:183], v[66:69]
	global_load_lds_dwordx4 v[132:133], off
	s_addk_i32 m0, 0x1000
	v_mfma_f32_16x16x32_bf16 v[62:65], v[192:195], v[146:149], v[62:65]
	v_mfma_f32_16x16x32_bf16 v[58:61], v[192:195], v[152:155], v[58:61]
	v_mfma_f32_16x16x32_bf16 v[54:57], v[192:195], v[156:159], v[54:57]
	global_load_lds_dwordx4 v[142:143], off
	v_lshl_add_u64 v[142:143], v[142:143], 0, s[2:3]
	s_addk_i32 m0, 0x1000
	v_mfma_f32_16x16x32_bf16 v[50:53], v[192:195], v[162:165], v[50:53]
	v_mfma_f32_16x16x32_bf16 v[46:49], v[192:195], v[166:169], v[46:49]
	v_mfma_f32_16x16x32_bf16 v[42:45], v[192:195], v[170:173], v[42:45]
	global_load_lds_dwordx4 v[142:143], off
	v_lshl_add_u64 v[142:143], v[142:143], 0, s[2:3]
	s_addk_i32 m0, 0x1000
	v_mfma_f32_16x16x32_bf16 v[38:41], v[192:195], v[176:179], v[38:41]
	v_mfma_f32_16x16x32_bf16 v[34:37], v[192:195], v[180:183], v[34:37]
	v_mfma_f32_16x16x32_bf16 v[30:33], v[196:199], v[146:149], v[30:33]
	global_load_lds_dwordx4 v[142:143], off
	s_addk_i32 m0, 0x1000
	v_lshl_add_u64 v[142:143], v[134:135], 0, s[2:3]
	v_mfma_f32_16x16x32_bf16 v[26:29], v[196:199], v[152:155], v[26:29]
	v_mfma_f32_16x16x32_bf16 v[22:25], v[196:199], v[156:159], v[22:25]
	v_mfma_f32_16x16x32_bf16 v[18:21], v[196:199], v[162:165], v[18:21]
	global_load_lds_dwordx4 v[134:135], off
	s_addk_i32 m0, 0x1000
	v_lshl_add_u64 v[132:133], v[132:133], 0, s[12:13]
	v_mfma_f32_16x16x32_bf16 v[14:17], v[196:199], v[166:169], v[14:17]
	v_mfma_f32_16x16x32_bf16 v[10:13], v[196:199], v[170:173], v[10:13]
	v_mfma_f32_16x16x32_bf16 v[6:9], v[196:199], v[176:179], v[6:9]
	global_load_lds_dwordx4 v[142:143], off
	v_lshl_add_u64 v[134:135], v[134:135], 0, s[4:5]
	v_mfma_f32_16x16x32_bf16 v[2:5], v[196:199], v[180:183], v[2:5]
	s_mov_b32 s41, s40
	s_add_i32 s40, s40, 0x6000
	s_cmp_eq_u32 s40, 0x12000
	s_cselect_b32 s40, 0, s40
	s_waitcnt vmcnt(6) lgkmcnt(0)
	s_barrier
;     ...
;   __syncthreads();
;   G2_STAGE(0); G2_STAGE(1);
;   const int fsw = (0x78 >> (((r16 >> 2) & 3) * 2)) & 3;
;   const int aoff = (wm * 128 + r16) * 64 + ((quad ^ fsw) << 4);
;   const int boff = 16384 + (wn * 64 + r16) * 64 + ((quad ^ fsw) << 4);
;   for (int kt = 0; kt < nk; kt++) {
;     if (kt + 1 < nk) asm volatile("s_waitcnt vmcnt(6)" ::: "memory");
;     else asm volatile("s_waitcnt vmcnt(0)" ::: "memory");
;     __builtin_amdgcn_s_barrier();
;     asm volatile("" ::: "memory");
;     if (kt + 2 < nk) G2_STAGE(kt + 2);
;     const char* cS = smem + (kt % 3) * 24576;
;     bf16x8 xa[8], wb[4];
; #pragma unroll
;     for (int f = 0; f < 8; f++) xa[f] = *(const bf16x8*)(cS + aoff + f * 1024);
; #pragma unroll
;     for (int f = 0; f < 4; f++) wb[f] = *(const bf16x8*)(cS + boff + f * 1024);
; #pragma unroll
;     for (int nf = 0; nf < 4; nf++)
; #pragma unroll
;       for (int mf = 0; mf < 8; mf++)
;         acc[nf][mf] = __builtin_amdgcn_mfma_f32_16x16x32_bf16(wb[nf], xa[mf], acc[nf][mf], 0, 0, 0);
;   }
	v_add_u32_e32 v144, s40, v136
	v_mfma_f32_16x16x32_bf16 v[126:129], v[232:235], v[200:203], v[126:129]
	ds_read_b128 v[146:149], v144 offset:0
	v_mfma_f32_16x16x32_bf16 v[122:125], v[232:235], v[204:207], v[122:125]
	ds_read_b128 v[152:155], v144 offset:1024
	v_mfma_f32_16x16x32_bf16 v[118:121], v[232:235], v[208:211], v[118:121]
	ds_read_b128 v[156:159], v144 offset:2048
	v_mfma_f32_16x16x32_bf16 v[114:117], v[232:235], v[212:215], v[114:117]
	ds_read_b128 v[162:165], v144 offset:3072
	v_mfma_f32_16x16x32_bf16 v[110:113], v[232:235], v[216:219], v[110:113]
	ds_read_b128 v[166:169], v144 offset:4096
	v_mfma_f32_16x16x32_bf16 v[106:109], v[232:235], v[220:223], v[106:109]
	ds_read_b128 v[170:173], v144 offset:5120
	v_mfma_f32_16x16x32_bf16 v[102:105], v[232:235], v[224:227], v[102:105]
	ds_read_b128 v[176:179], v144 offset:6144
	v_mfma_f32_16x16x32_bf16 v[98:101], v[232:235], v[228:231], v[98:101]
	ds_read_b128 v[180:183], v144 offset:7168
	v_mfma_f32_16x16x32_bf16 v[94:97], v[236:239], v[200:203], v[94:97]
	v_add_u32_e32 v144, s40, v137
	v_mfma_f32_16x16x32_bf16 v[90:93], v[236:239], v[204:207], v[90:93]
	v_mfma_f32_16x16x32_bf16 v[86:89], v[236:239], v[208:211], v[86:89]
	ds_read_b128 v[184:187], v144 offset:16384
	v_mfma_f32_16x16x32_bf16 v[82:85], v[236:239], v[212:215], v[82:85]
	ds_read_b128 v[188:191], v144 offset:17408
	v_mfma_f32_16x16x32_bf16 v[78:81], v[236:239], v[216:219], v[78:81]
	ds_read_b128 v[192:195], v144 offset:18432
	v_mfma_f32_16x16x32_bf16 v[74:77], v[236:239], v[220:223], v[74:77]
	ds_read_b128 v[196:199], v144 offset:19456
	s_add_i32 s42, s46, s41
	v_mfma_f32_16x16x32_bf16 v[70:73], v[236:239], v[224:227], v[70:73]
	s_mov_b32 m0, s42
	v_lshl_add_u64 v[142:143], v[132:133], 0, s[2:3]
	v_mfma_f32_16x16x32_bf16 v[66:69], v[236:239], v[228:231], v[66:69]
	global_load_lds_dwordx4 v[132:133], off
	s_addk_i32 m0, 0x1000
	v_mfma_f32_16x16x32_bf16 v[62:65], v[240:243], v[200:203], v[62:65]
	v_mfma_f32_16x16x32_bf16 v[58:61], v[240:243], v[204:207], v[58:61]
	v_mfma_f32_16x16x32_bf16 v[54:57], v[240:243], v[208:211], v[54:57]
	global_load_lds_dwordx4 v[142:143], off
	v_lshl_add_u64 v[142:143], v[142:143], 0, s[2:3]
	s_addk_i32 m0, 0x1000
	v_mfma_f32_16x16x32_bf16 v[50:53], v[240:243], v[212:215], v[50:53]
	v_mfma_f32_16x16x32_bf16 v[46:49], v[240:243], v[216:219], v[46:49]
	v_mfma_f32_16x16x32_bf16 v[42:45], v[240:243], v[220:223], v[42:45]
	global_load_lds_dwordx4 v[142:143], off
	v_lshl_add_u64 v[142:143], v[142:143], 0, s[2:3]
	s_addk_i32 m0, 0x1000
	v_mfma_f32_16x16x32_bf16 v[38:41], v[240:243], v[224:227], v[38:41]
	v_mfma_f32_16x16x32_bf16 v[34:37], v[240:243], v[228:231], v[34:37]
	v_mfma_f32_16x16x32_bf16 v[30:33], v[244:247], v[200:203], v[30:33]
	global_load_lds_dwordx4 v[142:143], off
	s_addk_i32 m0, 0x1000
	v_lshl_add_u64 v[142:143], v[134:135], 0, s[2:3]
	v_mfma_f32_16x16x32_bf16 v[26:29], v[244:247], v[204:207], v[26:29]
	v_mfma_f32_16x16x32_bf16 v[22:25], v[244:247], v[208:211], v[22:25]
	v_mfma_f32_16x16x32_bf16 v[18:21], v[244:247], v[212:215], v[18:21]
	global_load_lds_dwordx4 v[134:135], off
	s_addk_i32 m0, 0x1000
	v_lshl_add_u64 v[132:133], v[132:133], 0, s[12:13]
	v_mfma_f32_16x16x32_bf16 v[14:17], v[244:247], v[216:219], v[14:17]
	v_mfma_f32_16x16x32_bf16 v[10:13], v[244:247], v[220:223], v[10:13]
	v_mfma_f32_16x16x32_bf16 v[6:9], v[244:247], v[224:227], v[6:9]
	global_load_lds_dwordx4 v[142:143], off
	v_lshl_add_u64 v[134:135], v[134:135], 0, s[4:5]
	v_mfma_f32_16x16x32_bf16 v[2:5], v[244:247], v[228:231], v[2:5]
	s_mov_b32 s41, s40
	s_add_i32 s40, s40, 0x6000
	s_cmp_eq_u32 s40, 0x12000
	s_cselect_b32 s40, 0, s40
	s_sub_i32 s39, s39, 1
	s_cmp_lg_u32 s39, 0
	s_cbranch_scc1 .Lta11_loop
	s_waitcnt vmcnt(6) lgkmcnt(0)
	s_barrier
	v_add_u32_e32 v144, s40, v136
	v_mfma_f32_16x16x32_bf16 v[126:129], v[184:187], v[146:149], v[126:129]
	ds_read_b128 v[200:203], v144 offset:0
	v_mfma_f32_16x16x32_bf16 v[122:125], v[184:187], v[152:155], v[122:125]
	ds_read_b128 v[204:207], v144 offset:1024
	v_mfma_f32_16x16x32_bf16 v[118:121], v[184:187], v[156:159], v[118:121]
	ds_read_b128 v[208:211], v144 offset:2048
	v_mfma_f32_16x16x32_bf16 v[114:117], v[184:187], v[162:165], v[114:117]
	ds_read_b128 v[212:215], v144 offset:3072
	v_mfma_f32_16x16x32_bf16 v[110:113], v[184:187], v[166:169], v[110:113]
	ds_read_b128 v[216:219], v144 offset:4096
	v_mfma_f32_16x16x32_bf16 v[106:109], v[184:187], v[170:173], v[106:109]
	ds_read_b128 v[220:223], v144 offset:5120
	v_mfma_f32_16x16x32_bf16 v[102:105], v[184:187], v[176:179], v[102:105]
	ds_read_b128 v[224:227], v144 offset:6144
	v_mfma_f32_16x16x32_bf16 v[98:101], v[184:187], v[180:183], v[98:101]
	ds_read_b128 v[228:231], v144 offset:7168
	v_mfma_f32_16x16x32_bf16 v[94:97], v[188:191], v[146:149], v[94:97]
	v_add_u32_e32 v144, s40, v137
	v_mfma_f32_16x16x32_bf16 v[90:93], v[188:191], v[152:155], v[90:93]
	v_mfma_f32_16x16x32_bf16 v[86:89], v[188:191], v[156:159], v[86:89]
	ds_read_b128 v[232:235], v144 offset:16384
	v_mfma_f32_16x16x32_bf16 v[82:85], v[188:191], v[162:165], v[82:85]
	ds_read_b128 v[236:239], v144 offset:17408
	v_mfma_f32_16x16x32_bf16 v[78:81], v[188:191], v[166:169], v[78:81]
	ds_read_b128 v[240:243], v144 offset:18432
	v_mfma_f32_16x16x32_bf16 v[74:77], v[188:191], v[170:173], v[74:77]
	ds_read_b128 v[244:247], v144 offset:19456
	s_add_i32 s42, s46, s41
	v_mfma_f32_16x16x32_bf16 v[70:73], v[188:191], v[176:179], v[70:73]
	s_mov_b32 m0, s42
	v_lshl_add_u64 v[142:143], v[132:133], 0, s[2:3]
	v_mfma_f32_16x16x32_bf16 v[66:69], v[188:191], v[180:183], v[66:69]
	global_load_lds_dwordx4 v[132:133], off
	s_addk_i32 m0, 0x1000
	v_mfma_f32_16x16x32_bf16 v[62:65], v[192:195], v[146:149], v[62:65]
;     ...
;   __syncthreads();
;   G2_STAGE(0); G2_STAGE(1);
;   const int fsw = (0x78 >> (((r16 >> 2) & 3) * 2)) & 3;
;   const int aoff = (wm * 128 + r16) * 64 + ((quad ^ fsw) << 4);
;   const int boff = 16384 + (wn * 64 + r16) * 64 + ((quad ^ fsw) << 4);
;   for (int kt = 0; kt < nk; kt++) {
;     if (kt + 1 < nk) asm volatile("s_waitcnt vmcnt(6)" ::: "memory");
;     else asm volatile("s_waitcnt vmcnt(0)" ::: "memory");
;     __builtin_amdgcn_s_barrier();
;     asm volatile("" ::: "memory");
;     if (kt + 2 < nk) G2_STAGE(kt + 2);
;     const char* cS = smem + (kt % 3) * 24576;
;     bf16x8 xa[8], wb[4];
; #pragma unroll
;     for (int f = 0; f < 8; f++) xa[f] = *(const bf16x8*)(cS + aoff + f * 1024);
; #pragma unroll
;     for (int f = 0; f < 4; f++) wb[f] = *(const bf16x8*)(cS + boff + f * 1024);
; #pragma unroll
;     for (int nf = 0; nf < 4; nf++)
; #pragma unroll
;       for (int mf = 0; mf < 8; mf++)
;         acc[nf][mf] = __builtin_amdgcn_mfma_f32_16x16x32_bf16(wb[nf], xa[mf], acc[nf][mf], 0, 0, 0);
;   }
	v_mfma_f32_16x16x32_bf16 v[58:61], v[192:195], v[152:155], v[58:61]
	v_mfma_f32_16x16x32_bf16 v[54:57], v[192:195], v[156:159], v[54:57]
	global_load_lds_dwordx4 v[142:143], off
	v_lshl_add_u64 v[142:143], v[142:143], 0, s[2:3]
	s_addk_i32 m0, 0x1000
	v_mfma_f32_16x16x32_bf16 v[50:53], v[192:195], v[162:165], v[50:53]
	v_mfma_f32_16x16x32_bf16 v[46:49], v[192:195], v[166:169], v[46:49]
	v_mfma_f32_16x16x32_bf16 v[42:45], v[192:195], v[170:173], v[42:45]
	global_load_lds_dwordx4 v[142:143], off
	v_lshl_add_u64 v[142:143], v[142:143], 0, s[2:3]
	s_addk_i32 m0, 0x1000
	v_mfma_f32_16x16x32_bf16 v[38:41], v[192:195], v[176:179], v[38:41]
	v_mfma_f32_16x16x32_bf16 v[34:37], v[192:195], v[180:183], v[34:37]
	v_mfma_f32_16x16x32_bf16 v[30:33], v[196:199], v[146:149], v[30:33]
	global_load_lds_dwordx4 v[142:143], off
	s_addk_i32 m0, 0x1000
	v_lshl_add_u64 v[142:143], v[134:135], 0, s[2:3]
	v_mfma_f32_16x16x32_bf16 v[26:29], v[196:199], v[152:155], v[26:29]
	v_mfma_f32_16x16x32_bf16 v[22:25], v[196:199], v[156:159], v[22:25]
	v_mfma_f32_16x16x32_bf16 v[18:21], v[196:199], v[162:165], v[18:21]
	global_load_lds_dwordx4 v[134:135], off
	s_addk_i32 m0, 0x1000
	v_lshl_add_u64 v[132:133], v[132:133], 0, s[12:13]
	v_mfma_f32_16x16x32_bf16 v[14:17], v[196:199], v[166:169], v[14:17]
	v_mfma_f32_16x16x32_bf16 v[10:13], v[196:199], v[170:173], v[10:13]
	v_mfma_f32_16x16x32_bf16 v[6:9], v[196:199], v[176:179], v[6:9]
	global_load_lds_dwordx4 v[142:143], off
	v_lshl_add_u64 v[134:135], v[134:135], 0, s[4:5]
	v_mfma_f32_16x16x32_bf16 v[2:5], v[196:199], v[180:183], v[2:5]
	s_mov_b32 s41, s40
	s_add_i32 s40, s40, 0x6000
	s_cmp_eq_u32 s40, 0x12000
	s_cselect_b32 s40, 0, s40
	s_waitcnt vmcnt(6) lgkmcnt(0)
	s_barrier
	v_add_u32_e32 v144, s40, v136
	v_mfma_f32_16x16x32_bf16 v[126:129], v[232:235], v[200:203], v[126:129]
	ds_read_b128 v[146:149], v144 offset:0
	v_mfma_f32_16x16x32_bf16 v[122:125], v[232:235], v[204:207], v[122:125]
	ds_read_b128 v[152:155], v144 offset:1024
	v_mfma_f32_16x16x32_bf16 v[118:121], v[232:235], v[208:211], v[118:121]
	ds_read_b128 v[156:159], v144 offset:2048
	v_mfma_f32_16x16x32_bf16 v[114:117], v[232:235], v[212:215], v[114:117]
	ds_read_b128 v[162:165], v144 offset:3072
	v_mfma_f32_16x16x32_bf16 v[110:113], v[232:235], v[216:219], v[110:113]
	ds_read_b128 v[166:169], v144 offset:4096
	v_mfma_f32_16x16x32_bf16 v[106:109], v[232:235], v[220:223], v[106:109]
	ds_read_b128 v[170:173], v144 offset:5120
	v_mfma_f32_16x16x32_bf16 v[102:105], v[232:235], v[224:227], v[102:105]
	ds_read_b128 v[176:179], v144 offset:6144
	v_mfma_f32_16x16x32_bf16 v[98:101], v[232:235], v[228:231], v[98:101]
	ds_read_b128 v[180:183], v144 offset:7168
	v_mfma_f32_16x16x32_bf16 v[94:97], v[236:239], v[200:203], v[94:97]
	v_add_u32_e32 v144, s40, v137
	v_mfma_f32_16x16x32_bf16 v[90:93], v[236:239], v[204:207], v[90:93]
	v_mfma_f32_16x16x32_bf16 v[86:89], v[236:239], v[208:211], v[86:89]
	ds_read_b128 v[184:187], v144 offset:16384
	v_mfma_f32_16x16x32_bf16 v[82:85], v[236:239], v[212:215], v[82:85]
	ds_read_b128 v[188:191], v144 offset:17408
	v_mfma_f32_16x16x32_bf16 v[78:81], v[236:239], v[216:219], v[78:81]
	ds_read_b128 v[192:195], v144 offset:18432
	v_mfma_f32_16x16x32_bf16 v[74:77], v[236:239], v[220:223], v[74:77]
	ds_read_b128 v[196:199], v144 offset:19456
	v_mfma_f32_16x16x32_bf16 v[70:73], v[236:239], v[224:227], v[70:73]
	v_mfma_f32_16x16x32_bf16 v[66:69], v[236:239], v[228:231], v[66:69]
	v_mfma_f32_16x16x32_bf16 v[62:65], v[240:243], v[200:203], v[62:65]
	v_mfma_f32_16x16x32_bf16 v[58:61], v[240:243], v[204:207], v[58:61]
	v_mfma_f32_16x16x32_bf16 v[54:57], v[240:243], v[208:211], v[54:57]
	v_mfma_f32_16x16x32_bf16 v[50:53], v[240:243], v[212:215], v[50:53]
	v_mfma_f32_16x16x32_bf16 v[46:49], v[240:243], v[216:219], v[46:49]
	v_mfma_f32_16x16x32_bf16 v[42:45], v[240:243], v[220:223], v[42:45]
	v_mfma_f32_16x16x32_bf16 v[38:41], v[240:243], v[224:227], v[38:41]
	v_mfma_f32_16x16x32_bf16 v[34:37], v[240:243], v[228:231], v[34:37]
	v_mfma_f32_16x16x32_bf16 v[30:33], v[244:247], v[200:203], v[30:33]
	v_mfma_f32_16x16x32_bf16 v[26:29], v[244:247], v[204:207], v[26:29]
	v_mfma_f32_16x16x32_bf16 v[22:25], v[244:247], v[208:211], v[22:25]
	v_mfma_f32_16x16x32_bf16 v[18:21], v[244:247], v[212:215], v[18:21]
	v_mfma_f32_16x16x32_bf16 v[14:17], v[244:247], v[216:219], v[14:17]
	v_mfma_f32_16x16x32_bf16 v[10:13], v[244:247], v[220:223], v[10:13]
	v_mfma_f32_16x16x32_bf16 v[6:9], v[244:247], v[224:227], v[6:9]
	v_mfma_f32_16x16x32_bf16 v[2:5], v[244:247], v[228:231], v[2:5]
	s_mov_b32 s41, s40
	s_add_i32 s40, s40, 0x6000
	s_cmp_eq_u32 s40, 0x12000
	s_cselect_b32 s40, 0, s40
	s_waitcnt vmcnt(0) lgkmcnt(0)
	s_barrier
; DEVI unsigned pack2(float a, float b) { return __builtin_bit_cast(unsigned, __builtin_convertvector((f32x2_t){a, b}, bf16x2_t)); }
; DEVI float blo(unsigned u) { return __uint_as_float(u << 16); }
; DEVI float bhi(unsigned u) { return __uint_as_float(u & 0xffff0000u); }
;     ...
;   for (int kt = 0; kt < nk; kt++) {
;     if (kt + 1 < nk) asm volatile("s_waitcnt vmcnt(6)" ::: "memory");
;     else asm volatile("s_waitcnt vmcnt(0)" ::: "memory");
;     __builtin_amdgcn_s_barrier();
;     asm volatile("" ::: "memory");
;     if (kt + 2 < nk) G2_STAGE(kt + 2);
;     const char* cS = smem + (kt % 3) * 24576;
;     bf16x8 xa[8], wb[4];
; #pragma unroll
;     for (int f = 0; f < 8; f++) xa[f] = *(const bf16x8*)(cS + aoff + f * 1024);
; #pragma unroll
;     for (int f = 0; f < 4; f++) wb[f] = *(const bf16x8*)(cS + boff + f * 1024);
; #pragma unroll
;     for (int nf = 0; nf < 4; nf++)
; #pragma unroll
;       for (int mf = 0; mf < 8; mf++)
;         acc[nf][mf] = __builtin_amdgcn_mfma_f32_16x16x32_bf16(wb[nf], xa[mf], acc[nf][mf], 0, 0, 0);
;   }
;     ...
; #pragma unroll
;   for (int mf = 0; mf < 8; mf++) {
;     const int row = m0 + wm * 128 + mf * 16 + r16;
;     if (EPI == EPI_SWIGLU) {
; #pragma unroll
;       for (int nf = 0; nf < 2; nf++) {
;         const int hcol = (n0 >> 1) + wn * 32 + nf * 16 + quad * 4;
;         f32x4 g = acc[nf][mf], u = acc[nf + 2][mf];
;         u32x2 pk;
;         pk[0] = pack2(siluf_(g[0]) * u[0], siluf_(g[1]) * u[1]);
;         pk[1] = pack2(siluf_(g[2]) * u[2], siluf_(g[3]) * u[3]);
;         *(u32x2*)(outb + (size_t)row * DFF + hcol) = pk;
;       }
;     } else {
; #pragma unroll
;       for (int nf = 0; nf < 4; nf++) {
;         const int col = n0 + wn * 64 + nf * 16 + quad * 4;
;         f32x4 a = acc[nf][mf];
;         if (EPI == EPI_RESID || EPI == EPI_RESID_ATOMIC) {
;           f32x4 x = a;
;           if (EPI == EPI_RESID || kpart == 0) {
;             const u32x2 xr = *(const u32x2*)((const u16*)(p.ws + WS_XB) + (size_t)row * 1024 + col);
;             x[0] += ALPHA * blo(xr[0]); x[1] += ALPHA * bhi(xr[0]); x[2] += ALPHA * blo(xr[1]); x[3] += ALPHA * bhi(xr[1]);
;           }
;           if (EPI == EPI_RESID) *(f32x4*)((float*)(p.ws + WS_XF) + (size_t)row * 1024 + col) = x;
;           else *(f32x4*)((float*)(p.ws + WS_SLAB) + ((size_t)kpart * 512 + (row - T_P)) * 1024 + col) = x;
	v_add_u32_e32 v144, s40, v136
	v_mfma_f32_16x16x32_bf16 v[126:129], v[184:187], v[146:149], v[126:129]
	ds_read_b128 v[200:203], v144 offset:0
	v_mfma_f32_16x16x32_bf16 v[122:125], v[184:187], v[152:155], v[122:125]
	ds_read_b128 v[204:207], v144 offset:1024
	v_mfma_f32_16x16x32_bf16 v[118:121], v[184:187], v[156:159], v[118:121]
	ds_read_b128 v[208:211], v144 offset:2048
	v_mfma_f32_16x16x32_bf16 v[114:117], v[184:187], v[162:165], v[114:117]
	ds_read_b128 v[212:215], v144 offset:3072
	v_mfma_f32_16x16x32_bf16 v[110:113], v[184:187], v[166:169], v[110:113]
	ds_read_b128 v[216:219], v144 offset:4096
	v_mfma_f32_16x16x32_bf16 v[106:109], v[184:187], v[170:173], v[106:109]
	ds_read_b128 v[220:223], v144 offset:5120
	v_mfma_f32_16x16x32_bf16 v[102:105], v[184:187], v[176:179], v[102:105]
	ds_read_b128 v[224:227], v144 offset:6144
	v_mfma_f32_16x16x32_bf16 v[98:101], v[184:187], v[180:183], v[98:101]
	ds_read_b128 v[228:231], v144 offset:7168
	v_mfma_f32_16x16x32_bf16 v[94:97], v[188:191], v[146:149], v[94:97]
	v_add_u32_e32 v144, s40, v137
	v_mfma_f32_16x16x32_bf16 v[90:93], v[188:191], v[152:155], v[90:93]
	v_mfma_f32_16x16x32_bf16 v[86:89], v[188:191], v[156:159], v[86:89]
	ds_read_b128 v[232:235], v144 offset:16384
	v_mfma_f32_16x16x32_bf16 v[82:85], v[188:191], v[162:165], v[82:85]
	ds_read_b128 v[236:239], v144 offset:17408
	v_mfma_f32_16x16x32_bf16 v[78:81], v[188:191], v[166:169], v[78:81]
	ds_read_b128 v[240:243], v144 offset:18432
	v_mfma_f32_16x16x32_bf16 v[74:77], v[188:191], v[170:173], v[74:77]
	ds_read_b128 v[244:247], v144 offset:19456
	v_mfma_f32_16x16x32_bf16 v[70:73], v[188:191], v[176:179], v[70:73]
	v_mfma_f32_16x16x32_bf16 v[66:69], v[188:191], v[180:183], v[66:69]
	v_mfma_f32_16x16x32_bf16 v[62:65], v[192:195], v[146:149], v[62:65]
	v_mfma_f32_16x16x32_bf16 v[58:61], v[192:195], v[152:155], v[58:61]
	v_mfma_f32_16x16x32_bf16 v[54:57], v[192:195], v[156:159], v[54:57]
	v_mfma_f32_16x16x32_bf16 v[50:53], v[192:195], v[162:165], v[50:53]
	v_mfma_f32_16x16x32_bf16 v[46:49], v[192:195], v[166:169], v[46:49]
	v_mfma_f32_16x16x32_bf16 v[42:45], v[192:195], v[170:173], v[42:45]
	v_mfma_f32_16x16x32_bf16 v[38:41], v[192:195], v[176:179], v[38:41]
	v_mfma_f32_16x16x32_bf16 v[34:37], v[192:195], v[180:183], v[34:37]
	v_mfma_f32_16x16x32_bf16 v[30:33], v[196:199], v[146:149], v[30:33]
	v_mfma_f32_16x16x32_bf16 v[26:29], v[196:199], v[152:155], v[26:29]
	v_mfma_f32_16x16x32_bf16 v[22:25], v[196:199], v[156:159], v[22:25]
	v_mfma_f32_16x16x32_bf16 v[18:21], v[196:199], v[162:165], v[18:21]
	v_mfma_f32_16x16x32_bf16 v[14:17], v[196:199], v[166:169], v[14:17]
	v_mfma_f32_16x16x32_bf16 v[10:13], v[196:199], v[170:173], v[10:13]
	v_mfma_f32_16x16x32_bf16 v[6:9], v[196:199], v[176:179], v[6:9]
	v_mfma_f32_16x16x32_bf16 v[2:5], v[196:199], v[180:183], v[2:5]
	s_mov_b32 s41, s40
	s_add_i32 s40, s40, 0x6000
	s_cmp_eq_u32 s40, 0x12000
	s_cselect_b32 s40, 0, s40
	s_mov_b32 s4, 0x8000
	s_mov_b32 s5, 0
	s_mov_b32 s10, 0x10000
	s_mov_b32 s11, 0
	s_mov_b32 s44, 0x3fd744fd
	s_waitcnt lgkmcnt(0)
	v_mfma_f32_16x16x32_bf16 v[126:129], v[232:235], v[200:203], v[126:129]
	v_mfma_f32_16x16x32_bf16 v[122:125], v[232:235], v[204:207], v[122:125]
	v_mfma_f32_16x16x32_bf16 v[118:121], v[232:235], v[208:211], v[118:121]
	v_mfma_f32_16x16x32_bf16 v[114:117], v[232:235], v[212:215], v[114:117]
	v_mfma_f32_16x16x32_bf16 v[110:113], v[232:235], v[216:219], v[110:113]
	v_mfma_f32_16x16x32_bf16 v[106:109], v[232:235], v[220:223], v[106:109]
	v_mfma_f32_16x16x32_bf16 v[102:105], v[232:235], v[224:227], v[102:105]
	v_mfma_f32_16x16x32_bf16 v[98:101], v[232:235], v[228:231], v[98:101]
	v_mfma_f32_16x16x32_bf16 v[94:97], v[236:239], v[200:203], v[94:97]
	v_mfma_f32_16x16x32_bf16 v[90:93], v[236:239], v[204:207], v[90:93]
	v_mfma_f32_16x16x32_bf16 v[86:89], v[236:239], v[208:211], v[86:89]
	v_mfma_f32_16x16x32_bf16 v[82:85], v[236:239], v[212:215], v[82:85]
	v_mfma_f32_16x16x32_bf16 v[78:81], v[236:239], v[216:219], v[78:81]
	v_mfma_f32_16x16x32_bf16 v[74:77], v[236:239], v[220:223], v[74:77]
	v_mfma_f32_16x16x32_bf16 v[70:73], v[236:239], v[224:227], v[70:73]
	v_mfma_f32_16x16x32_bf16 v[66:69], v[236:239], v[228:231], v[66:69]
	v_mfma_f32_16x16x32_bf16 v[62:65], v[240:243], v[200:203], v[62:65]
	v_mfma_f32_16x16x32_bf16 v[58:61], v[240:243], v[204:207], v[58:61]
	v_mfma_f32_16x16x32_bf16 v[54:57], v[240:243], v[208:211], v[54:57]
	v_mfma_f32_16x16x32_bf16 v[50:53], v[240:243], v[212:215], v[50:53]
	v_mfma_f32_16x16x32_bf16 v[46:49], v[240:243], v[216:219], v[46:49]
	v_mfma_f32_16x16x32_bf16 v[42:45], v[240:243], v[220:223], v[42:45]
	v_mfma_f32_16x16x32_bf16 v[38:41], v[240:243], v[224:227], v[38:41]
	v_mfma_f32_16x16x32_bf16 v[34:37], v[240:243], v[228:231], v[34:37]
	v_mfma_f32_16x16x32_bf16 v[30:33], v[244:247], v[200:203], v[30:33]
	v_mfma_f32_16x16x32_bf16 v[26:29], v[244:247], v[204:207], v[26:29]
	v_mfma_f32_16x16x32_bf16 v[22:25], v[244:247], v[208:211], v[22:25]
	v_mfma_f32_16x16x32_bf16 v[18:21], v[244:247], v[212:215], v[18:21]
	v_mfma_f32_16x16x32_bf16 v[14:17], v[244:247], v[216:219], v[14:17]
	v_mfma_f32_16x16x32_bf16 v[10:13], v[244:247], v[220:223], v[10:13]
	v_mfma_f32_16x16x32_bf16 v[6:9], v[244:247], v[224:227], v[6:9]
	v_mfma_f32_16x16x32_bf16 v[2:5], v[244:247], v[228:231], v[2:5]
	s_mov_b32 m0, s43
	s_cmp_eq_u32 s47, 0
	s_cbranch_scc1 .Lta11_first
; DEVI float blo(unsigned u) { return __uint_as_float(u << 16); }
; DEVI float bhi(unsigned u) { return __uint_as_float(u & 0xffff0000u); }
;     ...
;       for (int nf = 0; nf < 4; nf++) {
;         const int col = n0 + wn * 64 + nf * 16 + quad * 4;
;         f32x4 a = acc[nf][mf];
;         if (EPI == EPI_RESID || EPI == EPI_RESID_ATOMIC) {
;           f32x4 x = a;
;           if (EPI == EPI_RESID || kpart == 0) {
;             const u32x2 xr = *(const u32x2*)((const u16*)(p.ws + WS_XB) + (size_t)row * 1024 + col);
;             x[0] += ALPHA * blo(xr[0]); x[1] += ALPHA * bhi(xr[0]); x[2] += ALPHA * blo(xr[1]); x[3] += ALPHA * bhi(xr[1]);
;           }
;           if (EPI == EPI_RESID) *(f32x4*)((float*)(p.ws + WS_XF) + (size_t)row * 1024 + col) = x;
;           else *(f32x4*)((float*)(p.ws + WS_SLAB) + ((size_t)kpart * 512 + (row - T_P)) * 1024 + col) = x;
	s_nop 7
	global_store_dwordx4 v[140:141], v[126:129], off offset:0
	global_store_dwordx4 v[140:141], v[94:97], off offset:64
	global_store_dwordx4 v[140:141], v[62:65], off offset:128
	global_store_dwordx4 v[140:141], v[30:33], off offset:192
	v_lshl_add_u64 v[140:141], v[140:141], 0, s[10:11]
	global_store_dwordx4 v[140:141], v[122:125], off offset:0
	global_store_dwordx4 v[140:141], v[90:93], off offset:64
	global_store_dwordx4 v[140:141], v[58:61], off offset:128
	global_store_dwordx4 v[140:141], v[26:29], off offset:192
	v_lshl_add_u64 v[140:141], v[140:141], 0, s[10:11]
	global_store_dwordx4 v[140:141], v[118:121], off offset:0
	global_store_dwordx4 v[140:141], v[86:89], off offset:64
	global_store_dwordx4 v[140:141], v[54:57], off offset:128
	global_store_dwordx4 v[140:141], v[22:25], off offset:192
	v_lshl_add_u64 v[140:141], v[140:141], 0, s[10:11]
	global_store_dwordx4 v[140:141], v[114:117], off offset:0
	global_store_dwordx4 v[140:141], v[82:85], off offset:64
	global_store_dwordx4 v[140:141], v[50:53], off offset:128
	global_store_dwordx4 v[140:141], v[18:21], off offset:192
	v_lshl_add_u64 v[140:141], v[140:141], 0, s[10:11]
	global_store_dwordx4 v[140:141], v[110:113], off offset:0
	global_store_dwordx4 v[140:141], v[78:81], off offset:64
	global_store_dwordx4 v[140:141], v[46:49], off offset:128
	global_store_dwordx4 v[140:141], v[14:17], off offset:192
	v_lshl_add_u64 v[140:141], v[140:141], 0, s[10:11]
	global_store_dwordx4 v[140:141], v[106:109], off offset:0
	global_store_dwordx4 v[140:141], v[74:77], off offset:64
	global_store_dwordx4 v[140:141], v[42:45], off offset:128
	global_store_dwordx4 v[140:141], v[10:13], off offset:192
	v_lshl_add_u64 v[140:141], v[140:141], 0, s[10:11]
	global_store_dwordx4 v[140:141], v[102:105], off offset:0
	global_store_dwordx4 v[140:141], v[70:73], off offset:64
	global_store_dwordx4 v[140:141], v[38:41], off offset:128
	global_store_dwordx4 v[140:141], v[6:9], off offset:192
	v_lshl_add_u64 v[140:141], v[140:141], 0, s[10:11]
	global_store_dwordx4 v[140:141], v[98:101], off offset:0
	global_store_dwordx4 v[140:141], v[66:69], off offset:64
	global_store_dwordx4 v[140:141], v[34:37], off offset:128
	global_store_dwordx4 v[140:141], v[2:5], off offset:192
	s_branch .LBB0_41
.Lta11_first:
	global_load_dwordx2 v[146:147], v[138:139], off offset:0
	global_load_dwordx2 v[148:149], v[138:139], off offset:32
	global_load_dwordx2 v[152:153], v[138:139], off offset:64
	global_load_dwordx2 v[154:155], v[138:139], off offset:96
	v_lshl_add_u64 v[138:139], v[138:139], 0, s[4:5]
	global_load_dwordx2 v[156:157], v[138:139], off offset:0
	global_load_dwordx2 v[158:159], v[138:139], off offset:32
	global_load_dwordx2 v[162:163], v[138:139], off offset:64
	global_load_dwordx2 v[164:165], v[138:139], off offset:96
	v_lshl_add_u64 v[138:139], v[138:139], 0, s[4:5]
	global_load_dwordx2 v[166:167], v[138:139], off offset:0
	global_load_dwordx2 v[168:169], v[138:139], off offset:32
	global_load_dwordx2 v[170:171], v[138:139], off offset:64
	global_load_dwordx2 v[172:173], v[138:139], off offset:96
	v_lshl_add_u64 v[138:139], v[138:139], 0, s[4:5]
	global_load_dwordx2 v[176:177], v[138:139], off offset:0
	global_load_dwordx2 v[178:179], v[138:139], off offset:32
	global_load_dwordx2 v[180:181], v[138:139], off offset:64
	global_load_dwordx2 v[182:183], v[138:139], off offset:96
	v_lshl_add_u64 v[138:139], v[138:139], 0, s[4:5]
	global_load_dwordx2 v[184:185], v[138:139], off offset:0
	global_load_dwordx2 v[186:187], v[138:139], off offset:32
	global_load_dwordx2 v[188:189], v[138:139], off offset:64
	global_load_dwordx2 v[190:191], v[138:139], off offset:96
	v_lshl_add_u64 v[138:139], v[138:139], 0, s[4:5]
	global_load_dwordx2 v[192:193], v[138:139], off offset:0
	global_load_dwordx2 v[194:195], v[138:139], off offset:32
	global_load_dwordx2 v[196:197], v[138:139], off offset:64
	global_load_dwordx2 v[198:199], v[138:139], off offset:96
	v_lshl_add_u64 v[138:139], v[138:139], 0, s[4:5]
	global_load_dwordx2 v[200:201], v[138:139], off offset:0
	global_load_dwordx2 v[202:203], v[138:139], off offset:32
	global_load_dwordx2 v[204:205], v[138:139], off offset:64
	global_load_dwordx2 v[206:207], v[138:139], off offset:96
	v_lshl_add_u64 v[138:139], v[138:139], 0, s[4:5]
	global_load_dwordx2 v[208:209], v[138:139], off offset:0
	global_load_dwordx2 v[210:211], v[138:139], off offset:32
	global_load_dwordx2 v[212:213], v[138:139], off offset:64
	global_load_dwordx2 v[214:215], v[138:139], off offset:96
	v_lshl_add_u64 v[138:139], v[138:139], 0, s[4:5]
	s_nop 7
	s_waitcnt vmcnt(31)
	v_lshlrev_b32_e32 v216, 16, v146
	v_and_b32_e32 v146, 0xffff0000, v146
	v_lshlrev_b32_e32 v217, 16, v147
	v_and_b32_e32 v147, 0xffff0000, v147
	v_fmac_f32_e32 v126, s44, v216
	v_fmac_f32_e32 v127, s44, v146
	v_fmac_f32_e32 v128, s44, v217
	v_fmac_f32_e32 v129, s44, v147
	global_store_dwordx4 v[140:141], v[126:129], off offset:0
	s_waitcnt vmcnt(31)
	v_lshlrev_b32_e32 v216, 16, v148
	v_and_b32_e32 v148, 0xffff0000, v148
	v_lshlrev_b32_e32 v217, 16, v149
	v_and_b32_e32 v149, 0xffff0000, v149
	v_fmac_f32_e32 v94, s44, v216
	v_fmac_f32_e32 v95, s44, v148
	v_fmac_f32_e32 v96, s44, v217
	v_fmac_f32_e32 v97, s44, v149
	global_store_dwordx4 v[140:141], v[94:97], off offset:64
	s_waitcnt vmcnt(31)
	v_lshlrev_b32_e32 v216, 16, v152
	v_and_b32_e32 v152, 0xffff0000, v152
	v_lshlrev_b32_e32 v217, 16, v153
	v_and_b32_e32 v153, 0xffff0000, v153
	v_fmac_f32_e32 v62, s44, v216
	v_fmac_f32_e32 v63, s44, v152
	v_fmac_f32_e32 v64, s44, v217
	v_fmac_f32_e32 v65, s44, v153
	global_store_dwordx4 v[140:141], v[62:65], off offset:128
	s_waitcnt vmcnt(31)
; DEVI float blo(unsigned u) { return __uint_as_float(u << 16); }
; DEVI float bhi(unsigned u) { return __uint_as_float(u & 0xffff0000u); }
;     ...
;         if (EPI == EPI_RESID || EPI == EPI_RESID_ATOMIC) {
;           f32x4 x = a;
;           if (EPI == EPI_RESID || kpart == 0) {
;             const u32x2 xr = *(const u32x2*)((const u16*)(p.ws + WS_XB) + (size_t)row * 1024 + col);
;             x[0] += ALPHA * blo(xr[0]); x[1] += ALPHA * bhi(xr[0]); x[2] += ALPHA * blo(xr[1]); x[3] += ALPHA * bhi(xr[1]);
;           }
;           if (EPI == EPI_RESID) *(f32x4*)((float*)(p.ws + WS_XF) + (size_t)row * 1024 + col) = x;
;           else *(f32x4*)((float*)(p.ws + WS_SLAB) + ((size_t)kpart * 512 + (row - T_P)) * 1024 + col) = x;
	v_lshlrev_b32_e32 v216, 16, v154
	v_and_b32_e32 v154, 0xffff0000, v154
	v_lshlrev_b32_e32 v217, 16, v155
	v_and_b32_e32 v155, 0xffff0000, v155
	v_fmac_f32_e32 v30, s44, v216
	v_fmac_f32_e32 v31, s44, v154
	v_fmac_f32_e32 v32, s44, v217
	v_fmac_f32_e32 v33, s44, v155
	global_store_dwordx4 v[140:141], v[30:33], off offset:192
	v_lshl_add_u64 v[140:141], v[140:141], 0, s[10:11]
	s_waitcnt vmcnt(31)
	v_lshlrev_b32_e32 v216, 16, v156
	v_and_b32_e32 v156, 0xffff0000, v156
	v_lshlrev_b32_e32 v217, 16, v157
	v_and_b32_e32 v157, 0xffff0000, v157
	v_fmac_f32_e32 v122, s44, v216
	v_fmac_f32_e32 v123, s44, v156
	v_fmac_f32_e32 v124, s44, v217
	v_fmac_f32_e32 v125, s44, v157
	global_store_dwordx4 v[140:141], v[122:125], off offset:0
	s_waitcnt vmcnt(31)
	v_lshlrev_b32_e32 v216, 16, v158
	v_and_b32_e32 v158, 0xffff0000, v158
	v_lshlrev_b32_e32 v217, 16, v159
	v_and_b32_e32 v159, 0xffff0000, v159
	v_fmac_f32_e32 v90, s44, v216
	v_fmac_f32_e32 v91, s44, v158
	v_fmac_f32_e32 v92, s44, v217
	v_fmac_f32_e32 v93, s44, v159
	global_store_dwordx4 v[140:141], v[90:93], off offset:64
	s_waitcnt vmcnt(31)
	v_lshlrev_b32_e32 v216, 16, v162
	v_and_b32_e32 v162, 0xffff0000, v162
	v_lshlrev_b32_e32 v217, 16, v163
	v_and_b32_e32 v163, 0xffff0000, v163
	v_fmac_f32_e32 v58, s44, v216
	v_fmac_f32_e32 v59, s44, v162
	v_fmac_f32_e32 v60, s44, v217
	v_fmac_f32_e32 v61, s44, v163
	global_store_dwordx4 v[140:141], v[58:61], off offset:128
	s_waitcnt vmcnt(31)
	v_lshlrev_b32_e32 v216, 16, v164
	v_and_b32_e32 v164, 0xffff0000, v164
	v_lshlrev_b32_e32 v217, 16, v165
	v_and_b32_e32 v165, 0xffff0000, v165
	v_fmac_f32_e32 v26, s44, v216
	v_fmac_f32_e32 v27, s44, v164
	v_fmac_f32_e32 v28, s44, v217
	v_fmac_f32_e32 v29, s44, v165
	global_store_dwordx4 v[140:141], v[26:29], off offset:192
	v_lshl_add_u64 v[140:141], v[140:141], 0, s[10:11]
	s_waitcnt vmcnt(31)
	v_lshlrev_b32_e32 v216, 16, v166
	v_and_b32_e32 v166, 0xffff0000, v166
	v_lshlrev_b32_e32 v217, 16, v167
	v_and_b32_e32 v167, 0xffff0000, v167
	v_fmac_f32_e32 v118, s44, v216
	v_fmac_f32_e32 v119, s44, v166
	v_fmac_f32_e32 v120, s44, v217
	v_fmac_f32_e32 v121, s44, v167
	global_store_dwordx4 v[140:141], v[118:121], off offset:0
	s_waitcnt vmcnt(31)
	v_lshlrev_b32_e32 v216, 16, v168
	v_and_b32_e32 v168, 0xffff0000, v168
	v_lshlrev_b32_e32 v217, 16, v169
	v_and_b32_e32 v169, 0xffff0000, v169
	v_fmac_f32_e32 v86, s44, v216
	v_fmac_f32_e32 v87, s44, v168
	v_fmac_f32_e32 v88, s44, v217
	v_fmac_f32_e32 v89, s44, v169
	global_store_dwordx4 v[140:141], v[86:89], off offset:64
	s_waitcnt vmcnt(31)
	v_lshlrev_b32_e32 v216, 16, v170
	v_and_b32_e32 v170, 0xffff0000, v170
	v_lshlrev_b32_e32 v217, 16, v171
	v_and_b32_e32 v171, 0xffff0000, v171
	v_fmac_f32_e32 v54, s44, v216
	v_fmac_f32_e32 v55, s44, v170
	v_fmac_f32_e32 v56, s44, v217
	v_fmac_f32_e32 v57, s44, v171
	global_store_dwordx4 v[140:141], v[54:57], off offset:128
	s_waitcnt vmcnt(31)
	v_lshlrev_b32_e32 v216, 16, v172
	v_and_b32_e32 v172, 0xffff0000, v172
	v_lshlrev_b32_e32 v217, 16, v173
	v_and_b32_e32 v173, 0xffff0000, v173
	v_fmac_f32_e32 v22, s44, v216
	v_fmac_f32_e32 v23, s44, v172
	v_fmac_f32_e32 v24, s44, v217
	v_fmac_f32_e32 v25, s44, v173
	global_store_dwordx4 v[140:141], v[22:25], off offset:192
	v_lshl_add_u64 v[140:141], v[140:141], 0, s[10:11]
	s_waitcnt vmcnt(31)
	v_lshlrev_b32_e32 v216, 16, v176
	v_and_b32_e32 v176, 0xffff0000, v176
	v_lshlrev_b32_e32 v217, 16, v177
	v_and_b32_e32 v177, 0xffff0000, v177
	v_fmac_f32_e32 v114, s44, v216
	v_fmac_f32_e32 v115, s44, v176
	v_fmac_f32_e32 v116, s44, v217
	v_fmac_f32_e32 v117, s44, v177
	global_store_dwordx4 v[140:141], v[114:117], off offset:0
	s_waitcnt vmcnt(31)
	v_lshlrev_b32_e32 v216, 16, v178
	v_and_b32_e32 v178, 0xffff0000, v178
	v_lshlrev_b32_e32 v217, 16, v179
	v_and_b32_e32 v179, 0xffff0000, v179
	v_fmac_f32_e32 v82, s44, v216
	v_fmac_f32_e32 v83, s44, v178
	v_fmac_f32_e32 v84, s44, v217
	v_fmac_f32_e32 v85, s44, v179
	global_store_dwordx4 v[140:141], v[82:85], off offset:64
	s_waitcnt vmcnt(31)
	v_lshlrev_b32_e32 v216, 16, v180
	v_and_b32_e32 v180, 0xffff0000, v180
	v_lshlrev_b32_e32 v217, 16, v181
	v_and_b32_e32 v181, 0xffff0000, v181
	v_fmac_f32_e32 v50, s44, v216
	v_fmac_f32_e32 v51, s44, v180
	v_fmac_f32_e32 v52, s44, v217
	v_fmac_f32_e32 v53, s44, v181
	global_store_dwordx4 v[140:141], v[50:53], off offset:128
	s_waitcnt vmcnt(31)
	v_lshlrev_b32_e32 v216, 16, v182
	v_and_b32_e32 v182, 0xffff0000, v182
	v_lshlrev_b32_e32 v217, 16, v183
	v_and_b32_e32 v183, 0xffff0000, v183
	v_fmac_f32_e32 v18, s44, v216
	v_fmac_f32_e32 v19, s44, v182
	v_fmac_f32_e32 v20, s44, v217
	v_fmac_f32_e32 v21, s44, v183
	global_store_dwordx4 v[140:141], v[18:21], off offset:192
	v_lshl_add_u64 v[140:141], v[140:141], 0, s[10:11]
	s_waitcnt vmcnt(31)
	v_lshlrev_b32_e32 v216, 16, v184
	v_and_b32_e32 v184, 0xffff0000, v184
	v_lshlrev_b32_e32 v217, 16, v185
	v_and_b32_e32 v185, 0xffff0000, v185
	v_fmac_f32_e32 v110, s44, v216
	v_fmac_f32_e32 v111, s44, v184
	v_fmac_f32_e32 v112, s44, v217
	v_fmac_f32_e32 v113, s44, v185
	global_store_dwordx4 v[140:141], v[110:113], off offset:0
	s_waitcnt vmcnt(31)
	v_lshlrev_b32_e32 v216, 16, v186
	v_and_b32_e32 v186, 0xffff0000, v186
	v_lshlrev_b32_e32 v217, 16, v187
	v_and_b32_e32 v187, 0xffff0000, v187
	v_fmac_f32_e32 v78, s44, v216
	v_fmac_f32_e32 v79, s44, v186
	v_fmac_f32_e32 v80, s44, v217
	v_fmac_f32_e32 v81, s44, v187
	global_store_dwordx4 v[140:141], v[78:81], off offset:64
	s_waitcnt vmcnt(31)
	v_lshlrev_b32_e32 v216, 16, v188
	v_and_b32_e32 v188, 0xffff0000, v188
	v_lshlrev_b32_e32 v217, 16, v189
	v_and_b32_e32 v189, 0xffff0000, v189
	v_fmac_f32_e32 v46, s44, v216
	v_fmac_f32_e32 v47, s44, v188
	v_fmac_f32_e32 v48, s44, v217
	v_fmac_f32_e32 v49, s44, v189
	global_store_dwordx4 v[140:141], v[46:49], off offset:128
	s_waitcnt vmcnt(31)
; DEVI float blo(unsigned u) { return __uint_as_float(u << 16); }
; DEVI float bhi(unsigned u) { return __uint_as_float(u & 0xffff0000u); }
;     ...
;         if (EPI == EPI_RESID || EPI == EPI_RESID_ATOMIC) {
;           f32x4 x = a;
;           if (EPI == EPI_RESID || kpart == 0) {
;             const u32x2 xr = *(const u32x2*)((const u16*)(p.ws + WS_XB) + (size_t)row * 1024 + col);
;             x[0] += ALPHA * blo(xr[0]); x[1] += ALPHA * bhi(xr[0]); x[2] += ALPHA * blo(xr[1]); x[3] += ALPHA * bhi(xr[1]);
;           }
;           if (EPI == EPI_RESID) *(f32x4*)((float*)(p.ws + WS_XF) + (size_t)row * 1024 + col) = x;
;           else *(f32x4*)((float*)(p.ws + WS_SLAB) + ((size_t)kpart * 512 + (row - T_P)) * 1024 + col) = x;
	v_lshlrev_b32_e32 v216, 16, v190
	v_and_b32_e32 v190, 0xffff0000, v190
	v_lshlrev_b32_e32 v217, 16, v191
	v_and_b32_e32 v191, 0xffff0000, v191
	v_fmac_f32_e32 v14, s44, v216
	v_fmac_f32_e32 v15, s44, v190
	v_fmac_f32_e32 v16, s44, v217
	v_fmac_f32_e32 v17, s44, v191
	global_store_dwordx4 v[140:141], v[14:17], off offset:192
	v_lshl_add_u64 v[140:141], v[140:141], 0, s[10:11]
	s_waitcnt vmcnt(31)
	v_lshlrev_b32_e32 v216, 16, v192
	v_and_b32_e32 v192, 0xffff0000, v192
	v_lshlrev_b32_e32 v217, 16, v193
	v_and_b32_e32 v193, 0xffff0000, v193
	v_fmac_f32_e32 v106, s44, v216
	v_fmac_f32_e32 v107, s44, v192
	v_fmac_f32_e32 v108, s44, v217
	v_fmac_f32_e32 v109, s44, v193
	global_store_dwordx4 v[140:141], v[106:109], off offset:0
	s_waitcnt vmcnt(31)
	v_lshlrev_b32_e32 v216, 16, v194
	v_and_b32_e32 v194, 0xffff0000, v194
	v_lshlrev_b32_e32 v217, 16, v195
	v_and_b32_e32 v195, 0xffff0000, v195
	v_fmac_f32_e32 v74, s44, v216
	v_fmac_f32_e32 v75, s44, v194
	v_fmac_f32_e32 v76, s44, v217
	v_fmac_f32_e32 v77, s44, v195
	global_store_dwordx4 v[140:141], v[74:77], off offset:64
	s_waitcnt vmcnt(31)
	v_lshlrev_b32_e32 v216, 16, v196
	v_and_b32_e32 v196, 0xffff0000, v196
	v_lshlrev_b32_e32 v217, 16, v197
	v_and_b32_e32 v197, 0xffff0000, v197
	v_fmac_f32_e32 v42, s44, v216
	v_fmac_f32_e32 v43, s44, v196
	v_fmac_f32_e32 v44, s44, v217
	v_fmac_f32_e32 v45, s44, v197
	global_store_dwordx4 v[140:141], v[42:45], off offset:128
	s_waitcnt vmcnt(31)
	v_lshlrev_b32_e32 v216, 16, v198
	v_and_b32_e32 v198, 0xffff0000, v198
	v_lshlrev_b32_e32 v217, 16, v199
	v_and_b32_e32 v199, 0xffff0000, v199
	v_fmac_f32_e32 v10, s44, v216
	v_fmac_f32_e32 v11, s44, v198
	v_fmac_f32_e32 v12, s44, v217
	v_fmac_f32_e32 v13, s44, v199
	global_store_dwordx4 v[140:141], v[10:13], off offset:192
	v_lshl_add_u64 v[140:141], v[140:141], 0, s[10:11]
	s_waitcnt vmcnt(31)
	v_lshlrev_b32_e32 v216, 16, v200
	v_and_b32_e32 v200, 0xffff0000, v200
	v_lshlrev_b32_e32 v217, 16, v201
	v_and_b32_e32 v201, 0xffff0000, v201
	v_fmac_f32_e32 v102, s44, v216
	v_fmac_f32_e32 v103, s44, v200
	v_fmac_f32_e32 v104, s44, v217
	v_fmac_f32_e32 v105, s44, v201
	global_store_dwordx4 v[140:141], v[102:105], off offset:0
	s_waitcnt vmcnt(31)
	v_lshlrev_b32_e32 v216, 16, v202
	v_and_b32_e32 v202, 0xffff0000, v202
	v_lshlrev_b32_e32 v217, 16, v203
	v_and_b32_e32 v203, 0xffff0000, v203
	v_fmac_f32_e32 v70, s44, v216
	v_fmac_f32_e32 v71, s44, v202
	v_fmac_f32_e32 v72, s44, v217
	v_fmac_f32_e32 v73, s44, v203
	global_store_dwordx4 v[140:141], v[70:73], off offset:64
	s_waitcnt vmcnt(31)
	v_lshlrev_b32_e32 v216, 16, v204
	v_and_b32_e32 v204, 0xffff0000, v204
	v_lshlrev_b32_e32 v217, 16, v205
	v_and_b32_e32 v205, 0xffff0000, v205
	v_fmac_f32_e32 v38, s44, v216
	v_fmac_f32_e32 v39, s44, v204
	v_fmac_f32_e32 v40, s44, v217
	v_fmac_f32_e32 v41, s44, v205
	global_store_dwordx4 v[140:141], v[38:41], off offset:128
	s_waitcnt vmcnt(31)
	v_lshlrev_b32_e32 v216, 16, v206
	v_and_b32_e32 v206, 0xffff0000, v206
	v_lshlrev_b32_e32 v217, 16, v207
	v_and_b32_e32 v207, 0xffff0000, v207
	v_fmac_f32_e32 v6, s44, v216
	v_fmac_f32_e32 v7, s44, v206
	v_fmac_f32_e32 v8, s44, v217
	v_fmac_f32_e32 v9, s44, v207
	global_store_dwordx4 v[140:141], v[6:9], off offset:192
	v_lshl_add_u64 v[140:141], v[140:141], 0, s[10:11]
	s_waitcnt vmcnt(31)
	v_lshlrev_b32_e32 v216, 16, v208
	v_and_b32_e32 v208, 0xffff0000, v208
	v_lshlrev_b32_e32 v217, 16, v209
	v_and_b32_e32 v209, 0xffff0000, v209
	v_fmac_f32_e32 v98, s44, v216
	v_fmac_f32_e32 v99, s44, v208
	v_fmac_f32_e32 v100, s44, v217
	v_fmac_f32_e32 v101, s44, v209
	global_store_dwordx4 v[140:141], v[98:101], off offset:0
	s_waitcnt vmcnt(31)
	v_lshlrev_b32_e32 v216, 16, v210
	v_and_b32_e32 v210, 0xffff0000, v210
	v_lshlrev_b32_e32 v217, 16, v211
	v_and_b32_e32 v211, 0xffff0000, v211
	v_fmac_f32_e32 v66, s44, v216
	v_fmac_f32_e32 v67, s44, v210
	v_fmac_f32_e32 v68, s44, v217
	v_fmac_f32_e32 v69, s44, v211
	global_store_dwordx4 v[140:141], v[66:69], off offset:64
	s_waitcnt vmcnt(31)
	v_lshlrev_b32_e32 v216, 16, v212
	v_and_b32_e32 v212, 0xffff0000, v212
	v_lshlrev_b32_e32 v217, 16, v213
	v_and_b32_e32 v213, 0xffff0000, v213
	v_fmac_f32_e32 v34, s44, v216
	v_fmac_f32_e32 v35, s44, v212
	v_fmac_f32_e32 v36, s44, v217
	v_fmac_f32_e32 v37, s44, v213
	global_store_dwordx4 v[140:141], v[34:37], off offset:128
	s_waitcnt vmcnt(31)
	v_lshlrev_b32_e32 v216, 16, v214
	v_and_b32_e32 v214, 0xffff0000, v214
	v_lshlrev_b32_e32 v217, 16, v215
	v_and_b32_e32 v215, 0xffff0000, v215
	v_fmac_f32_e32 v2, s44, v216
	v_fmac_f32_e32 v3, s44, v214
	v_fmac_f32_e32 v4, s44, v217
	v_fmac_f32_e32 v5, s44, v215
	global_store_dwordx4 v[140:141], v[2:5], off offset:192
	s_branch .LBB0_41
; #define LAS __attribute__((address_space(3)))
; DEVI int tidx() { int t = threadIdx.x; asm volatile("" : "+v"(t)); return t; }
;   const int tid = tidx(), lane = tid & 63, wid = tid >> 6;
;   const int wm = wid >> 1, wn = wid & 1, r16 = lane & 15, quad = lane >> 4;
;   f32x4 acc[4][8];
; #pragma unroll
;   for (int i = 0; i < 4; i++)
; #pragma unroll
;     for (int j = 0; j < 8; j++) acc[i][j] = (f32x4){0.f, 0.f, 0.f, 0.f};
;   const int nk = (nk_part < 0) ? (K >> 5) : nk_part;
;   const int lrow = tid >> 2, lpc = tid & 3;
;   const int lch = lpc ^ ((0x78 >> (((lrow >> 2) & 3) * 2)) & 3);
;   const u16* ga = A + (size_t)(m0 + lrow) * lda + kbeg + lch * 8;
;   const u16* gb = Bt + (size_t)(n0 + lrow) * K + kbeg + lch * 8;
;   const size_t ga1 = (size_t)64 * lda, gb1 = (size_t)64 * K;
;   const unsigned lds0 = (unsigned)(uintptr_t)(LAS char*)smem + (unsigned)__builtin_amdgcn_readfirstlane(wid) * 1024u;
;     ...
;   __syncthreads();
;   G2_STAGE(0); G2_STAGE(1);
;   const int fsw = (0x78 >> (((r16 >> 2) & 3) * 2)) & 3;
;   const int aoff = (wm * 128 + r16) * 64 + ((quad ^ fsw) << 4);
;   const int boff = 16384 + (wn * 64 + r16) * 64 + ((quad ^ fsw) << 4);
; DEVI void run_phase(const Params& p, int ph, char* smem) {
;     ...
;           int mt_, nt_; tile_coords(t, 64, 8, mt_, nt_);
;           gemm_tile256<EPI_RESID>(p, hb, DFF, Bt, DFF, mt_ * 256, nt_ * 128, nullptr, 0, smem);
.LBB0_116:
	s_and_b64 vcc, exec, s[2:3]
	s_cbranch_vccz .LBB0_41
	s_lshr_b32 s45, s38, 6
	s_and_b32 s46, s38, 63
	s_lshr_b32 s42, s46, 3
	s_and_b32 s46, s46, 7
	s_lshl_b32 s45, s45, 3
	s_add_i32 s45, s45, s46
	s_cmp_lt_u32 s45, 64
	s_cselect_b32 s44, 1, 0
	v_readlane_b32 s2, v250, 5
	v_readlane_b32 s3, v250, 6
	v_readlane_b32 s46, v254, 62
	s_mul_i32 s40, s45, 0x160000
	s_add_u32 s4, s2, s40
	s_addc_u32 s5, s3, 0
	s_add_u32 s4, s4, 0xef40000
	s_addc_u32 s5, s5, 0
	s_mul_i32 s40, s46, 0x580000
	s_mul_i32 s41, s42, 0xb0000
	s_add_i32 s40, s40, s41
	s_add_u32 s10, s2, s40
	s_addc_u32 s11, s3, 0
	s_add_u32 s10, s10, 0x19a00000
	s_addc_u32 s11, s11, 0
	s_movk_i32 s39, 0x78
	v_lshrrev_b32_e32 v0, 2, v145
	v_and_b32_e32 v131, 3, v145
	v_bfe_u32 v136, v145, 4, 2
	v_lshlrev_b32_e32 v136, 1, v136
	v_lshrrev_b32_e64 v136, v136, s39
	v_and_b32_e32 v136, 3, v136
	v_xor_b32_e32 v131, v131, v136
	v_lshlrev_b32_e32 v131, 4, v131
	s_movk_i32 s41, 0x1600
	v_mad_u32_u24 v0, v0, s41, v131
	v_bfe_u32 v137, v145, 2, 1
	s_movk_i32 s41, 0x15c0
	v_mul_u32_u24_e32 v136, s41, v137
	v_sub_u32_e32 v136, v0, v136
	v_mov_b32_e32 v137, 0
	v_lshl_add_u64 v[134:135], s[10:11], 0, v[136:137]
	v_bfe_u32 v137, v145, 2, 1
	s_mul_i32 s41, s44, 0x15c0
	v_mul_u32_u24_e32 v136, s41, v137
	v_sub_u32_e32 v0, v0, v136
	s_lshl_b32 s12, s44, 6
	s_add_i32 s12, s12, 64
	s_mov_b32 s13, 0
	v_lshl_add_u64 v[132:133], s[4:5], 0, v[0:1]
	v_bfe_u32 v136, v145, 2, 2
	v_lshlrev_b32_e32 v136, 1, v136
	v_lshrrev_b32_e64 v136, v136, s39
	v_and_b32_e32 v136, 3, v136
	v_bfe_u32 v137, v145, 4, 2
	v_xor_b32_e32 v136, v136, v137
	v_lshlrev_b32_e32 v136, 4, v136
	v_and_b32_e32 v131, 15, v145
	v_lshl_or_b32 v136, v131, 6, v136
	v_bfe_u32 v137, v145, 6, 1
	v_lshl_or_b32 v137, v137, 12, v136
	v_lshrrev_b32_e32 v0, 7, v145
	v_lshl_or_b32 v136, v0, 13, v136
	v_and_b32_e32 v140, 1, v131
	v_lshl_or_b32 v131, v0, 7, v131
	v_bfe_u32 v0, v145, 4, 2
	v_lshlrev_b32_e32 v0, 3, v0
	v_bfe_u32 v141, v145, 6, 1
	s_lshl_b32 s40, s45, 19
	s_lshl_b32 s41, s42, 9
	s_add_i32 s40, s40, s41
	s_add_u32 s4, s2, s40
	s_addc_u32 s5, s3, 0
	s_add_u32 s4, s4, 0x4200000
	s_addc_u32 s5, s5, 0
	v_lshlrev_b32_e32 v138, 11, v131
	v_lshl_add_u32 v138, v141, 8, v138
	v_add_u32_e32 v138, v138, v0
	s_movk_i32 s41, 1984
	v_mul_u32_u24_e32 v139, s41, v140
	v_sub_u32_e32 v138, v138, v139
	v_mov_b32_e32 v139, 0
	v_lshl_add_u64 v[138:139], s[4:5], 0, v[138:139]
	s_lshl_b32 s40, s45, 20
	s_lshl_b32 s41, s42, 9
	s_add_i32 s40, s40, s41
	s_add_u32 s10, s2, s40
	s_addc_u32 s11, s3, 0
	v_lshlrev_b32_e32 v140, 12, v131
	v_lshl_add_u32 v140, v141, 8, v140
	v_lshl_add_u32 v140, v0, 1, v140
	v_mov_b32_e32 v141, 0
	v_lshl_add_u64 v[140:141], s[10:11], 0, v[140:141]
	s_mov_b32 s2, 0x58000
	s_mov_b32 s3, 0
	v_lshrrev_b32_e32 v0, 6, v145
	v_lshlrev_b32_e32 v0, 10, v0
	s_nop 0
	v_readfirstlane_b32 s46, v0
	s_mov_b32 s43, m0
	s_mov_b32 s4, 128
	s_mov_b32 s5, 0
	v_mov_b32_e32 v2, 0
	v_mov_b32_e32 v3, 0
	v_mov_b32_e32 v4, 0
	v_mov_b32_e32 v5, 0
	v_mov_b32_e32 v6, 0
	v_mov_b32_e32 v7, 0
	v_mov_b32_e32 v8, 0
	v_mov_b32_e32 v9, 0
	v_mov_b32_e32 v10, 0
	v_mov_b32_e32 v11, 0
	v_mov_b32_e32 v12, 0
	v_mov_b32_e32 v13, 0
	v_mov_b32_e32 v14, 0
	v_mov_b32_e32 v15, 0
	v_mov_b32_e32 v16, 0
	v_mov_b32_e32 v17, 0
	v_mov_b32_e32 v18, 0
	v_mov_b32_e32 v19, 0
	v_mov_b32_e32 v20, 0
	v_mov_b32_e32 v21, 0
	v_mov_b32_e32 v22, 0
	v_mov_b32_e32 v23, 0
	v_mov_b32_e32 v24, 0
	v_mov_b32_e32 v25, 0
	v_mov_b32_e32 v26, 0
	v_mov_b32_e32 v27, 0
	v_mov_b32_e32 v28, 0
	v_mov_b32_e32 v29, 0
	v_mov_b32_e32 v30, 0
	v_mov_b32_e32 v31, 0
	v_mov_b32_e32 v32, 0
	v_mov_b32_e32 v33, 0
	v_mov_b32_e32 v34, 0
	v_mov_b32_e32 v35, 0
	v_mov_b32_e32 v36, 0
	v_mov_b32_e32 v37, 0
	v_mov_b32_e32 v38, 0
	v_mov_b32_e32 v39, 0
	v_mov_b32_e32 v40, 0
	v_mov_b32_e32 v41, 0
	v_mov_b32_e32 v42, 0
	v_mov_b32_e32 v43, 0
	v_mov_b32_e32 v44, 0
	v_mov_b32_e32 v45, 0
	v_mov_b32_e32 v46, 0
	v_mov_b32_e32 v47, 0
	v_mov_b32_e32 v48, 0
	v_mov_b32_e32 v49, 0
	v_mov_b32_e32 v50, 0
	v_mov_b32_e32 v51, 0
	v_mov_b32_e32 v52, 0
	v_mov_b32_e32 v53, 0
	v_mov_b32_e32 v54, 0
	v_mov_b32_e32 v55, 0
	v_mov_b32_e32 v56, 0
	v_mov_b32_e32 v57, 0
	v_mov_b32_e32 v58, 0
	v_mov_b32_e32 v59, 0
	v_mov_b32_e32 v60, 0
	v_mov_b32_e32 v61, 0
	v_mov_b32_e32 v62, 0
	v_mov_b32_e32 v63, 0
	v_mov_b32_e32 v64, 0
	v_mov_b32_e32 v65, 0
	v_mov_b32_e32 v66, 0
	v_mov_b32_e32 v67, 0
	v_mov_b32_e32 v68, 0
	v_mov_b32_e32 v69, 0
	v_mov_b32_e32 v70, 0
	v_mov_b32_e32 v71, 0
	v_mov_b32_e32 v72, 0
	v_mov_b32_e32 v73, 0
	v_mov_b32_e32 v74, 0
	v_mov_b32_e32 v75, 0
	v_mov_b32_e32 v76, 0
	v_mov_b32_e32 v77, 0
	v_mov_b32_e32 v78, 0
	v_mov_b32_e32 v79, 0
	v_mov_b32_e32 v80, 0
	v_mov_b32_e32 v81, 0
	v_mov_b32_e32 v82, 0
	v_mov_b32_e32 v83, 0
	v_mov_b32_e32 v84, 0
	v_mov_b32_e32 v85, 0
	v_mov_b32_e32 v86, 0
	v_mov_b32_e32 v87, 0
	v_mov_b32_e32 v88, 0
	v_mov_b32_e32 v89, 0
	v_mov_b32_e32 v90, 0
	v_mov_b32_e32 v91, 0
	v_mov_b32_e32 v92, 0
	v_mov_b32_e32 v93, 0
	v_mov_b32_e32 v94, 0
	v_mov_b32_e32 v95, 0
	v_mov_b32_e32 v96, 0
	v_mov_b32_e32 v97, 0
	v_mov_b32_e32 v98, 0
	v_mov_b32_e32 v99, 0
	v_mov_b32_e32 v100, 0
	v_mov_b32_e32 v101, 0
	v_mov_b32_e32 v102, 0
	v_mov_b32_e32 v103, 0
	v_mov_b32_e32 v104, 0
	v_mov_b32_e32 v105, 0
	v_mov_b32_e32 v106, 0
	v_mov_b32_e32 v107, 0
	v_mov_b32_e32 v108, 0
	v_mov_b32_e32 v109, 0
	v_mov_b32_e32 v110, 0
	v_mov_b32_e32 v111, 0
	v_mov_b32_e32 v112, 0
	v_mov_b32_e32 v113, 0
	v_mov_b32_e32 v114, 0
	v_mov_b32_e32 v115, 0
	v_mov_b32_e32 v116, 0
	v_mov_b32_e32 v117, 0
	v_mov_b32_e32 v118, 0
	v_mov_b32_e32 v119, 0
	v_mov_b32_e32 v120, 0
	v_mov_b32_e32 v121, 0
	v_mov_b32_e32 v122, 0
	v_mov_b32_e32 v123, 0
	v_mov_b32_e32 v124, 0
	v_mov_b32_e32 v125, 0
	v_mov_b32_e32 v126, 0
	v_mov_b32_e32 v127, 0
	v_mov_b32_e32 v128, 0
	v_mov_b32_e32 v129, 0
	s_barrier
;     ...
;   __syncthreads();
;   G2_STAGE(0); G2_STAGE(1);
;   const int fsw = (0x78 >> (((r16 >> 2) & 3) * 2)) & 3;
;   const int aoff = (wm * 128 + r16) * 64 + ((quad ^ fsw) << 4);
;   const int boff = 16384 + (wn * 64 + r16) * 64 + ((quad ^ fsw) << 4);
	s_add_i32 s42, s46, 0x0
	s_mov_b32 m0, s42
	v_lshl_add_u64 v[142:143], v[132:133], 0, s[2:3]
	global_load_lds_dwordx4 v[132:133], off
	s_addk_i32 m0, 0x1000
	s_nop 0
	global_load_lds_dwordx4 v[142:143], off
	v_lshl_add_u64 v[142:143], v[142:143], 0, s[2:3]
	s_addk_i32 m0, 0x1000
	s_nop 0
	global_load_lds_dwordx4 v[142:143], off
	v_lshl_add_u64 v[142:143], v[142:143], 0, s[2:3]
	s_addk_i32 m0, 0x1000
	s_nop 0
	global_load_lds_dwordx4 v[142:143], off
	s_addk_i32 m0, 0x1000
	v_lshl_add_u64 v[142:143], v[134:135], 0, s[2:3]
	s_nop 0
	global_load_lds_dwordx4 v[134:135], off
	s_addk_i32 m0, 0x1000
	v_lshl_add_u64 v[132:133], v[132:133], 0, s[12:13]
	s_nop 0
	global_load_lds_dwordx4 v[142:143], off
	v_lshl_add_u64 v[134:135], v[134:135], 0, s[4:5]
	s_nop 0
	s_add_i32 s42, s46, 0x6000
	s_mov_b32 m0, s42
	v_lshl_add_u64 v[142:143], v[132:133], 0, s[2:3]
	global_load_lds_dwordx4 v[132:133], off
	s_addk_i32 m0, 0x1000
	s_nop 0
	global_load_lds_dwordx4 v[142:143], off
	v_lshl_add_u64 v[142:143], v[142:143], 0, s[2:3]
	s_addk_i32 m0, 0x1000
	s_nop 0
	global_load_lds_dwordx4 v[142:143], off
	v_lshl_add_u64 v[142:143], v[142:143], 0, s[2:3]
	s_addk_i32 m0, 0x1000
	s_nop 0
	global_load_lds_dwordx4 v[142:143], off
	s_addk_i32 m0, 0x1000
	v_lshl_add_u64 v[142:143], v[134:135], 0, s[2:3]
	s_nop 0
	global_load_lds_dwordx4 v[134:135], off
	s_addk_i32 m0, 0x1000
	v_lshl_add_u64 v[132:133], v[132:133], 0, s[12:13]
	s_nop 0
	global_load_lds_dwordx4 v[142:143], off
	v_lshl_add_u64 v[134:135], v[134:135], 0, s[4:5]
	s_nop 0
	s_add_i32 s42, s46, 0xc000
	s_mov_b32 m0, s42
	v_lshl_add_u64 v[142:143], v[132:133], 0, s[2:3]
	global_load_lds_dwordx4 v[132:133], off
	s_addk_i32 m0, 0x1000
	s_nop 0
	global_load_lds_dwordx4 v[142:143], off
	v_lshl_add_u64 v[142:143], v[142:143], 0, s[2:3]
	s_addk_i32 m0, 0x1000
	s_nop 0
	global_load_lds_dwordx4 v[142:143], off
	v_lshl_add_u64 v[142:143], v[142:143], 0, s[2:3]
	s_addk_i32 m0, 0x1000
	s_nop 0
	global_load_lds_dwordx4 v[142:143], off
	s_addk_i32 m0, 0x1000
	v_lshl_add_u64 v[142:143], v[134:135], 0, s[2:3]
	s_nop 0
	global_load_lds_dwordx4 v[134:135], off
	s_addk_i32 m0, 0x1000
	v_lshl_add_u64 v[132:133], v[132:133], 0, s[12:13]
	s_nop 0
	global_load_lds_dwordx4 v[142:143], off
	v_lshl_add_u64 v[134:135], v[134:135], 0, s[4:5]
	s_nop 0
	s_waitcnt vmcnt(12)
	s_barrier
	ds_read_b128 v[146:149], v136 offset:0
	ds_read_b128 v[152:155], v136 offset:1024
	ds_read_b128 v[156:159], v136 offset:2048
	ds_read_b128 v[162:165], v136 offset:3072
	ds_read_b128 v[166:169], v136 offset:4096
	ds_read_b128 v[170:173], v136 offset:5120
	ds_read_b128 v[176:179], v136 offset:6144
	ds_read_b128 v[180:183], v136 offset:7168
	ds_read_b128 v[184:187], v137 offset:16384
	ds_read_b128 v[188:191], v137 offset:17408
	ds_read_b128 v[192:195], v137 offset:18432
	ds_read_b128 v[196:199], v137 offset:19456
	s_movk_i32 s40, 0x6000
	s_mov_b32 s41, 0
	s_movk_i32 s39, 42

; #define LAS __attribute__((address_space(3)))
; DEVI int tidx() { int t = threadIdx.x; asm volatile("" : "+v"(t)); return t; }
;   const int tid = tidx(), lane = tid & 63, wid = tid >> 6;
;   const int wm = wid >> 1, wn = wid & 1, r16 = lane & 15, quad = lane >> 4;
;   f32x4 acc[4][8];
; #pragma unroll
;   for (int i = 0; i < 4; i++)
; #pragma unroll
;     for (int j = 0; j < 8; j++) acc[i][j] = (f32x4){0.f, 0.f, 0.f, 0.f};
;   const int nk = (nk_part < 0) ? (K >> 5) : nk_part;
;   const int lrow = tid >> 2, lpc = tid & 3;
;   const int lch = lpc ^ ((0x78 >> (((lrow >> 2) & 3) * 2)) & 3);
;   const u16* ga = A + (size_t)(m0 + lrow) * lda + kbeg + lch * 8;
;   const u16* gb = Bt + (size_t)(n0 + lrow) * K + kbeg + lch * 8;
;   const size_t ga1 = (size_t)64 * lda, gb1 = (size_t)64 * K;
;   const unsigned lds0 = (unsigned)(uintptr_t)(LAS char*)smem + (unsigned)__builtin_amdgcn_readfirstlane(wid) * 1024u;
;     ...
;   __syncthreads();
;   G2_STAGE(0); G2_STAGE(1);
;   const int fsw = (0x78 >> (((r16 >> 2) & 3) * 2)) & 3;
;   const int aoff = (wm * 128 + r16) * 64 + ((quad ^ fsw) << 4);
;   const int boff = 16384 + (wn * 64 + r16) * 64 + ((quad ^ fsw) << 4);
; DEVI void run_phase(const Params& p, int ph, char* smem) {
;     ...
;           const int u_ = t - 512, tl_ = u_ / 2, q_ = u_ - tl_ * 2;
;           gemm_tile256<EPI_RESID_ATOMIC>(p, ox, 256, Bt, 256, (64 + (tl_ & 1)) * 256, (tl_ >> 1) * 128, nullptr, 0, smem, q_ * 128, 4, q_);
.LBB0_147:
	s_cmpk_gt_i32 s38, 0x1ff
	s_mov_b64 s[2:3], -1
	s_cbranch_scc0 .LBB0_208
	s_sub_i32 s98, s38, 512
	s_lshr_b32 s41, s98, 1
	s_and_b32 s99, s98, 1
	s_lshr_b32 s13, s41, 1
	s_and_b32 s41, s41, 1
	s_add_i32 s41, s41, 64
	v_readlane_b32 s2, v250, 5
	v_readlane_b32 s3, v250, 6
	v_readlane_b32 s98, v254, 62
	s_mul_i32 s1, s41, 0x20000
	s_add_u32 s4, s2, s1
	s_addc_u32 s5, s3, 0
	s_add_u32 s4, s4, 0xe700000
	s_addc_u32 s5, s5, 0
	s_mul_i32 s1, s98, 0x80000
	s_mul_i32 s12, s13, 0x10000
	s_add_i32 s1, s1, s12
	s_add_u32 s8, s2, s1
	s_addc_u32 s9, s3, 0
	s_add_u32 s8, s8, 0x16c00000
	s_addc_u32 s9, s9, 0
	s_mul_i32 s1, s99, 256
	s_add_u32 s4, s4, s1
	s_addc_u32 s5, s5, 0
	s_mul_i32 s1, s99, 512
	s_add_u32 s8, s8, s1
	s_addc_u32 s9, s9, 0
	s_movk_i32 s0, 0x78
	v_lshrrev_b32_e32 v0, 2, v145
	v_and_b32_e32 v131, 3, v145
	v_bfe_u32 v136, v145, 4, 2
	v_lshlrev_b32_e32 v136, 1, v136
	v_lshrrev_b32_e64 v136, v136, s0
	v_and_b32_e32 v136, 3, v136
	v_xor_b32_e32 v131, v131, v136
	v_lshlrev_b32_e32 v131, 4, v131
	s_movk_i32 s12, 0x200
	v_mad_u32_u24 v0, v0, s12, v131
	v_bfe_u32 v137, v145, 2, 1
	s_movk_i32 s12, 0x1c0
	v_mul_u32_u24_e32 v136, s12, v137
	v_sub_u32_e32 v136, v0, v136
	v_mov_b32_e32 v137, 0
	v_lshl_add_u64 v[134:135], s[8:9], 0, v[136:137]
	v_bfe_u32 v137, v145, 2, 1
	s_mov_b32 s10, 64
	s_mov_b32 s11, 0
	v_lshl_add_u64 v[132:133], s[4:5], 0, v[0:1]
	v_bfe_u32 v136, v145, 2, 2
	v_lshlrev_b32_e32 v136, 1, v136
	v_lshrrev_b32_e64 v136, v136, s0
	v_and_b32_e32 v136, 3, v136
	v_bfe_u32 v137, v145, 4, 2
	v_xor_b32_e32 v136, v136, v137
	v_lshlrev_b32_e32 v136, 4, v136
	v_and_b32_e32 v131, 15, v145
	v_lshl_or_b32 v136, v131, 6, v136
	v_bfe_u32 v137, v145, 6, 1
	v_lshl_or_b32 v137, v137, 12, v136
	v_lshrrev_b32_e32 v0, 7, v145
	v_lshl_or_b32 v136, v0, 13, v136
	v_and_b32_e32 v140, 1, v131
	v_lshl_or_b32 v131, v0, 7, v131
	v_bfe_u32 v0, v145, 4, 2
	v_lshlrev_b32_e32 v0, 3, v0
	v_bfe_u32 v141, v145, 6, 1
	s_lshl_b32 s1, s41, 19
	s_lshl_b32 s12, s13, 8
	s_add_i32 s1, s1, s12
	s_add_u32 s4, s2, s1
	s_addc_u32 s5, s3, 0
	s_add_u32 s4, s4, 0x4200000
	s_addc_u32 s5, s5, 0
	v_lshlrev_b32_e32 v138, 11, v131
	v_lshl_add_u32 v138, v141, 7, v138
	v_add_u32_e32 v138, v138, v0
	v_mov_b32_e32 v139, 0
	v_lshl_add_u64 v[138:139], s[4:5], 0, v[138:139]
	s_and_b32 s1, s41, 1
	s_lshl_b32 s1, s1, 20
	s_lshl_b32 s12, s99, 21
	s_add_i32 s1, s1, s12
	s_lshl_b32 s12, s13, 9
	s_add_i32 s1, s1, s12
	s_add_u32 s8, s2, s1
	s_addc_u32 s9, s3, 0
	s_add_u32 s8, s8, 0x1dcc0000
	s_addc_u32 s9, s9, 0
	v_lshlrev_b32_e32 v140, 12, v131
	v_lshl_add_u32 v140, v141, 8, v140
	v_lshl_add_u32 v140, v0, 1, v140
	v_mov_b32_e32 v141, 0
	v_lshl_add_u64 v[140:141], s[8:9], 0, v[140:141]
	s_mov_b32 s2, 0x8000
	s_mov_b32 s3, 0
	v_lshrrev_b32_e32 v0, 6, v145
	v_lshlrev_b32_e32 v0, 10, v0
	s_nop 0
	v_readfirstlane_b32 s98, v0
	s_mov_b32 s39, m0
	s_mov_b32 s4, 128
	s_mov_b32 s5, 0
	v_mov_b32_e32 v2, 0
	v_mov_b32_e32 v3, 0
	v_mov_b32_e32 v4, 0
	v_mov_b32_e32 v5, 0
	v_mov_b32_e32 v6, 0
	v_mov_b32_e32 v7, 0
	v_mov_b32_e32 v8, 0
	v_mov_b32_e32 v9, 0
	v_mov_b32_e32 v10, 0
	v_mov_b32_e32 v11, 0
	v_mov_b32_e32 v12, 0
	v_mov_b32_e32 v13, 0
	v_mov_b32_e32 v14, 0
	v_mov_b32_e32 v15, 0
	v_mov_b32_e32 v16, 0
	v_mov_b32_e32 v17, 0
	v_mov_b32_e32 v18, 0
	v_mov_b32_e32 v19, 0
	v_mov_b32_e32 v20, 0
	v_mov_b32_e32 v21, 0
	v_mov_b32_e32 v22, 0
	v_mov_b32_e32 v23, 0
	v_mov_b32_e32 v24, 0
	v_mov_b32_e32 v25, 0
	v_mov_b32_e32 v26, 0
	v_mov_b32_e32 v27, 0
	v_mov_b32_e32 v28, 0
	v_mov_b32_e32 v29, 0
	v_mov_b32_e32 v30, 0
	v_mov_b32_e32 v31, 0
	v_mov_b32_e32 v32, 0
	v_mov_b32_e32 v33, 0
	v_mov_b32_e32 v34, 0
	v_mov_b32_e32 v35, 0
	v_mov_b32_e32 v36, 0
	v_mov_b32_e32 v37, 0
	v_mov_b32_e32 v38, 0
	v_mov_b32_e32 v39, 0
	v_mov_b32_e32 v40, 0
	v_mov_b32_e32 v41, 0
	v_mov_b32_e32 v42, 0
	v_mov_b32_e32 v43, 0
	v_mov_b32_e32 v44, 0
	v_mov_b32_e32 v45, 0
	v_mov_b32_e32 v46, 0
	v_mov_b32_e32 v47, 0
	v_mov_b32_e32 v48, 0
	v_mov_b32_e32 v49, 0
	v_mov_b32_e32 v50, 0
	v_mov_b32_e32 v51, 0
	v_mov_b32_e32 v52, 0
	v_mov_b32_e32 v53, 0
	v_mov_b32_e32 v54, 0
	v_mov_b32_e32 v55, 0
	v_mov_b32_e32 v56, 0
	v_mov_b32_e32 v57, 0
	v_mov_b32_e32 v58, 0
	v_mov_b32_e32 v59, 0
	v_mov_b32_e32 v60, 0
	v_mov_b32_e32 v61, 0
	v_mov_b32_e32 v62, 0
	v_mov_b32_e32 v63, 0
	v_mov_b32_e32 v64, 0
	v_mov_b32_e32 v65, 0
	v_mov_b32_e32 v66, 0
	v_mov_b32_e32 v67, 0
	v_mov_b32_e32 v68, 0
	v_mov_b32_e32 v69, 0
	v_mov_b32_e32 v70, 0
	v_mov_b32_e32 v71, 0
	v_mov_b32_e32 v72, 0
	v_mov_b32_e32 v73, 0
	v_mov_b32_e32 v74, 0
	v_mov_b32_e32 v75, 0
	v_mov_b32_e32 v76, 0
	v_mov_b32_e32 v77, 0
	v_mov_b32_e32 v78, 0
	v_mov_b32_e32 v79, 0
	v_mov_b32_e32 v80, 0
	v_mov_b32_e32 v81, 0
	v_mov_b32_e32 v82, 0
	v_mov_b32_e32 v83, 0
	v_mov_b32_e32 v84, 0
	v_mov_b32_e32 v85, 0
	v_mov_b32_e32 v86, 0
	v_mov_b32_e32 v87, 0
	v_mov_b32_e32 v88, 0
	v_mov_b32_e32 v89, 0
	v_mov_b32_e32 v90, 0
	v_mov_b32_e32 v91, 0
	v_mov_b32_e32 v92, 0
	v_mov_b32_e32 v93, 0
	v_mov_b32_e32 v94, 0
	v_mov_b32_e32 v95, 0
	v_mov_b32_e32 v96, 0
	v_mov_b32_e32 v97, 0
	v_mov_b32_e32 v98, 0
	v_mov_b32_e32 v99, 0
	v_mov_b32_e32 v100, 0
	v_mov_b32_e32 v101, 0
	v_mov_b32_e32 v102, 0
	v_mov_b32_e32 v103, 0
	v_mov_b32_e32 v104, 0
	v_mov_b32_e32 v105, 0
	v_mov_b32_e32 v106, 0
	v_mov_b32_e32 v107, 0
	v_mov_b32_e32 v108, 0
	v_mov_b32_e32 v109, 0
	v_mov_b32_e32 v110, 0
	v_mov_b32_e32 v111, 0
	v_mov_b32_e32 v112, 0
	v_mov_b32_e32 v113, 0
	v_mov_b32_e32 v114, 0
	v_mov_b32_e32 v115, 0
	v_mov_b32_e32 v116, 0
	v_mov_b32_e32 v117, 0
	v_mov_b32_e32 v118, 0
	v_mov_b32_e32 v119, 0
	v_mov_b32_e32 v120, 0
	v_mov_b32_e32 v121, 0
	v_mov_b32_e32 v122, 0
	v_mov_b32_e32 v123, 0
	v_mov_b32_e32 v124, 0
	v_mov_b32_e32 v125, 0
	v_mov_b32_e32 v126, 0
	v_mov_b32_e32 v127, 0
	v_mov_b32_e32 v128, 0
	v_mov_b32_e32 v129, 0
	s_barrier
;     ...
;   __syncthreads();
;   G2_STAGE(0); G2_STAGE(1);
;   const int fsw = (0x78 >> (((r16 >> 2) & 3) * 2)) & 3;
;   const int aoff = (wm * 128 + r16) * 64 + ((quad ^ fsw) << 4);
;   const int boff = 16384 + (wn * 64 + r16) * 64 + ((quad ^ fsw) << 4);
;   for (int kt = 0; kt < nk; kt++) {
;     if (kt + 1 < nk) asm volatile("s_waitcnt vmcnt(6)" ::: "memory");
;     else asm volatile("s_waitcnt vmcnt(0)" ::: "memory");
;     __builtin_amdgcn_s_barrier();
;     asm volatile("" ::: "memory");
;     if (kt + 2 < nk) G2_STAGE(kt + 2);
;     const char* cS = smem + (kt % 3) * 24576;
;     bf16x8 xa[8], wb[4];
; #pragma unroll
;     for (int f = 0; f < 8; f++) xa[f] = *(const bf16x8*)(cS + aoff + f * 1024);
; #pragma unroll
;     for (int f = 0; f < 4; f++) wb[f] = *(const bf16x8*)(cS + boff + f * 1024);
; #pragma unroll
;     for (int nf = 0; nf < 4; nf++)
; #pragma unroll
;       for (int mf = 0; mf < 8; mf++)
;         acc[nf][mf] = __builtin_amdgcn_mfma_f32_16x16x32_bf16(wb[nf], xa[mf], acc[nf][mf], 0, 0, 0);
;   }
	s_add_i32 s13, s98, 0x0
	s_mov_b32 m0, s13
	v_lshl_add_u64 v[142:143], v[132:133], 0, s[2:3]
	global_load_lds_dwordx4 v[132:133], off
	s_addk_i32 m0, 0x1000
	s_nop 0
	global_load_lds_dwordx4 v[142:143], off
	v_lshl_add_u64 v[142:143], v[142:143], 0, s[2:3]
	s_addk_i32 m0, 0x1000
	s_nop 0
	global_load_lds_dwordx4 v[142:143], off
	v_lshl_add_u64 v[142:143], v[142:143], 0, s[2:3]
	s_addk_i32 m0, 0x1000
	s_nop 0
	global_load_lds_dwordx4 v[142:143], off
	s_addk_i32 m0, 0x1000
	v_lshl_add_u64 v[142:143], v[134:135], 0, s[2:3]
	s_nop 0
	global_load_lds_dwordx4 v[134:135], off
	s_addk_i32 m0, 0x1000
	v_lshl_add_u64 v[132:133], v[132:133], 0, s[10:11]
	s_nop 0
	global_load_lds_dwordx4 v[142:143], off
	v_lshl_add_u64 v[134:135], v[134:135], 0, s[4:5]
	s_nop 0
	s_add_i32 s13, s98, 0x6000
	s_mov_b32 m0, s13
	v_lshl_add_u64 v[142:143], v[132:133], 0, s[2:3]
	global_load_lds_dwordx4 v[132:133], off
	s_addk_i32 m0, 0x1000
	s_nop 0
	global_load_lds_dwordx4 v[142:143], off
	v_lshl_add_u64 v[142:143], v[142:143], 0, s[2:3]
	s_addk_i32 m0, 0x1000
	s_nop 0
	global_load_lds_dwordx4 v[142:143], off
	v_lshl_add_u64 v[142:143], v[142:143], 0, s[2:3]
	s_addk_i32 m0, 0x1000
	s_nop 0
	global_load_lds_dwordx4 v[142:143], off
	s_addk_i32 m0, 0x1000
	v_lshl_add_u64 v[142:143], v[134:135], 0, s[2:3]
	s_nop 0
	global_load_lds_dwordx4 v[134:135], off
	s_addk_i32 m0, 0x1000
	v_lshl_add_u64 v[132:133], v[132:133], 0, s[10:11]
	s_nop 0
	global_load_lds_dwordx4 v[142:143], off
	v_lshl_add_u64 v[134:135], v[134:135], 0, s[4:5]
	s_nop 0
	s_add_i32 s13, s98, 0xc000
	s_mov_b32 m0, s13
	v_lshl_add_u64 v[142:143], v[132:133], 0, s[2:3]
	global_load_lds_dwordx4 v[132:133], off
	s_addk_i32 m0, 0x1000
	s_nop 0
	global_load_lds_dwordx4 v[142:143], off
	v_lshl_add_u64 v[142:143], v[142:143], 0, s[2:3]
	s_addk_i32 m0, 0x1000
	s_nop 0
	global_load_lds_dwordx4 v[142:143], off
	v_lshl_add_u64 v[142:143], v[142:143], 0, s[2:3]
	s_addk_i32 m0, 0x1000
	s_nop 0
	global_load_lds_dwordx4 v[142:143], off
	s_addk_i32 m0, 0x1000
	v_lshl_add_u64 v[142:143], v[134:135], 0, s[2:3]
	s_nop 0
	global_load_lds_dwordx4 v[134:135], off
	s_addk_i32 m0, 0x1000
	v_lshl_add_u64 v[132:133], v[132:133], 0, s[10:11]
	s_nop 0
	global_load_lds_dwordx4 v[142:143], off
	v_lshl_add_u64 v[134:135], v[134:135], 0, s[4:5]
	s_nop 0
	s_waitcnt vmcnt(12)
	s_barrier
	ds_read_b128 v[146:149], v136 offset:0
	ds_read_b128 v[152:155], v136 offset:1024
	ds_read_b128 v[156:159], v136 offset:2048
	ds_read_b128 v[162:165], v136 offset:3072
	ds_read_b128 v[166:169], v136 offset:4096
	ds_read_b128 v[170:173], v136 offset:5120
	ds_read_b128 v[176:179], v136 offset:6144
	ds_read_b128 v[180:183], v136 offset:7168
	ds_read_b128 v[184:187], v137 offset:16384
	ds_read_b128 v[188:191], v137 offset:17408
	ds_read_b128 v[192:195], v137 offset:18432
	ds_read_b128 v[196:199], v137 offset:19456
	s_movk_i32 s1, 0x6000
	s_mov_b32 s12, 0
	s_waitcnt vmcnt(6) lgkmcnt(0)
	s_barrier
	v_add_u32_e32 v144, s1, v136
	v_mfma_f32_16x16x32_bf16 v[126:129], v[184:187], v[146:149], v[126:129]
	ds_read_b128 v[200:203], v144 offset:0
	v_mfma_f32_16x16x32_bf16 v[122:125], v[184:187], v[152:155], v[122:125]
	ds_read_b128 v[204:207], v144 offset:1024
	v_mfma_f32_16x16x32_bf16 v[118:121], v[184:187], v[156:159], v[118:121]
	ds_read_b128 v[208:211], v144 offset:2048
	v_mfma_f32_16x16x32_bf16 v[114:117], v[184:187], v[162:165], v[114:117]
	ds_read_b128 v[212:215], v144 offset:3072
	v_mfma_f32_16x16x32_bf16 v[110:113], v[184:187], v[166:169], v[110:113]
	ds_read_b128 v[216:219], v144 offset:4096
	v_mfma_f32_16x16x32_bf16 v[106:109], v[184:187], v[170:173], v[106:109]
	ds_read_b128 v[220:223], v144 offset:5120
	v_mfma_f32_16x16x32_bf16 v[102:105], v[184:187], v[176:179], v[102:105]
	ds_read_b128 v[224:227], v144 offset:6144
	v_mfma_f32_16x16x32_bf16 v[98:101], v[184:187], v[180:183], v[98:101]
	ds_read_b128 v[228:231], v144 offset:7168
	v_mfma_f32_16x16x32_bf16 v[94:97], v[188:191], v[146:149], v[94:97]
	v_add_u32_e32 v144, s1, v137
	v_mfma_f32_16x16x32_bf16 v[90:93], v[188:191], v[152:155], v[90:93]
	v_mfma_f32_16x16x32_bf16 v[86:89], v[188:191], v[156:159], v[86:89]
	ds_read_b128 v[232:235], v144 offset:16384
	v_mfma_f32_16x16x32_bf16 v[82:85], v[188:191], v[162:165], v[82:85]
	ds_read_b128 v[236:239], v144 offset:17408
	v_mfma_f32_16x16x32_bf16 v[78:81], v[188:191], v[166:169], v[78:81]
	ds_read_b128 v[240:243], v144 offset:18432
	v_mfma_f32_16x16x32_bf16 v[74:77], v[188:191], v[170:173], v[74:77]
	ds_read_b128 v[244:247], v144 offset:19456
	s_add_i32 s13, s98, s12
	v_mfma_f32_16x16x32_bf16 v[70:73], v[188:191], v[176:179], v[70:73]
	s_mov_b32 m0, s13
	v_lshl_add_u64 v[142:143], v[132:133], 0, s[2:3]
	v_mfma_f32_16x16x32_bf16 v[66:69], v[188:191], v[180:183], v[66:69]
	global_load_lds_dwordx4 v[132:133], off
	s_addk_i32 m0, 0x1000
	v_mfma_f32_16x16x32_bf16 v[62:65], v[192:195], v[146:149], v[62:65]
	v_mfma_f32_16x16x32_bf16 v[58:61], v[192:195], v[152:155], v[58:61]
	v_mfma_f32_16x16x32_bf16 v[54:57], v[192:195], v[156:159], v[54:57]
	global_load_lds_dwordx4 v[142:143], off
	v_lshl_add_u64 v[142:143], v[142:143], 0, s[2:3]
	s_addk_i32 m0, 0x1000
	v_mfma_f32_16x16x32_bf16 v[50:53], v[192:195], v[162:165], v[50:53]
	v_mfma_f32_16x16x32_bf16 v[46:49], v[192:195], v[166:169], v[46:49]
	v_mfma_f32_16x16x32_bf16 v[42:45], v[192:195], v[170:173], v[42:45]
	global_load_lds_dwordx4 v[142:143], off
	v_lshl_add_u64 v[142:143], v[142:143], 0, s[2:3]
	s_addk_i32 m0, 0x1000
	v_mfma_f32_16x16x32_bf16 v[38:41], v[192:195], v[176:179], v[38:41]
	v_mfma_f32_16x16x32_bf16 v[34:37], v[192:195], v[180:183], v[34:37]
	v_mfma_f32_16x16x32_bf16 v[30:33], v[196:199], v[146:149], v[30:33]
	global_load_lds_dwordx4 v[142:143], off
	s_addk_i32 m0, 0x1000
	v_lshl_add_u64 v[142:143], v[134:135], 0, s[2:3]
	v_mfma_f32_16x16x32_bf16 v[26:29], v[196:199], v[152:155], v[26:29]
	v_mfma_f32_16x16x32_bf16 v[22:25], v[196:199], v[156:159], v[22:25]
	v_mfma_f32_16x16x32_bf16 v[18:21], v[196:199], v[162:165], v[18:21]
	global_load_lds_dwordx4 v[134:135], off
	s_addk_i32 m0, 0x1000
	v_lshl_add_u64 v[132:133], v[132:133], 0, s[10:11]
	v_mfma_f32_16x16x32_bf16 v[14:17], v[196:199], v[166:169], v[14:17]
	v_mfma_f32_16x16x32_bf16 v[10:13], v[196:199], v[170:173], v[10:13]
	v_mfma_f32_16x16x32_bf16 v[6:9], v[196:199], v[176:179], v[6:9]
	global_load_lds_dwordx4 v[142:143], off
	v_lshl_add_u64 v[134:135], v[134:135], 0, s[4:5]
	v_mfma_f32_16x16x32_bf16 v[2:5], v[196:199], v[180:183], v[2:5]
	s_mov_b32 s12, s1
	s_add_i32 s1, s1, 0x6000
	s_cmp_eq_u32 s1, 0x12000
	s_cselect_b32 s1, 0, s1
	s_waitcnt vmcnt(6) lgkmcnt(0)
	s_barrier
; DEVI float blo(unsigned u) { return __uint_as_float(u << 16); }
;     ...
;   __syncthreads();
;   G2_STAGE(0); G2_STAGE(1);
;   const int fsw = (0x78 >> (((r16 >> 2) & 3) * 2)) & 3;
;   const int aoff = (wm * 128 + r16) * 64 + ((quad ^ fsw) << 4);
;   const int boff = 16384 + (wn * 64 + r16) * 64 + ((quad ^ fsw) << 4);
;   for (int kt = 0; kt < nk; kt++) {
;     if (kt + 1 < nk) asm volatile("s_waitcnt vmcnt(6)" ::: "memory");
;     else asm volatile("s_waitcnt vmcnt(0)" ::: "memory");
;     __builtin_amdgcn_s_barrier();
;     asm volatile("" ::: "memory");
;     if (kt + 2 < nk) G2_STAGE(kt + 2);
;     const char* cS = smem + (kt % 3) * 24576;
;     bf16x8 xa[8], wb[4];
; #pragma unroll
;     for (int f = 0; f < 8; f++) xa[f] = *(const bf16x8*)(cS + aoff + f * 1024);
; #pragma unroll
;     for (int f = 0; f < 4; f++) wb[f] = *(const bf16x8*)(cS + boff + f * 1024);
; #pragma unroll
;     for (int nf = 0; nf < 4; nf++)
; #pragma unroll
;       for (int mf = 0; mf < 8; mf++)
;         acc[nf][mf] = __builtin_amdgcn_mfma_f32_16x16x32_bf16(wb[nf], xa[mf], acc[nf][mf], 0, 0, 0);
;   }
;     ...
; #pragma unroll
;   for (int mf = 0; mf < 8; mf++) {
;     const int row = m0 + wm * 128 + mf * 16 + r16;
;     if (EPI == EPI_SWIGLU) {
; #pragma unroll
;       for (int nf = 0; nf < 2; nf++) {
;         const int hcol = (n0 >> 1) + wn * 32 + nf * 16 + quad * 4;
;         f32x4 g = acc[nf][mf], u = acc[nf + 2][mf];
;         u32x2 pk;
;         pk[0] = pack2(siluf_(g[0]) * u[0], siluf_(g[1]) * u[1]);
;         pk[1] = pack2(siluf_(g[2]) * u[2], siluf_(g[3]) * u[3]);
;         *(u32x2*)(outb + (size_t)row * DFF + hcol) = pk;
;       }
;     } else {
; #pragma unroll
;       for (int nf = 0; nf < 4; nf++) {
;         const int col = n0 + wn * 64 + nf * 16 + quad * 4;
;         f32x4 a = acc[nf][mf];
;         if (EPI == EPI_RESID || EPI == EPI_RESID_ATOMIC) {
;           f32x4 x = a;
;           if (EPI == EPI_RESID || kpart == 0) {
;             const u32x2 xr = *(const u32x2*)((const u16*)(p.ws + WS_XB) + (size_t)row * 1024 + col);
;             x[0] += ALPHA * blo(xr[0]); x[1] += ALPHA * bhi(xr[0]); x[2] += ALPHA * blo(xr[1]); x[3] += ALPHA * bhi(xr[1]);
;           }
;           if (EPI == EPI_RESID) *(f32x4*)((float*)(p.ws + WS_XF) + (size_t)row * 1024 + col) = x;
;           else *(f32x4*)((float*)(p.ws + WS_SLAB) + ((size_t)kpart * 512 + (row - T_P)) * 1024 + col) = x;
	v_add_u32_e32 v144, s1, v136
	v_mfma_f32_16x16x32_bf16 v[126:129], v[232:235], v[200:203], v[126:129]
	ds_read_b128 v[146:149], v144 offset:0
	v_mfma_f32_16x16x32_bf16 v[122:125], v[232:235], v[204:207], v[122:125]
	ds_read_b128 v[152:155], v144 offset:1024
	v_mfma_f32_16x16x32_bf16 v[118:121], v[232:235], v[208:211], v[118:121]
	ds_read_b128 v[156:159], v144 offset:2048
	v_mfma_f32_16x16x32_bf16 v[114:117], v[232:235], v[212:215], v[114:117]
	ds_read_b128 v[162:165], v144 offset:3072
	v_mfma_f32_16x16x32_bf16 v[110:113], v[232:235], v[216:219], v[110:113]
	ds_read_b128 v[166:169], v144 offset:4096
	v_mfma_f32_16x16x32_bf16 v[106:109], v[232:235], v[220:223], v[106:109]
	ds_read_b128 v[170:173], v144 offset:5120
	v_mfma_f32_16x16x32_bf16 v[102:105], v[232:235], v[224:227], v[102:105]
	ds_read_b128 v[176:179], v144 offset:6144
	v_mfma_f32_16x16x32_bf16 v[98:101], v[232:235], v[228:231], v[98:101]
	ds_read_b128 v[180:183], v144 offset:7168
	v_mfma_f32_16x16x32_bf16 v[94:97], v[236:239], v[200:203], v[94:97]
	v_add_u32_e32 v144, s1, v137
	v_mfma_f32_16x16x32_bf16 v[90:93], v[236:239], v[204:207], v[90:93]
	v_mfma_f32_16x16x32_bf16 v[86:89], v[236:239], v[208:211], v[86:89]
	ds_read_b128 v[184:187], v144 offset:16384
	v_mfma_f32_16x16x32_bf16 v[82:85], v[236:239], v[212:215], v[82:85]
	ds_read_b128 v[188:191], v144 offset:17408
	v_mfma_f32_16x16x32_bf16 v[78:81], v[236:239], v[216:219], v[78:81]
	ds_read_b128 v[192:195], v144 offset:18432
	v_mfma_f32_16x16x32_bf16 v[74:77], v[236:239], v[220:223], v[74:77]
	ds_read_b128 v[196:199], v144 offset:19456
	v_mfma_f32_16x16x32_bf16 v[70:73], v[236:239], v[224:227], v[70:73]
	v_mfma_f32_16x16x32_bf16 v[66:69], v[236:239], v[228:231], v[66:69]
	v_mfma_f32_16x16x32_bf16 v[62:65], v[240:243], v[200:203], v[62:65]
	v_mfma_f32_16x16x32_bf16 v[58:61], v[240:243], v[204:207], v[58:61]
	v_mfma_f32_16x16x32_bf16 v[54:57], v[240:243], v[208:211], v[54:57]
	v_mfma_f32_16x16x32_bf16 v[50:53], v[240:243], v[212:215], v[50:53]
	v_mfma_f32_16x16x32_bf16 v[46:49], v[240:243], v[216:219], v[46:49]
	v_mfma_f32_16x16x32_bf16 v[42:45], v[240:243], v[220:223], v[42:45]
	v_mfma_f32_16x16x32_bf16 v[38:41], v[240:243], v[224:227], v[38:41]
	v_mfma_f32_16x16x32_bf16 v[34:37], v[240:243], v[228:231], v[34:37]
	v_mfma_f32_16x16x32_bf16 v[30:33], v[244:247], v[200:203], v[30:33]
	v_mfma_f32_16x16x32_bf16 v[26:29], v[244:247], v[204:207], v[26:29]
	v_mfma_f32_16x16x32_bf16 v[22:25], v[244:247], v[208:211], v[22:25]
	v_mfma_f32_16x16x32_bf16 v[18:21], v[244:247], v[212:215], v[18:21]
	v_mfma_f32_16x16x32_bf16 v[14:17], v[244:247], v[216:219], v[14:17]
	v_mfma_f32_16x16x32_bf16 v[10:13], v[244:247], v[220:223], v[10:13]
	v_mfma_f32_16x16x32_bf16 v[6:9], v[244:247], v[224:227], v[6:9]
	v_mfma_f32_16x16x32_bf16 v[2:5], v[244:247], v[228:231], v[2:5]
	s_mov_b32 s12, s1
	s_add_i32 s1, s1, 0x6000
	s_cmp_eq_u32 s1, 0x12000
	s_cselect_b32 s1, 0, s1
	s_waitcnt vmcnt(0) lgkmcnt(0)
	s_barrier
	v_add_u32_e32 v144, s1, v136
	v_mfma_f32_16x16x32_bf16 v[126:129], v[184:187], v[146:149], v[126:129]
	ds_read_b128 v[200:203], v144 offset:0
	v_mfma_f32_16x16x32_bf16 v[122:125], v[184:187], v[152:155], v[122:125]
	ds_read_b128 v[204:207], v144 offset:1024
	v_mfma_f32_16x16x32_bf16 v[118:121], v[184:187], v[156:159], v[118:121]
	ds_read_b128 v[208:211], v144 offset:2048
	v_mfma_f32_16x16x32_bf16 v[114:117], v[184:187], v[162:165], v[114:117]
	ds_read_b128 v[212:215], v144 offset:3072
	v_mfma_f32_16x16x32_bf16 v[110:113], v[184:187], v[166:169], v[110:113]
	ds_read_b128 v[216:219], v144 offset:4096
	v_mfma_f32_16x16x32_bf16 v[106:109], v[184:187], v[170:173], v[106:109]
	ds_read_b128 v[220:223], v144 offset:5120
	v_mfma_f32_16x16x32_bf16 v[102:105], v[184:187], v[176:179], v[102:105]
	ds_read_b128 v[224:227], v144 offset:6144
	v_mfma_f32_16x16x32_bf16 v[98:101], v[184:187], v[180:183], v[98:101]
	ds_read_b128 v[228:231], v144 offset:7168
	v_mfma_f32_16x16x32_bf16 v[94:97], v[188:191], v[146:149], v[94:97]
	v_add_u32_e32 v144, s1, v137
	v_mfma_f32_16x16x32_bf16 v[90:93], v[188:191], v[152:155], v[90:93]
	v_mfma_f32_16x16x32_bf16 v[86:89], v[188:191], v[156:159], v[86:89]
	ds_read_b128 v[232:235], v144 offset:16384
	v_mfma_f32_16x16x32_bf16 v[82:85], v[188:191], v[162:165], v[82:85]
	ds_read_b128 v[236:239], v144 offset:17408
	v_mfma_f32_16x16x32_bf16 v[78:81], v[188:191], v[166:169], v[78:81]
	ds_read_b128 v[240:243], v144 offset:18432
	v_mfma_f32_16x16x32_bf16 v[74:77], v[188:191], v[170:173], v[74:77]
	ds_read_b128 v[244:247], v144 offset:19456
	v_mfma_f32_16x16x32_bf16 v[70:73], v[188:191], v[176:179], v[70:73]
	v_mfma_f32_16x16x32_bf16 v[66:69], v[188:191], v[180:183], v[66:69]
	v_mfma_f32_16x16x32_bf16 v[62:65], v[192:195], v[146:149], v[62:65]
	v_mfma_f32_16x16x32_bf16 v[58:61], v[192:195], v[152:155], v[58:61]
	v_mfma_f32_16x16x32_bf16 v[54:57], v[192:195], v[156:159], v[54:57]
	v_mfma_f32_16x16x32_bf16 v[50:53], v[192:195], v[162:165], v[50:53]
	v_mfma_f32_16x16x32_bf16 v[46:49], v[192:195], v[166:169], v[46:49]
	v_mfma_f32_16x16x32_bf16 v[42:45], v[192:195], v[170:173], v[42:45]
	v_mfma_f32_16x16x32_bf16 v[38:41], v[192:195], v[176:179], v[38:41]
	v_mfma_f32_16x16x32_bf16 v[34:37], v[192:195], v[180:183], v[34:37]
	v_mfma_f32_16x16x32_bf16 v[30:33], v[196:199], v[146:149], v[30:33]
	v_mfma_f32_16x16x32_bf16 v[26:29], v[196:199], v[152:155], v[26:29]
	v_mfma_f32_16x16x32_bf16 v[22:25], v[196:199], v[156:159], v[22:25]
	v_mfma_f32_16x16x32_bf16 v[18:21], v[196:199], v[162:165], v[18:21]
	v_mfma_f32_16x16x32_bf16 v[14:17], v[196:199], v[166:169], v[14:17]
	v_mfma_f32_16x16x32_bf16 v[10:13], v[196:199], v[170:173], v[10:13]
	v_mfma_f32_16x16x32_bf16 v[6:9], v[196:199], v[176:179], v[6:9]
	v_mfma_f32_16x16x32_bf16 v[2:5], v[196:199], v[180:183], v[2:5]
	s_mov_b32 s12, s1
	s_add_i32 s1, s1, 0x6000
	s_cmp_eq_u32 s1, 0x12000
	s_cselect_b32 s1, 0, s1
	s_mov_b32 s4, 0x8000
	s_mov_b32 s5, 0
	s_mov_b32 s8, 0x10000
	s_mov_b32 s9, 0
	s_mov_b32 s40, 0x3fd744fd
	s_waitcnt lgkmcnt(0)
; DEVI unsigned pack2(float a, float b) { return __builtin_bit_cast(unsigned, __builtin_convertvector((f32x2_t){a, b}, bf16x2_t)); }
; DEVI float blo(unsigned u) { return __uint_as_float(u << 16); }
; DEVI float bhi(unsigned u) { return __uint_as_float(u & 0xffff0000u); }
; DEVI float siluf_(float x) { return x * __builtin_amdgcn_rcpf(1.f + __expf(-x)); }
;     ...
;       for (int mf = 0; mf < 8; mf++)
;         acc[nf][mf] = __builtin_amdgcn_mfma_f32_16x16x32_bf16(wb[nf], xa[mf], acc[nf][mf], 0, 0, 0);
;   }
;     ...
; #pragma unroll
;   for (int mf = 0; mf < 8; mf++) {
;     const int row = m0 + wm * 128 + mf * 16 + r16;
;     if (EPI == EPI_SWIGLU) {
; #pragma unroll
;       for (int nf = 0; nf < 2; nf++) {
;         const int hcol = (n0 >> 1) + wn * 32 + nf * 16 + quad * 4;
;         f32x4 g = acc[nf][mf], u = acc[nf + 2][mf];
;         u32x2 pk;
;         pk[0] = pack2(siluf_(g[0]) * u[0], siluf_(g[1]) * u[1]);
;         pk[1] = pack2(siluf_(g[2]) * u[2], siluf_(g[3]) * u[3]);
;         *(u32x2*)(outb + (size_t)row * DFF + hcol) = pk;
;       }
;     } else {
; #pragma unroll
;       for (int nf = 0; nf < 4; nf++) {
;         const int col = n0 + wn * 64 + nf * 16 + quad * 4;
;         f32x4 a = acc[nf][mf];
;         if (EPI == EPI_RESID || EPI == EPI_RESID_ATOMIC) {
;           f32x4 x = a;
;           if (EPI == EPI_RESID || kpart == 0) {
;             const u32x2 xr = *(const u32x2*)((const u16*)(p.ws + WS_XB) + (size_t)row * 1024 + col);
;             x[0] += ALPHA * blo(xr[0]); x[1] += ALPHA * bhi(xr[0]); x[2] += ALPHA * blo(xr[1]); x[3] += ALPHA * bhi(xr[1]);
;           }
;           if (EPI == EPI_RESID) *(f32x4*)((float*)(p.ws + WS_XF) + (size_t)row * 1024 + col) = x;
;           else *(f32x4*)((float*)(p.ws + WS_SLAB) + ((size_t)kpart * 512 + (row - T_P)) * 1024 + col) = x;
	v_mfma_f32_16x16x32_bf16 v[126:129], v[232:235], v[200:203], v[126:129]
	v_mfma_f32_16x16x32_bf16 v[122:125], v[232:235], v[204:207], v[122:125]
	v_mfma_f32_16x16x32_bf16 v[118:121], v[232:235], v[208:211], v[118:121]
	v_mfma_f32_16x16x32_bf16 v[114:117], v[232:235], v[212:215], v[114:117]
	v_mfma_f32_16x16x32_bf16 v[110:113], v[232:235], v[216:219], v[110:113]
	v_mfma_f32_16x16x32_bf16 v[106:109], v[232:235], v[220:223], v[106:109]
	v_mfma_f32_16x16x32_bf16 v[102:105], v[232:235], v[224:227], v[102:105]
	v_mfma_f32_16x16x32_bf16 v[98:101], v[232:235], v[228:231], v[98:101]
	v_mfma_f32_16x16x32_bf16 v[94:97], v[236:239], v[200:203], v[94:97]
	v_mfma_f32_16x16x32_bf16 v[90:93], v[236:239], v[204:207], v[90:93]
	v_mfma_f32_16x16x32_bf16 v[86:89], v[236:239], v[208:211], v[86:89]
	v_mfma_f32_16x16x32_bf16 v[82:85], v[236:239], v[212:215], v[82:85]
	v_mfma_f32_16x16x32_bf16 v[78:81], v[236:239], v[216:219], v[78:81]
	v_mfma_f32_16x16x32_bf16 v[74:77], v[236:239], v[220:223], v[74:77]
	v_mfma_f32_16x16x32_bf16 v[70:73], v[236:239], v[224:227], v[70:73]
	v_mfma_f32_16x16x32_bf16 v[66:69], v[236:239], v[228:231], v[66:69]
	v_mfma_f32_16x16x32_bf16 v[62:65], v[240:243], v[200:203], v[62:65]
	v_mfma_f32_16x16x32_bf16 v[58:61], v[240:243], v[204:207], v[58:61]
	v_mfma_f32_16x16x32_bf16 v[54:57], v[240:243], v[208:211], v[54:57]
	v_mfma_f32_16x16x32_bf16 v[50:53], v[240:243], v[212:215], v[50:53]
	v_mfma_f32_16x16x32_bf16 v[46:49], v[240:243], v[216:219], v[46:49]
	v_mfma_f32_16x16x32_bf16 v[42:45], v[240:243], v[220:223], v[42:45]
	v_mfma_f32_16x16x32_bf16 v[38:41], v[240:243], v[224:227], v[38:41]
	v_mfma_f32_16x16x32_bf16 v[34:37], v[240:243], v[228:231], v[34:37]
	v_mfma_f32_16x16x32_bf16 v[30:33], v[244:247], v[200:203], v[30:33]
	v_mfma_f32_16x16x32_bf16 v[26:29], v[244:247], v[204:207], v[26:29]
	v_mfma_f32_16x16x32_bf16 v[22:25], v[244:247], v[208:211], v[22:25]
	v_mfma_f32_16x16x32_bf16 v[18:21], v[244:247], v[212:215], v[18:21]
	v_mfma_f32_16x16x32_bf16 v[14:17], v[244:247], v[216:219], v[14:17]
	v_mfma_f32_16x16x32_bf16 v[10:13], v[244:247], v[220:223], v[10:13]
	v_mfma_f32_16x16x32_bf16 v[6:9], v[244:247], v[224:227], v[6:9]
	v_mfma_f32_16x16x32_bf16 v[2:5], v[244:247], v[228:231], v[2:5]
	s_mov_b32 m0, s39
	s_cmp_eq_u32 s99, 0
	s_cbranch_scc1 .Lta8_first
	s_nop 7
	global_store_dwordx4 v[140:141], v[126:129], off offset:0
	global_store_dwordx4 v[140:141], v[94:97], off offset:64
	global_store_dwordx4 v[140:141], v[62:65], off offset:128
	global_store_dwordx4 v[140:141], v[30:33], off offset:192
	v_lshl_add_u64 v[140:141], v[140:141], 0, s[8:9]
	global_store_dwordx4 v[140:141], v[122:125], off offset:0
	global_store_dwordx4 v[140:141], v[90:93], off offset:64
	global_store_dwordx4 v[140:141], v[58:61], off offset:128
	global_store_dwordx4 v[140:141], v[26:29], off offset:192
	v_lshl_add_u64 v[140:141], v[140:141], 0, s[8:9]
	global_store_dwordx4 v[140:141], v[118:121], off offset:0
	global_store_dwordx4 v[140:141], v[86:89], off offset:64
	global_store_dwordx4 v[140:141], v[54:57], off offset:128
	global_store_dwordx4 v[140:141], v[22:25], off offset:192
	v_lshl_add_u64 v[140:141], v[140:141], 0, s[8:9]
	global_store_dwordx4 v[140:141], v[114:117], off offset:0
	global_store_dwordx4 v[140:141], v[82:85], off offset:64
	global_store_dwordx4 v[140:141], v[50:53], off offset:128
	global_store_dwordx4 v[140:141], v[18:21], off offset:192
	v_lshl_add_u64 v[140:141], v[140:141], 0, s[8:9]
	global_store_dwordx4 v[140:141], v[110:113], off offset:0
	global_store_dwordx4 v[140:141], v[78:81], off offset:64
	global_store_dwordx4 v[140:141], v[46:49], off offset:128
	global_store_dwordx4 v[140:141], v[14:17], off offset:192
	v_lshl_add_u64 v[140:141], v[140:141], 0, s[8:9]
	global_store_dwordx4 v[140:141], v[106:109], off offset:0
	global_store_dwordx4 v[140:141], v[74:77], off offset:64
	global_store_dwordx4 v[140:141], v[42:45], off offset:128
	global_store_dwordx4 v[140:141], v[10:13], off offset:192
	v_lshl_add_u64 v[140:141], v[140:141], 0, s[8:9]
	global_store_dwordx4 v[140:141], v[102:105], off offset:0
	global_store_dwordx4 v[140:141], v[70:73], off offset:64
	global_store_dwordx4 v[140:141], v[38:41], off offset:128
	global_store_dwordx4 v[140:141], v[6:9], off offset:192
	v_lshl_add_u64 v[140:141], v[140:141], 0, s[8:9]
	global_store_dwordx4 v[140:141], v[98:101], off offset:0
	global_store_dwordx4 v[140:141], v[66:69], off offset:64
	global_store_dwordx4 v[140:141], v[34:37], off offset:128
	global_store_dwordx4 v[140:141], v[2:5], off offset:192
	s_branch .LBB0_146
; DEVI float blo(unsigned u) { return __uint_as_float(u << 16); }
; DEVI float bhi(unsigned u) { return __uint_as_float(u & 0xffff0000u); }
;     ...
;         if (EPI == EPI_RESID || EPI == EPI_RESID_ATOMIC) {
;           f32x4 x = a;
;           if (EPI == EPI_RESID || kpart == 0) {
;             const u32x2 xr = *(const u32x2*)((const u16*)(p.ws + WS_XB) + (size_t)row * 1024 + col);
;             x[0] += ALPHA * blo(xr[0]); x[1] += ALPHA * bhi(xr[0]); x[2] += ALPHA * blo(xr[1]); x[3] += ALPHA * bhi(xr[1]);
;           }
;           if (EPI == EPI_RESID) *(f32x4*)((float*)(p.ws + WS_XF) + (size_t)row * 1024 + col) = x;
;           else *(f32x4*)((float*)(p.ws + WS_SLAB) + ((size_t)kpart * 512 + (row - T_P)) * 1024 + col) = x;
.Lta8_first:
	global_load_dwordx2 v[146:147], v[138:139], off offset:0
	global_load_dwordx2 v[148:149], v[138:139], off offset:32
	global_load_dwordx2 v[152:153], v[138:139], off offset:64
	global_load_dwordx2 v[154:155], v[138:139], off offset:96
	v_lshl_add_u64 v[138:139], v[138:139], 0, s[4:5]
	global_load_dwordx2 v[156:157], v[138:139], off offset:0
	global_load_dwordx2 v[158:159], v[138:139], off offset:32
	global_load_dwordx2 v[162:163], v[138:139], off offset:64
	global_load_dwordx2 v[164:165], v[138:139], off offset:96
	v_lshl_add_u64 v[138:139], v[138:139], 0, s[4:5]
	global_load_dwordx2 v[166:167], v[138:139], off offset:0
	global_load_dwordx2 v[168:169], v[138:139], off offset:32
	global_load_dwordx2 v[170:171], v[138:139], off offset:64
	global_load_dwordx2 v[172:173], v[138:139], off offset:96
	v_lshl_add_u64 v[138:139], v[138:139], 0, s[4:5]
	global_load_dwordx2 v[176:177], v[138:139], off offset:0
	global_load_dwordx2 v[178:179], v[138:139], off offset:32
	global_load_dwordx2 v[180:181], v[138:139], off offset:64
	global_load_dwordx2 v[182:183], v[138:139], off offset:96
	v_lshl_add_u64 v[138:139], v[138:139], 0, s[4:5]
	global_load_dwordx2 v[184:185], v[138:139], off offset:0
	global_load_dwordx2 v[186:187], v[138:139], off offset:32
	global_load_dwordx2 v[188:189], v[138:139], off offset:64
	global_load_dwordx2 v[190:191], v[138:139], off offset:96
	v_lshl_add_u64 v[138:139], v[138:139], 0, s[4:5]
	global_load_dwordx2 v[192:193], v[138:139], off offset:0
	global_load_dwordx2 v[194:195], v[138:139], off offset:32
	global_load_dwordx2 v[196:197], v[138:139], off offset:64
	global_load_dwordx2 v[198:199], v[138:139], off offset:96
	v_lshl_add_u64 v[138:139], v[138:139], 0, s[4:5]
	global_load_dwordx2 v[200:201], v[138:139], off offset:0
	global_load_dwordx2 v[202:203], v[138:139], off offset:32
	global_load_dwordx2 v[204:205], v[138:139], off offset:64
	global_load_dwordx2 v[206:207], v[138:139], off offset:96
	v_lshl_add_u64 v[138:139], v[138:139], 0, s[4:5]
	global_load_dwordx2 v[208:209], v[138:139], off offset:0
	global_load_dwordx2 v[210:211], v[138:139], off offset:32
	global_load_dwordx2 v[212:213], v[138:139], off offset:64
	global_load_dwordx2 v[214:215], v[138:139], off offset:96
	v_lshl_add_u64 v[138:139], v[138:139], 0, s[4:5]
	s_nop 7
	s_waitcnt vmcnt(31)
	v_lshlrev_b32_e32 v216, 16, v146
	v_and_b32_e32 v146, 0xffff0000, v146
	v_lshlrev_b32_e32 v217, 16, v147
	v_and_b32_e32 v147, 0xffff0000, v147
	v_fmac_f32_e32 v126, s40, v216
	v_fmac_f32_e32 v127, s40, v146
	v_fmac_f32_e32 v128, s40, v217
	v_fmac_f32_e32 v129, s40, v147
	global_store_dwordx4 v[140:141], v[126:129], off offset:0
	s_waitcnt vmcnt(31)
	v_lshlrev_b32_e32 v216, 16, v148
	v_and_b32_e32 v148, 0xffff0000, v148
	v_lshlrev_b32_e32 v217, 16, v149
	v_and_b32_e32 v149, 0xffff0000, v149
	v_fmac_f32_e32 v94, s40, v216
	v_fmac_f32_e32 v95, s40, v148
	v_fmac_f32_e32 v96, s40, v217
	v_fmac_f32_e32 v97, s40, v149
	global_store_dwordx4 v[140:141], v[94:97], off offset:64
	s_waitcnt vmcnt(31)
	v_lshlrev_b32_e32 v216, 16, v152
	v_and_b32_e32 v152, 0xffff0000, v152
	v_lshlrev_b32_e32 v217, 16, v153
	v_and_b32_e32 v153, 0xffff0000, v153
	v_fmac_f32_e32 v62, s40, v216
	v_fmac_f32_e32 v63, s40, v152
	v_fmac_f32_e32 v64, s40, v217
	v_fmac_f32_e32 v65, s40, v153
	global_store_dwordx4 v[140:141], v[62:65], off offset:128
	s_waitcnt vmcnt(31)
	v_lshlrev_b32_e32 v216, 16, v154
	v_and_b32_e32 v154, 0xffff0000, v154
	v_lshlrev_b32_e32 v217, 16, v155
	v_and_b32_e32 v155, 0xffff0000, v155
	v_fmac_f32_e32 v30, s40, v216
	v_fmac_f32_e32 v31, s40, v154
	v_fmac_f32_e32 v32, s40, v217
	v_fmac_f32_e32 v33, s40, v155
	global_store_dwordx4 v[140:141], v[30:33], off offset:192
	v_lshl_add_u64 v[140:141], v[140:141], 0, s[8:9]
	s_waitcnt vmcnt(31)
	v_lshlrev_b32_e32 v216, 16, v156
	v_and_b32_e32 v156, 0xffff0000, v156
	v_lshlrev_b32_e32 v217, 16, v157
	v_and_b32_e32 v157, 0xffff0000, v157
	v_fmac_f32_e32 v122, s40, v216
	v_fmac_f32_e32 v123, s40, v156
	v_fmac_f32_e32 v124, s40, v217
	v_fmac_f32_e32 v125, s40, v157
	global_store_dwordx4 v[140:141], v[122:125], off offset:0
	s_waitcnt vmcnt(31)
	v_lshlrev_b32_e32 v216, 16, v158
	v_and_b32_e32 v158, 0xffff0000, v158
	v_lshlrev_b32_e32 v217, 16, v159
	v_and_b32_e32 v159, 0xffff0000, v159
	v_fmac_f32_e32 v90, s40, v216
	v_fmac_f32_e32 v91, s40, v158
	v_fmac_f32_e32 v92, s40, v217
	v_fmac_f32_e32 v93, s40, v159
	global_store_dwordx4 v[140:141], v[90:93], off offset:64
	s_waitcnt vmcnt(31)
	v_lshlrev_b32_e32 v216, 16, v162
	v_and_b32_e32 v162, 0xffff0000, v162
	v_lshlrev_b32_e32 v217, 16, v163
	v_and_b32_e32 v163, 0xffff0000, v163
	v_fmac_f32_e32 v58, s40, v216
	v_fmac_f32_e32 v59, s40, v162
	v_fmac_f32_e32 v60, s40, v217
	v_fmac_f32_e32 v61, s40, v163
	global_store_dwordx4 v[140:141], v[58:61], off offset:128
	s_waitcnt vmcnt(31)
	v_lshlrev_b32_e32 v216, 16, v164
	v_and_b32_e32 v164, 0xffff0000, v164
	v_lshlrev_b32_e32 v217, 16, v165
	v_and_b32_e32 v165, 0xffff0000, v165
	v_fmac_f32_e32 v26, s40, v216
	v_fmac_f32_e32 v27, s40, v164
	v_fmac_f32_e32 v28, s40, v217
	v_fmac_f32_e32 v29, s40, v165
	global_store_dwordx4 v[140:141], v[26:29], off offset:192
	v_lshl_add_u64 v[140:141], v[140:141], 0, s[8:9]
	s_waitcnt vmcnt(31)
	v_lshlrev_b32_e32 v216, 16, v166
	v_and_b32_e32 v166, 0xffff0000, v166
	v_lshlrev_b32_e32 v217, 16, v167
	v_and_b32_e32 v167, 0xffff0000, v167
	v_fmac_f32_e32 v118, s40, v216
	v_fmac_f32_e32 v119, s40, v166
	v_fmac_f32_e32 v120, s40, v217
	v_fmac_f32_e32 v121, s40, v167
	global_store_dwordx4 v[140:141], v[118:121], off offset:0
	s_waitcnt vmcnt(31)
; DEVI float blo(unsigned u) { return __uint_as_float(u << 16); }
; DEVI float bhi(unsigned u) { return __uint_as_float(u & 0xffff0000u); }
;     ...
;         if (EPI == EPI_RESID || EPI == EPI_RESID_ATOMIC) {
;           f32x4 x = a;
;           if (EPI == EPI_RESID || kpart == 0) {
;             const u32x2 xr = *(const u32x2*)((const u16*)(p.ws + WS_XB) + (size_t)row * 1024 + col);
;             x[0] += ALPHA * blo(xr[0]); x[1] += ALPHA * bhi(xr[0]); x[2] += ALPHA * blo(xr[1]); x[3] += ALPHA * bhi(xr[1]);
;           }
;           if (EPI == EPI_RESID) *(f32x4*)((float*)(p.ws + WS_XF) + (size_t)row * 1024 + col) = x;
;           else *(f32x4*)((float*)(p.ws + WS_SLAB) + ((size_t)kpart * 512 + (row - T_P)) * 1024 + col) = x;
	v_lshlrev_b32_e32 v216, 16, v168
	v_and_b32_e32 v168, 0xffff0000, v168
	v_lshlrev_b32_e32 v217, 16, v169
	v_and_b32_e32 v169, 0xffff0000, v169
	v_fmac_f32_e32 v86, s40, v216
	v_fmac_f32_e32 v87, s40, v168
	v_fmac_f32_e32 v88, s40, v217
	v_fmac_f32_e32 v89, s40, v169
	global_store_dwordx4 v[140:141], v[86:89], off offset:64
	s_waitcnt vmcnt(31)
	v_lshlrev_b32_e32 v216, 16, v170
	v_and_b32_e32 v170, 0xffff0000, v170
	v_lshlrev_b32_e32 v217, 16, v171
	v_and_b32_e32 v171, 0xffff0000, v171
	v_fmac_f32_e32 v54, s40, v216
	v_fmac_f32_e32 v55, s40, v170
	v_fmac_f32_e32 v56, s40, v217
	v_fmac_f32_e32 v57, s40, v171
	global_store_dwordx4 v[140:141], v[54:57], off offset:128
	s_waitcnt vmcnt(31)
	v_lshlrev_b32_e32 v216, 16, v172
	v_and_b32_e32 v172, 0xffff0000, v172
	v_lshlrev_b32_e32 v217, 16, v173
	v_and_b32_e32 v173, 0xffff0000, v173
	v_fmac_f32_e32 v22, s40, v216
	v_fmac_f32_e32 v23, s40, v172
	v_fmac_f32_e32 v24, s40, v217
	v_fmac_f32_e32 v25, s40, v173
	global_store_dwordx4 v[140:141], v[22:25], off offset:192
	v_lshl_add_u64 v[140:141], v[140:141], 0, s[8:9]
	s_waitcnt vmcnt(31)
	v_lshlrev_b32_e32 v216, 16, v176
	v_and_b32_e32 v176, 0xffff0000, v176
	v_lshlrev_b32_e32 v217, 16, v177
	v_and_b32_e32 v177, 0xffff0000, v177
	v_fmac_f32_e32 v114, s40, v216
	v_fmac_f32_e32 v115, s40, v176
	v_fmac_f32_e32 v116, s40, v217
	v_fmac_f32_e32 v117, s40, v177
	global_store_dwordx4 v[140:141], v[114:117], off offset:0
	s_waitcnt vmcnt(31)
	v_lshlrev_b32_e32 v216, 16, v178
	v_and_b32_e32 v178, 0xffff0000, v178
	v_lshlrev_b32_e32 v217, 16, v179
	v_and_b32_e32 v179, 0xffff0000, v179
	v_fmac_f32_e32 v82, s40, v216
	v_fmac_f32_e32 v83, s40, v178
	v_fmac_f32_e32 v84, s40, v217
	v_fmac_f32_e32 v85, s40, v179
	global_store_dwordx4 v[140:141], v[82:85], off offset:64
	s_waitcnt vmcnt(31)
	v_lshlrev_b32_e32 v216, 16, v180
	v_and_b32_e32 v180, 0xffff0000, v180
	v_lshlrev_b32_e32 v217, 16, v181
	v_and_b32_e32 v181, 0xffff0000, v181
	v_fmac_f32_e32 v50, s40, v216
	v_fmac_f32_e32 v51, s40, v180
	v_fmac_f32_e32 v52, s40, v217
	v_fmac_f32_e32 v53, s40, v181
	global_store_dwordx4 v[140:141], v[50:53], off offset:128
	s_waitcnt vmcnt(31)
	v_lshlrev_b32_e32 v216, 16, v182
	v_and_b32_e32 v182, 0xffff0000, v182
	v_lshlrev_b32_e32 v217, 16, v183
	v_and_b32_e32 v183, 0xffff0000, v183
	v_fmac_f32_e32 v18, s40, v216
	v_fmac_f32_e32 v19, s40, v182
	v_fmac_f32_e32 v20, s40, v217
	v_fmac_f32_e32 v21, s40, v183
	global_store_dwordx4 v[140:141], v[18:21], off offset:192
	v_lshl_add_u64 v[140:141], v[140:141], 0, s[8:9]
	s_waitcnt vmcnt(31)
	v_lshlrev_b32_e32 v216, 16, v184
	v_and_b32_e32 v184, 0xffff0000, v184
	v_lshlrev_b32_e32 v217, 16, v185
	v_and_b32_e32 v185, 0xffff0000, v185
	v_fmac_f32_e32 v110, s40, v216
	v_fmac_f32_e32 v111, s40, v184
	v_fmac_f32_e32 v112, s40, v217
	v_fmac_f32_e32 v113, s40, v185
	global_store_dwordx4 v[140:141], v[110:113], off offset:0
	s_waitcnt vmcnt(31)
	v_lshlrev_b32_e32 v216, 16, v186
	v_and_b32_e32 v186, 0xffff0000, v186
	v_lshlrev_b32_e32 v217, 16, v187
	v_and_b32_e32 v187, 0xffff0000, v187
	v_fmac_f32_e32 v78, s40, v216
	v_fmac_f32_e32 v79, s40, v186
	v_fmac_f32_e32 v80, s40, v217
	v_fmac_f32_e32 v81, s40, v187
	global_store_dwordx4 v[140:141], v[78:81], off offset:64
	s_waitcnt vmcnt(31)
	v_lshlrev_b32_e32 v216, 16, v188
	v_and_b32_e32 v188, 0xffff0000, v188
	v_lshlrev_b32_e32 v217, 16, v189
	v_and_b32_e32 v189, 0xffff0000, v189
	v_fmac_f32_e32 v46, s40, v216
	v_fmac_f32_e32 v47, s40, v188
	v_fmac_f32_e32 v48, s40, v217
	v_fmac_f32_e32 v49, s40, v189
	global_store_dwordx4 v[140:141], v[46:49], off offset:128
	s_waitcnt vmcnt(31)
	v_lshlrev_b32_e32 v216, 16, v190
	v_and_b32_e32 v190, 0xffff0000, v190
	v_lshlrev_b32_e32 v217, 16, v191
	v_and_b32_e32 v191, 0xffff0000, v191
	v_fmac_f32_e32 v14, s40, v216
	v_fmac_f32_e32 v15, s40, v190
	v_fmac_f32_e32 v16, s40, v217
	v_fmac_f32_e32 v17, s40, v191
	global_store_dwordx4 v[140:141], v[14:17], off offset:192
	v_lshl_add_u64 v[140:141], v[140:141], 0, s[8:9]
	s_waitcnt vmcnt(31)
	v_lshlrev_b32_e32 v216, 16, v192
	v_and_b32_e32 v192, 0xffff0000, v192
	v_lshlrev_b32_e32 v217, 16, v193
	v_and_b32_e32 v193, 0xffff0000, v193
	v_fmac_f32_e32 v106, s40, v216
	v_fmac_f32_e32 v107, s40, v192
	v_fmac_f32_e32 v108, s40, v217
	v_fmac_f32_e32 v109, s40, v193
	global_store_dwordx4 v[140:141], v[106:109], off offset:0
	s_waitcnt vmcnt(31)
	v_lshlrev_b32_e32 v216, 16, v194
	v_and_b32_e32 v194, 0xffff0000, v194
	v_lshlrev_b32_e32 v217, 16, v195
	v_and_b32_e32 v195, 0xffff0000, v195
	v_fmac_f32_e32 v74, s40, v216
	v_fmac_f32_e32 v75, s40, v194
	v_fmac_f32_e32 v76, s40, v217
	v_fmac_f32_e32 v77, s40, v195
	global_store_dwordx4 v[140:141], v[74:77], off offset:64
	s_waitcnt vmcnt(31)
	v_lshlrev_b32_e32 v216, 16, v196
	v_and_b32_e32 v196, 0xffff0000, v196
	v_lshlrev_b32_e32 v217, 16, v197
	v_and_b32_e32 v197, 0xffff0000, v197
	v_fmac_f32_e32 v42, s40, v216
	v_fmac_f32_e32 v43, s40, v196
	v_fmac_f32_e32 v44, s40, v217
	v_fmac_f32_e32 v45, s40, v197
	global_store_dwordx4 v[140:141], v[42:45], off offset:128
	s_waitcnt vmcnt(31)
	v_lshlrev_b32_e32 v216, 16, v198
	v_and_b32_e32 v198, 0xffff0000, v198
	v_lshlrev_b32_e32 v217, 16, v199
	v_and_b32_e32 v199, 0xffff0000, v199
	v_fmac_f32_e32 v10, s40, v216
	v_fmac_f32_e32 v11, s40, v198
	v_fmac_f32_e32 v12, s40, v217
	v_fmac_f32_e32 v13, s40, v199
	global_store_dwordx4 v[140:141], v[10:13], off offset:192
	v_lshl_add_u64 v[140:141], v[140:141], 0, s[8:9]
	s_waitcnt vmcnt(31)
	v_lshlrev_b32_e32 v216, 16, v200
	v_and_b32_e32 v200, 0xffff0000, v200
	v_lshlrev_b32_e32 v217, 16, v201
	v_and_b32_e32 v201, 0xffff0000, v201
	v_fmac_f32_e32 v102, s40, v216
	v_fmac_f32_e32 v103, s40, v200
	v_fmac_f32_e32 v104, s40, v217
	v_fmac_f32_e32 v105, s40, v201
	global_store_dwordx4 v[140:141], v[102:105], off offset:0
	s_waitcnt vmcnt(31)
; #define LAS __attribute__((address_space(3)))
; DEVI float blo(unsigned u) { return __uint_as_float(u << 16); }
; DEVI float bhi(unsigned u) { return __uint_as_float(u & 0xffff0000u); }
;     ...
;   const int nk = (nk_part < 0) ? (K >> 5) : nk_part;
;   const int lrow = tid >> 2, lpc = tid & 3;
;   const int lch = lpc ^ ((0x78 >> (((lrow >> 2) & 3) * 2)) & 3);
;   const u16* ga = A + (size_t)(m0 + lrow) * lda + kbeg + lch * 8;
;   const u16* gb = Bt + (size_t)(n0 + lrow) * K + kbeg + lch * 8;
;   const size_t ga1 = (size_t)64 * lda, gb1 = (size_t)64 * K;
;   const unsigned lds0 = (unsigned)(uintptr_t)(LAS char*)smem + (unsigned)__builtin_amdgcn_readfirstlane(wid) * 1024u;
;     ...
;   __syncthreads();
;   G2_STAGE(0); G2_STAGE(1);
;   const int fsw = (0x78 >> (((r16 >> 2) & 3) * 2)) & 3;
;   const int aoff = (wm * 128 + r16) * 64 + ((quad ^ fsw) << 4);
;   const int boff = 16384 + (wn * 64 + r16) * 64 + ((quad ^ fsw) << 4);
;     ...
;         if (EPI == EPI_RESID || EPI == EPI_RESID_ATOMIC) {
;           f32x4 x = a;
;           if (EPI == EPI_RESID || kpart == 0) {
;             const u32x2 xr = *(const u32x2*)((const u16*)(p.ws + WS_XB) + (size_t)row * 1024 + col);
;             x[0] += ALPHA * blo(xr[0]); x[1] += ALPHA * bhi(xr[0]); x[2] += ALPHA * blo(xr[1]); x[3] += ALPHA * bhi(xr[1]);
;           }
;           if (EPI == EPI_RESID) *(f32x4*)((float*)(p.ws + WS_XF) + (size_t)row * 1024 + col) = x;
;           else *(f32x4*)((float*)(p.ws + WS_SLAB) + ((size_t)kpart * 512 + (row - T_P)) * 1024 + col) = x;
	v_lshlrev_b32_e32 v216, 16, v202
	v_and_b32_e32 v202, 0xffff0000, v202
	v_lshlrev_b32_e32 v217, 16, v203
	v_and_b32_e32 v203, 0xffff0000, v203
	v_fmac_f32_e32 v70, s40, v216
	v_fmac_f32_e32 v71, s40, v202
	v_fmac_f32_e32 v72, s40, v217
	v_fmac_f32_e32 v73, s40, v203
	global_store_dwordx4 v[140:141], v[70:73], off offset:64
	s_waitcnt vmcnt(31)
	v_lshlrev_b32_e32 v216, 16, v204
	v_and_b32_e32 v204, 0xffff0000, v204
	v_lshlrev_b32_e32 v217, 16, v205
	v_and_b32_e32 v205, 0xffff0000, v205
	v_fmac_f32_e32 v38, s40, v216
	v_fmac_f32_e32 v39, s40, v204
	v_fmac_f32_e32 v40, s40, v217
	v_fmac_f32_e32 v41, s40, v205
	global_store_dwordx4 v[140:141], v[38:41], off offset:128
	s_waitcnt vmcnt(31)
	v_lshlrev_b32_e32 v216, 16, v206
	v_and_b32_e32 v206, 0xffff0000, v206
	v_lshlrev_b32_e32 v217, 16, v207
	v_and_b32_e32 v207, 0xffff0000, v207
	v_fmac_f32_e32 v6, s40, v216
	v_fmac_f32_e32 v7, s40, v206
	v_fmac_f32_e32 v8, s40, v217
	v_fmac_f32_e32 v9, s40, v207
	global_store_dwordx4 v[140:141], v[6:9], off offset:192
	v_lshl_add_u64 v[140:141], v[140:141], 0, s[8:9]
	s_waitcnt vmcnt(31)
	v_lshlrev_b32_e32 v216, 16, v208
	v_and_b32_e32 v208, 0xffff0000, v208
	v_lshlrev_b32_e32 v217, 16, v209
	v_and_b32_e32 v209, 0xffff0000, v209
	v_fmac_f32_e32 v98, s40, v216
	v_fmac_f32_e32 v99, s40, v208
	v_fmac_f32_e32 v100, s40, v217
	v_fmac_f32_e32 v101, s40, v209
	global_store_dwordx4 v[140:141], v[98:101], off offset:0
	s_waitcnt vmcnt(31)
	v_lshlrev_b32_e32 v216, 16, v210
	v_and_b32_e32 v210, 0xffff0000, v210
	v_lshlrev_b32_e32 v217, 16, v211
	v_and_b32_e32 v211, 0xffff0000, v211
	v_fmac_f32_e32 v66, s40, v216
	v_fmac_f32_e32 v67, s40, v210
	v_fmac_f32_e32 v68, s40, v217
	v_fmac_f32_e32 v69, s40, v211
	global_store_dwordx4 v[140:141], v[66:69], off offset:64
	s_waitcnt vmcnt(31)
	v_lshlrev_b32_e32 v216, 16, v212
	v_and_b32_e32 v212, 0xffff0000, v212
	v_lshlrev_b32_e32 v217, 16, v213
	v_and_b32_e32 v213, 0xffff0000, v213
	v_fmac_f32_e32 v34, s40, v216
	v_fmac_f32_e32 v35, s40, v212
	v_fmac_f32_e32 v36, s40, v217
	v_fmac_f32_e32 v37, s40, v213
	global_store_dwordx4 v[140:141], v[34:37], off offset:128
	s_waitcnt vmcnt(31)
	v_lshlrev_b32_e32 v216, 16, v214
	v_and_b32_e32 v214, 0xffff0000, v214
	v_lshlrev_b32_e32 v217, 16, v215
	v_and_b32_e32 v215, 0xffff0000, v215
	v_fmac_f32_e32 v2, s40, v216
	v_fmac_f32_e32 v3, s40, v214
	v_fmac_f32_e32 v4, s40, v217
	v_fmac_f32_e32 v5, s40, v215
	global_store_dwordx4 v[140:141], v[2:5], off offset:192
	s_branch .LBB0_146
.LBB0_208:
	s_and_b64 vcc, exec, s[2:3]
	s_cbranch_vccz .LBB0_146
	s_lshr_b32 s45, s38, 6
	s_and_b32 s46, s38, 63
	s_lshr_b32 s42, s46, 3
	s_and_b32 s46, s46, 7
	s_lshl_b32 s45, s45, 3
	s_add_i32 s45, s45, s46
	v_readlane_b32 s2, v250, 5
	v_readlane_b32 s3, v250, 6
	v_readlane_b32 s46, v254, 62
	s_mul_i32 s40, s45, 0x20000
	s_add_u32 s4, s2, s40
	s_addc_u32 s5, s3, 0
	s_add_u32 s4, s4, 0xe700000
	s_addc_u32 s5, s5, 0
	s_mul_i32 s40, s46, 0x80000
	s_mul_i32 s41, s42, 0x10000
	s_add_i32 s40, s40, s41
	s_add_u32 s10, s2, s40
	s_addc_u32 s11, s3, 0
	s_add_u32 s10, s10, 0x16c00000
	s_addc_u32 s11, s11, 0
	s_movk_i32 s39, 0x78
	v_lshrrev_b32_e32 v0, 2, v145
	v_and_b32_e32 v131, 3, v145
	v_bfe_u32 v136, v145, 4, 2
	v_lshlrev_b32_e32 v136, 1, v136
	v_lshrrev_b32_e64 v136, v136, s39
	v_and_b32_e32 v136, 3, v136
	v_xor_b32_e32 v131, v131, v136
	v_lshlrev_b32_e32 v131, 4, v131
	s_movk_i32 s41, 0x200
	v_mad_u32_u24 v0, v0, s41, v131
	v_bfe_u32 v137, v145, 2, 1
	s_movk_i32 s41, 0x1c0
	v_mul_u32_u24_e32 v136, s41, v137
	v_sub_u32_e32 v136, v0, v136
	v_mov_b32_e32 v137, 0
	v_lshl_add_u64 v[134:135], s[10:11], 0, v[136:137]
	v_bfe_u32 v137, v145, 2, 1
	s_mov_b32 s12, 64
	s_mov_b32 s13, 0
	v_lshl_add_u64 v[132:133], s[4:5], 0, v[0:1]
	v_bfe_u32 v136, v145, 2, 2
	v_lshlrev_b32_e32 v136, 1, v136
	v_lshrrev_b32_e64 v136, v136, s39
	v_and_b32_e32 v136, 3, v136
	v_bfe_u32 v137, v145, 4, 2
	v_xor_b32_e32 v136, v136, v137
	v_lshlrev_b32_e32 v136, 4, v136
	v_and_b32_e32 v131, 15, v145
	v_lshl_or_b32 v136, v131, 6, v136
	v_bfe_u32 v137, v145, 6, 1
	v_lshl_or_b32 v137, v137, 12, v136
	v_lshrrev_b32_e32 v0, 7, v145
	v_lshl_or_b32 v136, v0, 13, v136
	v_and_b32_e32 v140, 1, v131
	v_lshl_or_b32 v131, v0, 7, v131
	v_bfe_u32 v0, v145, 4, 2
	v_lshlrev_b32_e32 v0, 3, v0
	v_bfe_u32 v141, v145, 6, 1
	s_lshl_b32 s40, s45, 19
	s_lshl_b32 s41, s42, 8
	s_add_i32 s40, s40, s41
	s_add_u32 s4, s2, s40
	s_addc_u32 s5, s3, 0
	s_add_u32 s4, s4, 0x4200000
	s_addc_u32 s5, s5, 0
	v_lshlrev_b32_e32 v138, 11, v131
	v_lshl_add_u32 v138, v141, 7, v138
	v_add_u32_e32 v138, v138, v0
	v_mov_b32_e32 v139, 0
	v_lshl_add_u64 v[138:139], s[4:5], 0, v[138:139]
	s_lshl_b32 s40, s45, 20
	s_lshl_b32 s41, s42, 9
	s_add_i32 s40, s40, s41
	s_add_u32 s10, s2, s40
	s_addc_u32 s11, s3, 0
	v_lshlrev_b32_e32 v140, 12, v131
	v_lshl_add_u32 v140, v141, 8, v140
	v_lshl_add_u32 v140, v0, 1, v140
	v_mov_b32_e32 v141, 0
	v_lshl_add_u64 v[140:141], s[10:11], 0, v[140:141]
	s_mov_b32 s2, 0x8000
	s_mov_b32 s3, 0
	v_lshrrev_b32_e32 v0, 6, v145
	v_lshlrev_b32_e32 v0, 10, v0
	s_nop 0
	v_readfirstlane_b32 s46, v0
	s_mov_b32 s43, m0
	s_mov_b32 s4, 128
	s_mov_b32 s5, 0
	v_mov_b32_e32 v2, 0
	v_mov_b32_e32 v3, 0
	v_mov_b32_e32 v4, 0
	v_mov_b32_e32 v5, 0
	v_mov_b32_e32 v6, 0
	v_mov_b32_e32 v7, 0
	v_mov_b32_e32 v8, 0
	v_mov_b32_e32 v9, 0
	v_mov_b32_e32 v10, 0
	v_mov_b32_e32 v11, 0
	v_mov_b32_e32 v12, 0
	v_mov_b32_e32 v13, 0
	v_mov_b32_e32 v14, 0
	v_mov_b32_e32 v15, 0
	v_mov_b32_e32 v16, 0
	v_mov_b32_e32 v17, 0
	v_mov_b32_e32 v18, 0
	v_mov_b32_e32 v19, 0
	v_mov_b32_e32 v20, 0
	v_mov_b32_e32 v21, 0
	v_mov_b32_e32 v22, 0
	v_mov_b32_e32 v23, 0
	v_mov_b32_e32 v24, 0
	v_mov_b32_e32 v25, 0
	v_mov_b32_e32 v26, 0
; #define LAS __attribute__((address_space(3)))
;     ...
;   f32x4 acc[4][8];
; #pragma unroll
;   for (int i = 0; i < 4; i++)
; #pragma unroll
;     for (int j = 0; j < 8; j++) acc[i][j] = (f32x4){0.f, 0.f, 0.f, 0.f};
;   const int nk = (nk_part < 0) ? (K >> 5) : nk_part;
;   const int lrow = tid >> 2, lpc = tid & 3;
;   const int lch = lpc ^ ((0x78 >> (((lrow >> 2) & 3) * 2)) & 3);
;   const u16* ga = A + (size_t)(m0 + lrow) * lda + kbeg + lch * 8;
;   const u16* gb = Bt + (size_t)(n0 + lrow) * K + kbeg + lch * 8;
;   const size_t ga1 = (size_t)64 * lda, gb1 = (size_t)64 * K;
;   const unsigned lds0 = (unsigned)(uintptr_t)(LAS char*)smem + (unsigned)__builtin_amdgcn_readfirstlane(wid) * 1024u;
;     ...
;   __syncthreads();
;   G2_STAGE(0); G2_STAGE(1);
	v_mov_b32_e32 v27, 0
	v_mov_b32_e32 v28, 0
	v_mov_b32_e32 v29, 0
	v_mov_b32_e32 v30, 0
	v_mov_b32_e32 v31, 0
	v_mov_b32_e32 v32, 0
	v_mov_b32_e32 v33, 0
	v_mov_b32_e32 v34, 0
	v_mov_b32_e32 v35, 0
	v_mov_b32_e32 v36, 0
	v_mov_b32_e32 v37, 0
	v_mov_b32_e32 v38, 0
	v_mov_b32_e32 v39, 0
	v_mov_b32_e32 v40, 0
	v_mov_b32_e32 v41, 0
	v_mov_b32_e32 v42, 0
	v_mov_b32_e32 v43, 0
	v_mov_b32_e32 v44, 0
	v_mov_b32_e32 v45, 0
	v_mov_b32_e32 v46, 0
	v_mov_b32_e32 v47, 0
	v_mov_b32_e32 v48, 0
	v_mov_b32_e32 v49, 0
	v_mov_b32_e32 v50, 0
	v_mov_b32_e32 v51, 0
	v_mov_b32_e32 v52, 0
	v_mov_b32_e32 v53, 0
	v_mov_b32_e32 v54, 0
	v_mov_b32_e32 v55, 0
	v_mov_b32_e32 v56, 0
	v_mov_b32_e32 v57, 0
	v_mov_b32_e32 v58, 0
	v_mov_b32_e32 v59, 0
	v_mov_b32_e32 v60, 0
	v_mov_b32_e32 v61, 0
	v_mov_b32_e32 v62, 0
	v_mov_b32_e32 v63, 0
	v_mov_b32_e32 v64, 0
	v_mov_b32_e32 v65, 0
	v_mov_b32_e32 v66, 0
	v_mov_b32_e32 v67, 0
	v_mov_b32_e32 v68, 0
	v_mov_b32_e32 v69, 0
	v_mov_b32_e32 v70, 0
	v_mov_b32_e32 v71, 0
	v_mov_b32_e32 v72, 0
	v_mov_b32_e32 v73, 0
	v_mov_b32_e32 v74, 0
	v_mov_b32_e32 v75, 0
	v_mov_b32_e32 v76, 0
	v_mov_b32_e32 v77, 0
	v_mov_b32_e32 v78, 0
	v_mov_b32_e32 v79, 0
	v_mov_b32_e32 v80, 0
	v_mov_b32_e32 v81, 0
	v_mov_b32_e32 v82, 0
	v_mov_b32_e32 v83, 0
	v_mov_b32_e32 v84, 0
	v_mov_b32_e32 v85, 0
	v_mov_b32_e32 v86, 0
	v_mov_b32_e32 v87, 0
	v_mov_b32_e32 v88, 0
	v_mov_b32_e32 v89, 0
	v_mov_b32_e32 v90, 0
	v_mov_b32_e32 v91, 0
	v_mov_b32_e32 v92, 0
	v_mov_b32_e32 v93, 0
	v_mov_b32_e32 v94, 0
	v_mov_b32_e32 v95, 0
	v_mov_b32_e32 v96, 0
	v_mov_b32_e32 v97, 0
	v_mov_b32_e32 v98, 0
	v_mov_b32_e32 v99, 0
	v_mov_b32_e32 v100, 0
	v_mov_b32_e32 v101, 0
	v_mov_b32_e32 v102, 0
	v_mov_b32_e32 v103, 0
	v_mov_b32_e32 v104, 0
	v_mov_b32_e32 v105, 0
	v_mov_b32_e32 v106, 0
	v_mov_b32_e32 v107, 0
	v_mov_b32_e32 v108, 0
	v_mov_b32_e32 v109, 0
	v_mov_b32_e32 v110, 0
	v_mov_b32_e32 v111, 0
	v_mov_b32_e32 v112, 0
	v_mov_b32_e32 v113, 0
	v_mov_b32_e32 v114, 0
	v_mov_b32_e32 v115, 0
	v_mov_b32_e32 v116, 0
	v_mov_b32_e32 v117, 0
	v_mov_b32_e32 v118, 0
	v_mov_b32_e32 v119, 0
	v_mov_b32_e32 v120, 0
	v_mov_b32_e32 v121, 0
	v_mov_b32_e32 v122, 0
	v_mov_b32_e32 v123, 0
	v_mov_b32_e32 v124, 0
	v_mov_b32_e32 v125, 0
	v_mov_b32_e32 v126, 0
	v_mov_b32_e32 v127, 0
	v_mov_b32_e32 v128, 0
	v_mov_b32_e32 v129, 0
	s_barrier
	s_add_i32 s42, s46, 0x0
	s_mov_b32 m0, s42
	v_lshl_add_u64 v[142:143], v[132:133], 0, s[2:3]
	global_load_lds_dwordx4 v[132:133], off
	s_addk_i32 m0, 0x1000
	s_nop 0
	global_load_lds_dwordx4 v[142:143], off
	v_lshl_add_u64 v[142:143], v[142:143], 0, s[2:3]
	s_addk_i32 m0, 0x1000
	s_nop 0
	global_load_lds_dwordx4 v[142:143], off
	v_lshl_add_u64 v[142:143], v[142:143], 0, s[2:3]
	s_addk_i32 m0, 0x1000
	s_nop 0
	global_load_lds_dwordx4 v[142:143], off
	s_addk_i32 m0, 0x1000
	v_lshl_add_u64 v[142:143], v[134:135], 0, s[2:3]
	s_nop 0
	global_load_lds_dwordx4 v[134:135], off
	s_addk_i32 m0, 0x1000
	v_lshl_add_u64 v[132:133], v[132:133], 0, s[12:13]
	s_nop 0
	global_load_lds_dwordx4 v[142:143], off
	v_lshl_add_u64 v[134:135], v[134:135], 0, s[4:5]
	s_nop 0
	s_add_i32 s42, s46, 0x6000
	s_mov_b32 m0, s42
	v_lshl_add_u64 v[142:143], v[132:133], 0, s[2:3]
	global_load_lds_dwordx4 v[132:133], off
	s_addk_i32 m0, 0x1000
	s_nop 0
	global_load_lds_dwordx4 v[142:143], off
	v_lshl_add_u64 v[142:143], v[142:143], 0, s[2:3]
	s_addk_i32 m0, 0x1000
	s_nop 0
	global_load_lds_dwordx4 v[142:143], off
	v_lshl_add_u64 v[142:143], v[142:143], 0, s[2:3]
	s_addk_i32 m0, 0x1000
	s_nop 0
	global_load_lds_dwordx4 v[142:143], off
	s_addk_i32 m0, 0x1000
	v_lshl_add_u64 v[142:143], v[134:135], 0, s[2:3]
	s_nop 0
	global_load_lds_dwordx4 v[134:135], off
	s_addk_i32 m0, 0x1000
	v_lshl_add_u64 v[132:133], v[132:133], 0, s[12:13]
	s_nop 0
	global_load_lds_dwordx4 v[142:143], off
	v_lshl_add_u64 v[134:135], v[134:135], 0, s[4:5]
	s_nop 0
	s_add_i32 s42, s46, 0xc000
	s_mov_b32 m0, s42
	v_lshl_add_u64 v[142:143], v[132:133], 0, s[2:3]
	global_load_lds_dwordx4 v[132:133], off
	s_addk_i32 m0, 0x1000
	s_nop 0
	global_load_lds_dwordx4 v[142:143], off
	v_lshl_add_u64 v[142:143], v[142:143], 0, s[2:3]
	s_addk_i32 m0, 0x1000
	s_nop 0
	global_load_lds_dwordx4 v[142:143], off
	v_lshl_add_u64 v[142:143], v[142:143], 0, s[2:3]
	s_addk_i32 m0, 0x1000
	s_nop 0
	global_load_lds_dwordx4 v[142:143], off
	s_addk_i32 m0, 0x1000
	v_lshl_add_u64 v[142:143], v[134:135], 0, s[2:3]
	s_nop 0
	global_load_lds_dwordx4 v[134:135], off
	s_addk_i32 m0, 0x1000
	v_lshl_add_u64 v[132:133], v[132:133], 0, s[12:13]
	s_nop 0
	global_load_lds_dwordx4 v[142:143], off
	v_lshl_add_u64 v[134:135], v[134:135], 0, s[4:5]
	s_nop 0
	s_waitcnt vmcnt(12)
	s_barrier
	ds_read_b128 v[146:149], v136 offset:0
	ds_read_b128 v[152:155], v136 offset:1024
	ds_read_b128 v[156:159], v136 offset:2048
	ds_read_b128 v[162:165], v136 offset:3072
	ds_read_b128 v[166:169], v136 offset:4096
	ds_read_b128 v[170:173], v136 offset:5120
	ds_read_b128 v[176:179], v136 offset:6144
	ds_read_b128 v[180:183], v136 offset:7168
	ds_read_b128 v[184:187], v137 offset:16384
	ds_read_b128 v[188:191], v137 offset:17408
	ds_read_b128 v[192:195], v137 offset:18432
	ds_read_b128 v[196:199], v137 offset:19456
	s_movk_i32 s40, 0x6000
	s_mov_b32 s41, 0
	s_movk_i32 s39, 2
;     ...
;   for (int kt = 0; kt < nk; kt++) {
;     if (kt + 1 < nk) asm volatile("s_waitcnt vmcnt(6)" ::: "memory");
;     else asm volatile("s_waitcnt vmcnt(0)" ::: "memory");
;     __builtin_amdgcn_s_barrier();
;     asm volatile("" ::: "memory");
;     if (kt + 2 < nk) G2_STAGE(kt + 2);
;     const char* cS = smem + (kt % 3) * 24576;
;     bf16x8 xa[8], wb[4];
; #pragma unroll
;     for (int f = 0; f < 8; f++) xa[f] = *(const bf16x8*)(cS + aoff + f * 1024);
; #pragma unroll
;     for (int f = 0; f < 4; f++) wb[f] = *(const bf16x8*)(cS + boff + f * 1024);
; #pragma unroll
;     for (int nf = 0; nf < 4; nf++)
; #pragma unroll
;       for (int mf = 0; mf < 8; mf++)
;         acc[nf][mf] = __builtin_amdgcn_mfma_f32_16x16x32_bf16(wb[nf], xa[mf], acc[nf][mf], 0, 0, 0);
;   }
.Lt8_loop:
	s_waitcnt vmcnt(6) lgkmcnt(0)
	s_barrier
	v_add_u32_e32 v144, s40, v136
	v_mfma_f32_16x16x32_bf16 v[126:129], v[184:187], v[146:149], v[126:129]
	ds_read_b128 v[200:203], v144 offset:0
	v_mfma_f32_16x16x32_bf16 v[122:125], v[184:187], v[152:155], v[122:125]
	ds_read_b128 v[204:207], v144 offset:1024
	v_mfma_f32_16x16x32_bf16 v[118:121], v[184:187], v[156:159], v[118:121]
	ds_read_b128 v[208:211], v144 offset:2048
	v_mfma_f32_16x16x32_bf16 v[114:117], v[184:187], v[162:165], v[114:117]
	ds_read_b128 v[212:215], v144 offset:3072
	v_mfma_f32_16x16x32_bf16 v[110:113], v[184:187], v[166:169], v[110:113]
	ds_read_b128 v[216:219], v144 offset:4096
	v_mfma_f32_16x16x32_bf16 v[106:109], v[184:187], v[170:173], v[106:109]
	ds_read_b128 v[220:223], v144 offset:5120
	v_mfma_f32_16x16x32_bf16 v[102:105], v[184:187], v[176:179], v[102:105]
	ds_read_b128 v[224:227], v144 offset:6144
	v_mfma_f32_16x16x32_bf16 v[98:101], v[184:187], v[180:183], v[98:101]
	ds_read_b128 v[228:231], v144 offset:7168
	v_mfma_f32_16x16x32_bf16 v[94:97], v[188:191], v[146:149], v[94:97]
	v_add_u32_e32 v144, s40, v137
	v_mfma_f32_16x16x32_bf16 v[90:93], v[188:191], v[152:155], v[90:93]
	v_mfma_f32_16x16x32_bf16 v[86:89], v[188:191], v[156:159], v[86:89]
	ds_read_b128 v[232:235], v144 offset:16384
	v_mfma_f32_16x16x32_bf16 v[82:85], v[188:191], v[162:165], v[82:85]
	ds_read_b128 v[236:239], v144 offset:17408
	v_mfma_f32_16x16x32_bf16 v[78:81], v[188:191], v[166:169], v[78:81]
	ds_read_b128 v[240:243], v144 offset:18432
	v_mfma_f32_16x16x32_bf16 v[74:77], v[188:191], v[170:173], v[74:77]
	ds_read_b128 v[244:247], v144 offset:19456
	s_add_i32 s42, s46, s41
	v_mfma_f32_16x16x32_bf16 v[70:73], v[188:191], v[176:179], v[70:73]
	s_mov_b32 m0, s42
	v_lshl_add_u64 v[142:143], v[132:133], 0, s[2:3]
	v_mfma_f32_16x16x32_bf16 v[66:69], v[188:191], v[180:183], v[66:69]
	global_load_lds_dwordx4 v[132:133], off
	s_addk_i32 m0, 0x1000
	v_mfma_f32_16x16x32_bf16 v[62:65], v[192:195], v[146:149], v[62:65]
	v_mfma_f32_16x16x32_bf16 v[58:61], v[192:195], v[152:155], v[58:61]
	v_mfma_f32_16x16x32_bf16 v[54:57], v[192:195], v[156:159], v[54:57]
	global_load_lds_dwordx4 v[142:143], off
	v_lshl_add_u64 v[142:143], v[142:143], 0, s[2:3]
	s_addk_i32 m0, 0x1000
	v_mfma_f32_16x16x32_bf16 v[50:53], v[192:195], v[162:165], v[50:53]
	v_mfma_f32_16x16x32_bf16 v[46:49], v[192:195], v[166:169], v[46:49]
	v_mfma_f32_16x16x32_bf16 v[42:45], v[192:195], v[170:173], v[42:45]
	global_load_lds_dwordx4 v[142:143], off
	v_lshl_add_u64 v[142:143], v[142:143], 0, s[2:3]
	s_addk_i32 m0, 0x1000
	v_mfma_f32_16x16x32_bf16 v[38:41], v[192:195], v[176:179], v[38:41]
	v_mfma_f32_16x16x32_bf16 v[34:37], v[192:195], v[180:183], v[34:37]
	v_mfma_f32_16x16x32_bf16 v[30:33], v[196:199], v[146:149], v[30:33]
	global_load_lds_dwordx4 v[142:143], off
	s_addk_i32 m0, 0x1000
	v_lshl_add_u64 v[142:143], v[134:135], 0, s[2:3]
	v_mfma_f32_16x16x32_bf16 v[26:29], v[196:199], v[152:155], v[26:29]
	v_mfma_f32_16x16x32_bf16 v[22:25], v[196:199], v[156:159], v[22:25]
	v_mfma_f32_16x16x32_bf16 v[18:21], v[196:199], v[162:165], v[18:21]
	global_load_lds_dwordx4 v[134:135], off
	s_addk_i32 m0, 0x1000
	v_lshl_add_u64 v[132:133], v[132:133], 0, s[12:13]
	v_mfma_f32_16x16x32_bf16 v[14:17], v[196:199], v[166:169], v[14:17]
	v_mfma_f32_16x16x32_bf16 v[10:13], v[196:199], v[170:173], v[10:13]
	v_mfma_f32_16x16x32_bf16 v[6:9], v[196:199], v[176:179], v[6:9]
	global_load_lds_dwordx4 v[142:143], off
	v_lshl_add_u64 v[134:135], v[134:135], 0, s[4:5]
	v_mfma_f32_16x16x32_bf16 v[2:5], v[196:199], v[180:183], v[2:5]
	s_mov_b32 s41, s40
	s_add_i32 s40, s40, 0x6000
	s_cmp_eq_u32 s40, 0x12000
	s_cselect_b32 s40, 0, s40
	s_waitcnt vmcnt(6) lgkmcnt(0)
	s_barrier
	v_add_u32_e32 v144, s40, v136
	v_mfma_f32_16x16x32_bf16 v[126:129], v[232:235], v[200:203], v[126:129]
	ds_read_b128 v[146:149], v144 offset:0
	v_mfma_f32_16x16x32_bf16 v[122:125], v[232:235], v[204:207], v[122:125]
	ds_read_b128 v[152:155], v144 offset:1024
	v_mfma_f32_16x16x32_bf16 v[118:121], v[232:235], v[208:211], v[118:121]
	ds_read_b128 v[156:159], v144 offset:2048
	v_mfma_f32_16x16x32_bf16 v[114:117], v[232:235], v[212:215], v[114:117]
	ds_read_b128 v[162:165], v144 offset:3072
	v_mfma_f32_16x16x32_bf16 v[110:113], v[232:235], v[216:219], v[110:113]
	ds_read_b128 v[166:169], v144 offset:4096
	v_mfma_f32_16x16x32_bf16 v[106:109], v[232:235], v[220:223], v[106:109]
	ds_read_b128 v[170:173], v144 offset:5120
	v_mfma_f32_16x16x32_bf16 v[102:105], v[232:235], v[224:227], v[102:105]
	ds_read_b128 v[176:179], v144 offset:6144
	v_mfma_f32_16x16x32_bf16 v[98:101], v[232:235], v[228:231], v[98:101]
	ds_read_b128 v[180:183], v144 offset:7168
	v_mfma_f32_16x16x32_bf16 v[94:97], v[236:239], v[200:203], v[94:97]
	v_add_u32_e32 v144, s40, v137
	v_mfma_f32_16x16x32_bf16 v[90:93], v[236:239], v[204:207], v[90:93]
	v_mfma_f32_16x16x32_bf16 v[86:89], v[236:239], v[208:211], v[86:89]
	ds_read_b128 v[184:187], v144 offset:16384
	v_mfma_f32_16x16x32_bf16 v[82:85], v[236:239], v[212:215], v[82:85]
	ds_read_b128 v[188:191], v144 offset:17408
	v_mfma_f32_16x16x32_bf16 v[78:81], v[236:239], v[216:219], v[78:81]
	ds_read_b128 v[192:195], v144 offset:18432
	v_mfma_f32_16x16x32_bf16 v[74:77], v[236:239], v[220:223], v[74:77]
	ds_read_b128 v[196:199], v144 offset:19456
	s_add_i32 s42, s46, s41
	v_mfma_f32_16x16x32_bf16 v[70:73], v[236:239], v[224:227], v[70:73]
	s_mov_b32 m0, s42
	v_lshl_add_u64 v[142:143], v[132:133], 0, s[2:3]
	v_mfma_f32_16x16x32_bf16 v[66:69], v[236:239], v[228:231], v[66:69]
	global_load_lds_dwordx4 v[132:133], off
	s_addk_i32 m0, 0x1000
	v_mfma_f32_16x16x32_bf16 v[62:65], v[240:243], v[200:203], v[62:65]
;     ...
;   for (int kt = 0; kt < nk; kt++) {
;     if (kt + 1 < nk) asm volatile("s_waitcnt vmcnt(6)" ::: "memory");
;     else asm volatile("s_waitcnt vmcnt(0)" ::: "memory");
;     __builtin_amdgcn_s_barrier();
;     asm volatile("" ::: "memory");
;     if (kt + 2 < nk) G2_STAGE(kt + 2);
;     const char* cS = smem + (kt % 3) * 24576;
;     bf16x8 xa[8], wb[4];
; #pragma unroll
;     for (int f = 0; f < 8; f++) xa[f] = *(const bf16x8*)(cS + aoff + f * 1024);
; #pragma unroll
;     for (int f = 0; f < 4; f++) wb[f] = *(const bf16x8*)(cS + boff + f * 1024);
; #pragma unroll
;     for (int nf = 0; nf < 4; nf++)
; #pragma unroll
;       for (int mf = 0; mf < 8; mf++)
;         acc[nf][mf] = __builtin_amdgcn_mfma_f32_16x16x32_bf16(wb[nf], xa[mf], acc[nf][mf], 0, 0, 0);
;   }
	v_mfma_f32_16x16x32_bf16 v[58:61], v[240:243], v[204:207], v[58:61]
	v_mfma_f32_16x16x32_bf16 v[54:57], v[240:243], v[208:211], v[54:57]
	global_load_lds_dwordx4 v[142:143], off
	v_lshl_add_u64 v[142:143], v[142:143], 0, s[2:3]
	s_addk_i32 m0, 0x1000
	v_mfma_f32_16x16x32_bf16 v[50:53], v[240:243], v[212:215], v[50:53]
	v_mfma_f32_16x16x32_bf16 v[46:49], v[240:243], v[216:219], v[46:49]
	v_mfma_f32_16x16x32_bf16 v[42:45], v[240:243], v[220:223], v[42:45]
	global_load_lds_dwordx4 v[142:143], off
	v_lshl_add_u64 v[142:143], v[142:143], 0, s[2:3]
	s_addk_i32 m0, 0x1000
	v_mfma_f32_16x16x32_bf16 v[38:41], v[240:243], v[224:227], v[38:41]
	v_mfma_f32_16x16x32_bf16 v[34:37], v[240:243], v[228:231], v[34:37]
	v_mfma_f32_16x16x32_bf16 v[30:33], v[244:247], v[200:203], v[30:33]
	global_load_lds_dwordx4 v[142:143], off
	s_addk_i32 m0, 0x1000
	v_lshl_add_u64 v[142:143], v[134:135], 0, s[2:3]
	v_mfma_f32_16x16x32_bf16 v[26:29], v[244:247], v[204:207], v[26:29]
	v_mfma_f32_16x16x32_bf16 v[22:25], v[244:247], v[208:211], v[22:25]
	v_mfma_f32_16x16x32_bf16 v[18:21], v[244:247], v[212:215], v[18:21]
	global_load_lds_dwordx4 v[134:135], off
	s_addk_i32 m0, 0x1000
	v_lshl_add_u64 v[132:133], v[132:133], 0, s[12:13]
	v_mfma_f32_16x16x32_bf16 v[14:17], v[244:247], v[216:219], v[14:17]
	v_mfma_f32_16x16x32_bf16 v[10:13], v[244:247], v[220:223], v[10:13]
	v_mfma_f32_16x16x32_bf16 v[6:9], v[244:247], v[224:227], v[6:9]
	global_load_lds_dwordx4 v[142:143], off
	v_lshl_add_u64 v[134:135], v[134:135], 0, s[4:5]
	v_mfma_f32_16x16x32_bf16 v[2:5], v[244:247], v[228:231], v[2:5]
	s_mov_b32 s41, s40
	s_add_i32 s40, s40, 0x6000
	s_cmp_eq_u32 s40, 0x12000
	s_cselect_b32 s40, 0, s40
	s_sub_i32 s39, s39, 1
	s_cmp_lg_u32 s39, 0
	s_cbranch_scc1 .Lt8_loop
	s_waitcnt vmcnt(6) lgkmcnt(0)
	s_barrier
	v_add_u32_e32 v144, s40, v136
	v_mfma_f32_16x16x32_bf16 v[126:129], v[184:187], v[146:149], v[126:129]
	ds_read_b128 v[200:203], v144 offset:0
	v_mfma_f32_16x16x32_bf16 v[122:125], v[184:187], v[152:155], v[122:125]
	ds_read_b128 v[204:207], v144 offset:1024
	v_mfma_f32_16x16x32_bf16 v[118:121], v[184:187], v[156:159], v[118:121]
	ds_read_b128 v[208:211], v144 offset:2048
	v_mfma_f32_16x16x32_bf16 v[114:117], v[184:187], v[162:165], v[114:117]
	ds_read_b128 v[212:215], v144 offset:3072
	v_mfma_f32_16x16x32_bf16 v[110:113], v[184:187], v[166:169], v[110:113]
	ds_read_b128 v[216:219], v144 offset:4096
	v_mfma_f32_16x16x32_bf16 v[106:109], v[184:187], v[170:173], v[106:109]
	ds_read_b128 v[220:223], v144 offset:5120
	v_mfma_f32_16x16x32_bf16 v[102:105], v[184:187], v[176:179], v[102:105]
	ds_read_b128 v[224:227], v144 offset:6144
	v_mfma_f32_16x16x32_bf16 v[98:101], v[184:187], v[180:183], v[98:101]
	ds_read_b128 v[228:231], v144 offset:7168
	v_mfma_f32_16x16x32_bf16 v[94:97], v[188:191], v[146:149], v[94:97]
	v_add_u32_e32 v144, s40, v137
	v_mfma_f32_16x16x32_bf16 v[90:93], v[188:191], v[152:155], v[90:93]
	v_mfma_f32_16x16x32_bf16 v[86:89], v[188:191], v[156:159], v[86:89]
	ds_read_b128 v[232:235], v144 offset:16384
	v_mfma_f32_16x16x32_bf16 v[82:85], v[188:191], v[162:165], v[82:85]
	ds_read_b128 v[236:239], v144 offset:17408
	v_mfma_f32_16x16x32_bf16 v[78:81], v[188:191], v[166:169], v[78:81]
	ds_read_b128 v[240:243], v144 offset:18432
	v_mfma_f32_16x16x32_bf16 v[74:77], v[188:191], v[170:173], v[74:77]
	ds_read_b128 v[244:247], v144 offset:19456
	s_add_i32 s42, s46, s41
	v_mfma_f32_16x16x32_bf16 v[70:73], v[188:191], v[176:179], v[70:73]
	s_mov_b32 m0, s42
	v_lshl_add_u64 v[142:143], v[132:133], 0, s[2:3]
	v_mfma_f32_16x16x32_bf16 v[66:69], v[188:191], v[180:183], v[66:69]
	global_load_lds_dwordx4 v[132:133], off
	s_addk_i32 m0, 0x1000
	v_mfma_f32_16x16x32_bf16 v[62:65], v[192:195], v[146:149], v[62:65]
	v_mfma_f32_16x16x32_bf16 v[58:61], v[192:195], v[152:155], v[58:61]
	v_mfma_f32_16x16x32_bf16 v[54:57], v[192:195], v[156:159], v[54:57]
	global_load_lds_dwordx4 v[142:143], off
	v_lshl_add_u64 v[142:143], v[142:143], 0, s[2:3]
	s_addk_i32 m0, 0x1000
	v_mfma_f32_16x16x32_bf16 v[50:53], v[192:195], v[162:165], v[50:53]
	v_mfma_f32_16x16x32_bf16 v[46:49], v[192:195], v[166:169], v[46:49]
	v_mfma_f32_16x16x32_bf16 v[42:45], v[192:195], v[170:173], v[42:45]
	global_load_lds_dwordx4 v[142:143], off
	v_lshl_add_u64 v[142:143], v[142:143], 0, s[2:3]
	s_addk_i32 m0, 0x1000
	v_mfma_f32_16x16x32_bf16 v[38:41], v[192:195], v[176:179], v[38:41]
	v_mfma_f32_16x16x32_bf16 v[34:37], v[192:195], v[180:183], v[34:37]
	v_mfma_f32_16x16x32_bf16 v[30:33], v[196:199], v[146:149], v[30:33]
	global_load_lds_dwordx4 v[142:143], off
	s_addk_i32 m0, 0x1000
	v_lshl_add_u64 v[142:143], v[134:135], 0, s[2:3]
	v_mfma_f32_16x16x32_bf16 v[26:29], v[196:199], v[152:155], v[26:29]
	v_mfma_f32_16x16x32_bf16 v[22:25], v[196:199], v[156:159], v[22:25]
	v_mfma_f32_16x16x32_bf16 v[18:21], v[196:199], v[162:165], v[18:21]
	global_load_lds_dwordx4 v[134:135], off
	s_addk_i32 m0, 0x1000
	v_lshl_add_u64 v[132:133], v[132:133], 0, s[12:13]
	v_mfma_f32_16x16x32_bf16 v[14:17], v[196:199], v[166:169], v[14:17]
	v_mfma_f32_16x16x32_bf16 v[10:13], v[196:199], v[170:173], v[10:13]
	v_mfma_f32_16x16x32_bf16 v[6:9], v[196:199], v[176:179], v[6:9]
	global_load_lds_dwordx4 v[142:143], off
	v_lshl_add_u64 v[134:135], v[134:135], 0, s[4:5]
	v_mfma_f32_16x16x32_bf16 v[2:5], v[196:199], v[180:183], v[2:5]
	s_mov_b32 s41, s40
	s_add_i32 s40, s40, 0x6000
	s_cmp_eq_u32 s40, 0x12000
	s_cselect_b32 s40, 0, s40
	s_waitcnt vmcnt(6) lgkmcnt(0)
	s_barrier
;     ...
;   for (int kt = 0; kt < nk; kt++) {
;     if (kt + 1 < nk) asm volatile("s_waitcnt vmcnt(6)" ::: "memory");
;     else asm volatile("s_waitcnt vmcnt(0)" ::: "memory");
;     __builtin_amdgcn_s_barrier();
;     asm volatile("" ::: "memory");
;     if (kt + 2 < nk) G2_STAGE(kt + 2);
;     const char* cS = smem + (kt % 3) * 24576;
;     bf16x8 xa[8], wb[4];
; #pragma unroll
;     for (int f = 0; f < 8; f++) xa[f] = *(const bf16x8*)(cS + aoff + f * 1024);
; #pragma unroll
;     for (int f = 0; f < 4; f++) wb[f] = *(const bf16x8*)(cS + boff + f * 1024);
; #pragma unroll
;     for (int nf = 0; nf < 4; nf++)
; #pragma unroll
;       for (int mf = 0; mf < 8; mf++)
;         acc[nf][mf] = __builtin_amdgcn_mfma_f32_16x16x32_bf16(wb[nf], xa[mf], acc[nf][mf], 0, 0, 0);
;   }
	v_add_u32_e32 v144, s40, v136
	v_mfma_f32_16x16x32_bf16 v[126:129], v[232:235], v[200:203], v[126:129]
	ds_read_b128 v[146:149], v144 offset:0
	v_mfma_f32_16x16x32_bf16 v[122:125], v[232:235], v[204:207], v[122:125]
	ds_read_b128 v[152:155], v144 offset:1024
	v_mfma_f32_16x16x32_bf16 v[118:121], v[232:235], v[208:211], v[118:121]
	ds_read_b128 v[156:159], v144 offset:2048
	v_mfma_f32_16x16x32_bf16 v[114:117], v[232:235], v[212:215], v[114:117]
	ds_read_b128 v[162:165], v144 offset:3072
	v_mfma_f32_16x16x32_bf16 v[110:113], v[232:235], v[216:219], v[110:113]
	ds_read_b128 v[166:169], v144 offset:4096
	v_mfma_f32_16x16x32_bf16 v[106:109], v[232:235], v[220:223], v[106:109]
	ds_read_b128 v[170:173], v144 offset:5120
	v_mfma_f32_16x16x32_bf16 v[102:105], v[232:235], v[224:227], v[102:105]
	ds_read_b128 v[176:179], v144 offset:6144
	v_mfma_f32_16x16x32_bf16 v[98:101], v[232:235], v[228:231], v[98:101]
	ds_read_b128 v[180:183], v144 offset:7168
	v_mfma_f32_16x16x32_bf16 v[94:97], v[236:239], v[200:203], v[94:97]
	v_add_u32_e32 v144, s40, v137
	v_mfma_f32_16x16x32_bf16 v[90:93], v[236:239], v[204:207], v[90:93]
	v_mfma_f32_16x16x32_bf16 v[86:89], v[236:239], v[208:211], v[86:89]
	ds_read_b128 v[184:187], v144 offset:16384
	v_mfma_f32_16x16x32_bf16 v[82:85], v[236:239], v[212:215], v[82:85]
	ds_read_b128 v[188:191], v144 offset:17408
	v_mfma_f32_16x16x32_bf16 v[78:81], v[236:239], v[216:219], v[78:81]
	ds_read_b128 v[192:195], v144 offset:18432
	v_mfma_f32_16x16x32_bf16 v[74:77], v[236:239], v[220:223], v[74:77]
	ds_read_b128 v[196:199], v144 offset:19456
	v_mfma_f32_16x16x32_bf16 v[70:73], v[236:239], v[224:227], v[70:73]
	v_mfma_f32_16x16x32_bf16 v[66:69], v[236:239], v[228:231], v[66:69]
	v_mfma_f32_16x16x32_bf16 v[62:65], v[240:243], v[200:203], v[62:65]
	v_mfma_f32_16x16x32_bf16 v[58:61], v[240:243], v[204:207], v[58:61]
	v_mfma_f32_16x16x32_bf16 v[54:57], v[240:243], v[208:211], v[54:57]
	v_mfma_f32_16x16x32_bf16 v[50:53], v[240:243], v[212:215], v[50:53]
	v_mfma_f32_16x16x32_bf16 v[46:49], v[240:243], v[216:219], v[46:49]
	v_mfma_f32_16x16x32_bf16 v[42:45], v[240:243], v[220:223], v[42:45]
	v_mfma_f32_16x16x32_bf16 v[38:41], v[240:243], v[224:227], v[38:41]
	v_mfma_f32_16x16x32_bf16 v[34:37], v[240:243], v[228:231], v[34:37]
	v_mfma_f32_16x16x32_bf16 v[30:33], v[244:247], v[200:203], v[30:33]
	v_mfma_f32_16x16x32_bf16 v[26:29], v[244:247], v[204:207], v[26:29]
	v_mfma_f32_16x16x32_bf16 v[22:25], v[244:247], v[208:211], v[22:25]
	v_mfma_f32_16x16x32_bf16 v[18:21], v[244:247], v[212:215], v[18:21]
	v_mfma_f32_16x16x32_bf16 v[14:17], v[244:247], v[216:219], v[14:17]
	v_mfma_f32_16x16x32_bf16 v[10:13], v[244:247], v[220:223], v[10:13]
	v_mfma_f32_16x16x32_bf16 v[6:9], v[244:247], v[224:227], v[6:9]
	v_mfma_f32_16x16x32_bf16 v[2:5], v[244:247], v[228:231], v[2:5]
	s_mov_b32 s41, s40
	s_add_i32 s40, s40, 0x6000
	s_cmp_eq_u32 s40, 0x12000
	s_cselect_b32 s40, 0, s40
	s_waitcnt vmcnt(0) lgkmcnt(0)
	s_barrier
	v_add_u32_e32 v144, s40, v136
	v_mfma_f32_16x16x32_bf16 v[126:129], v[184:187], v[146:149], v[126:129]
	ds_read_b128 v[200:203], v144 offset:0
	v_mfma_f32_16x16x32_bf16 v[122:125], v[184:187], v[152:155], v[122:125]
	ds_read_b128 v[204:207], v144 offset:1024
	v_mfma_f32_16x16x32_bf16 v[118:121], v[184:187], v[156:159], v[118:121]
	ds_read_b128 v[208:211], v144 offset:2048
	v_mfma_f32_16x16x32_bf16 v[114:117], v[184:187], v[162:165], v[114:117]
	ds_read_b128 v[212:215], v144 offset:3072
	v_mfma_f32_16x16x32_bf16 v[110:113], v[184:187], v[166:169], v[110:113]
	ds_read_b128 v[216:219], v144 offset:4096
	v_mfma_f32_16x16x32_bf16 v[106:109], v[184:187], v[170:173], v[106:109]
	ds_read_b128 v[220:223], v144 offset:5120
	v_mfma_f32_16x16x32_bf16 v[102:105], v[184:187], v[176:179], v[102:105]
	ds_read_b128 v[224:227], v144 offset:6144
	v_mfma_f32_16x16x32_bf16 v[98:101], v[184:187], v[180:183], v[98:101]
	ds_read_b128 v[228:231], v144 offset:7168
	v_mfma_f32_16x16x32_bf16 v[94:97], v[188:191], v[146:149], v[94:97]
	v_add_u32_e32 v144, s40, v137
	v_mfma_f32_16x16x32_bf16 v[90:93], v[188:191], v[152:155], v[90:93]
	v_mfma_f32_16x16x32_bf16 v[86:89], v[188:191], v[156:159], v[86:89]
	ds_read_b128 v[232:235], v144 offset:16384
	v_mfma_f32_16x16x32_bf16 v[82:85], v[188:191], v[162:165], v[82:85]
	ds_read_b128 v[236:239], v144 offset:17408
	v_mfma_f32_16x16x32_bf16 v[78:81], v[188:191], v[166:169], v[78:81]
	ds_read_b128 v[240:243], v144 offset:18432
	v_mfma_f32_16x16x32_bf16 v[74:77], v[188:191], v[170:173], v[74:77]
	ds_read_b128 v[244:247], v144 offset:19456
	v_mfma_f32_16x16x32_bf16 v[70:73], v[188:191], v[176:179], v[70:73]
	v_mfma_f32_16x16x32_bf16 v[66:69], v[188:191], v[180:183], v[66:69]
	v_mfma_f32_16x16x32_bf16 v[62:65], v[192:195], v[146:149], v[62:65]
	v_mfma_f32_16x16x32_bf16 v[58:61], v[192:195], v[152:155], v[58:61]
	v_mfma_f32_16x16x32_bf16 v[54:57], v[192:195], v[156:159], v[54:57]
	v_mfma_f32_16x16x32_bf16 v[50:53], v[192:195], v[162:165], v[50:53]
	v_mfma_f32_16x16x32_bf16 v[46:49], v[192:195], v[166:169], v[46:49]
	v_mfma_f32_16x16x32_bf16 v[42:45], v[192:195], v[170:173], v[42:45]
	v_mfma_f32_16x16x32_bf16 v[38:41], v[192:195], v[176:179], v[38:41]
	v_mfma_f32_16x16x32_bf16 v[34:37], v[192:195], v[180:183], v[34:37]
	v_mfma_f32_16x16x32_bf16 v[30:33], v[196:199], v[146:149], v[30:33]
	v_mfma_f32_16x16x32_bf16 v[26:29], v[196:199], v[152:155], v[26:29]
	v_mfma_f32_16x16x32_bf16 v[22:25], v[196:199], v[156:159], v[22:25]
	v_mfma_f32_16x16x32_bf16 v[18:21], v[196:199], v[162:165], v[18:21]
	v_mfma_f32_16x16x32_bf16 v[14:17], v[196:199], v[166:169], v[14:17]
	v_mfma_f32_16x16x32_bf16 v[10:13], v[196:199], v[170:173], v[10:13]
	v_mfma_f32_16x16x32_bf16 v[6:9], v[196:199], v[176:179], v[6:9]
	v_mfma_f32_16x16x32_bf16 v[2:5], v[196:199], v[180:183], v[2:5]
	s_mov_b32 s41, s40
	s_add_i32 s40, s40, 0x6000
	s_cmp_eq_u32 s40, 0x12000
	s_cselect_b32 s40, 0, s40
	s_mov_b32 s4, 0x8000
	s_mov_b32 s5, 0
	s_mov_b32 s10, 0x10000
	s_mov_b32 s11, 0
	s_mov_b32 s44, 0x3fd744fd
	s_waitcnt lgkmcnt(0)
; DEVI unsigned pack2(float a, float b) { return __builtin_bit_cast(unsigned, __builtin_convertvector((f32x2_t){a, b}, bf16x2_t)); }
; DEVI float blo(unsigned u) { return __uint_as_float(u << 16); }
; DEVI float bhi(unsigned u) { return __uint_as_float(u & 0xffff0000u); }
; DEVI float siluf_(float x) { return x * __builtin_amdgcn_rcpf(1.f + __expf(-x)); }
;     ...
;     for (int nf = 0; nf < 4; nf++)
; #pragma unroll
;       for (int mf = 0; mf < 8; mf++)
;         acc[nf][mf] = __builtin_amdgcn_mfma_f32_16x16x32_bf16(wb[nf], xa[mf], acc[nf][mf], 0, 0, 0);
;   }
;     ...
; #pragma unroll
;   for (int mf = 0; mf < 8; mf++) {
;     const int row = m0 + wm * 128 + mf * 16 + r16;
;     if (EPI == EPI_SWIGLU) {
; #pragma unroll
;       for (int nf = 0; nf < 2; nf++) {
;         const int hcol = (n0 >> 1) + wn * 32 + nf * 16 + quad * 4;
;         f32x4 g = acc[nf][mf], u = acc[nf + 2][mf];
;         u32x2 pk;
;         pk[0] = pack2(siluf_(g[0]) * u[0], siluf_(g[1]) * u[1]);
;         pk[1] = pack2(siluf_(g[2]) * u[2], siluf_(g[3]) * u[3]);
;         *(u32x2*)(outb + (size_t)row * DFF + hcol) = pk;
;       }
;     } else {
; #pragma unroll
;       for (int nf = 0; nf < 4; nf++) {
;         const int col = n0 + wn * 64 + nf * 16 + quad * 4;
;         f32x4 a = acc[nf][mf];
;         if (EPI == EPI_RESID || EPI == EPI_RESID_ATOMIC) {
;           f32x4 x = a;
;           if (EPI == EPI_RESID || kpart == 0) {
;             const u32x2 xr = *(const u32x2*)((const u16*)(p.ws + WS_XB) + (size_t)row * 1024 + col);
;             x[0] += ALPHA * blo(xr[0]); x[1] += ALPHA * bhi(xr[0]); x[2] += ALPHA * blo(xr[1]); x[3] += ALPHA * bhi(xr[1]);
;           }
;           if (EPI == EPI_RESID) *(f32x4*)((float*)(p.ws + WS_XF) + (size_t)row * 1024 + col) = x;
	v_mfma_f32_16x16x32_bf16 v[126:129], v[232:235], v[200:203], v[126:129]
	v_mfma_f32_16x16x32_bf16 v[122:125], v[232:235], v[204:207], v[122:125]
	v_mfma_f32_16x16x32_bf16 v[118:121], v[232:235], v[208:211], v[118:121]
	v_mfma_f32_16x16x32_bf16 v[114:117], v[232:235], v[212:215], v[114:117]
	v_mfma_f32_16x16x32_bf16 v[110:113], v[232:235], v[216:219], v[110:113]
	global_load_dwordx2 v[146:147], v[138:139], off offset:0
	v_mfma_f32_16x16x32_bf16 v[106:109], v[232:235], v[220:223], v[106:109]
	global_load_dwordx2 v[148:149], v[138:139], off offset:32
	v_mfma_f32_16x16x32_bf16 v[102:105], v[232:235], v[224:227], v[102:105]
	global_load_dwordx2 v[152:153], v[138:139], off offset:64
	v_mfma_f32_16x16x32_bf16 v[98:101], v[232:235], v[228:231], v[98:101]
	global_load_dwordx2 v[154:155], v[138:139], off offset:96
	v_lshl_add_u64 v[138:139], v[138:139], 0, s[4:5]
	v_mfma_f32_16x16x32_bf16 v[94:97], v[236:239], v[200:203], v[94:97]
	global_load_dwordx2 v[156:157], v[138:139], off offset:0
	v_mfma_f32_16x16x32_bf16 v[90:93], v[236:239], v[204:207], v[90:93]
	global_load_dwordx2 v[158:159], v[138:139], off offset:32
	v_mfma_f32_16x16x32_bf16 v[86:89], v[236:239], v[208:211], v[86:89]
	global_load_dwordx2 v[162:163], v[138:139], off offset:64
	v_mfma_f32_16x16x32_bf16 v[82:85], v[236:239], v[212:215], v[82:85]
	global_load_dwordx2 v[164:165], v[138:139], off offset:96
	v_lshl_add_u64 v[138:139], v[138:139], 0, s[4:5]
	v_mfma_f32_16x16x32_bf16 v[78:81], v[236:239], v[216:219], v[78:81]
	global_load_dwordx2 v[166:167], v[138:139], off offset:0
	v_mfma_f32_16x16x32_bf16 v[74:77], v[236:239], v[220:223], v[74:77]
	global_load_dwordx2 v[168:169], v[138:139], off offset:32
	v_mfma_f32_16x16x32_bf16 v[70:73], v[236:239], v[224:227], v[70:73]
	global_load_dwordx2 v[170:171], v[138:139], off offset:64
	v_mfma_f32_16x16x32_bf16 v[66:69], v[236:239], v[228:231], v[66:69]
	global_load_dwordx2 v[172:173], v[138:139], off offset:96
	v_lshl_add_u64 v[138:139], v[138:139], 0, s[4:5]
	v_mfma_f32_16x16x32_bf16 v[62:65], v[240:243], v[200:203], v[62:65]
	global_load_dwordx2 v[176:177], v[138:139], off offset:0
	v_mfma_f32_16x16x32_bf16 v[58:61], v[240:243], v[204:207], v[58:61]
	global_load_dwordx2 v[178:179], v[138:139], off offset:32
	v_mfma_f32_16x16x32_bf16 v[54:57], v[240:243], v[208:211], v[54:57]
	global_load_dwordx2 v[180:181], v[138:139], off offset:64
	v_mfma_f32_16x16x32_bf16 v[50:53], v[240:243], v[212:215], v[50:53]
	global_load_dwordx2 v[182:183], v[138:139], off offset:96
	v_lshl_add_u64 v[138:139], v[138:139], 0, s[4:5]
	v_mfma_f32_16x16x32_bf16 v[46:49], v[240:243], v[216:219], v[46:49]
	global_load_dwordx2 v[184:185], v[138:139], off offset:0
	v_mfma_f32_16x16x32_bf16 v[42:45], v[240:243], v[220:223], v[42:45]
	global_load_dwordx2 v[186:187], v[138:139], off offset:32
	v_mfma_f32_16x16x32_bf16 v[38:41], v[240:243], v[224:227], v[38:41]
	global_load_dwordx2 v[188:189], v[138:139], off offset:64
	v_mfma_f32_16x16x32_bf16 v[34:37], v[240:243], v[228:231], v[34:37]
	global_load_dwordx2 v[190:191], v[138:139], off offset:96
	v_lshl_add_u64 v[138:139], v[138:139], 0, s[4:5]
	v_mfma_f32_16x16x32_bf16 v[30:33], v[244:247], v[200:203], v[30:33]
	global_load_dwordx2 v[192:193], v[138:139], off offset:0
	v_mfma_f32_16x16x32_bf16 v[26:29], v[244:247], v[204:207], v[26:29]
	global_load_dwordx2 v[194:195], v[138:139], off offset:32
	v_mfma_f32_16x16x32_bf16 v[22:25], v[244:247], v[208:211], v[22:25]
	global_load_dwordx2 v[196:197], v[138:139], off offset:64
	v_mfma_f32_16x16x32_bf16 v[18:21], v[244:247], v[212:215], v[18:21]
	global_load_dwordx2 v[198:199], v[138:139], off offset:96
	v_lshl_add_u64 v[138:139], v[138:139], 0, s[4:5]
	v_mfma_f32_16x16x32_bf16 v[14:17], v[244:247], v[216:219], v[14:17]
	v_mfma_f32_16x16x32_bf16 v[10:13], v[244:247], v[220:223], v[10:13]
	v_mfma_f32_16x16x32_bf16 v[6:9], v[244:247], v[224:227], v[6:9]
	v_mfma_f32_16x16x32_bf16 v[2:5], v[244:247], v[228:231], v[2:5]
	s_mov_b32 m0, s43
	global_load_dwordx2 v[200:201], v[138:139], off offset:0
	global_load_dwordx2 v[202:203], v[138:139], off offset:32
	global_load_dwordx2 v[204:205], v[138:139], off offset:64
	global_load_dwordx2 v[206:207], v[138:139], off offset:96
	v_lshl_add_u64 v[138:139], v[138:139], 0, s[4:5]
	global_load_dwordx2 v[208:209], v[138:139], off offset:0
	global_load_dwordx2 v[210:211], v[138:139], off offset:32
	global_load_dwordx2 v[212:213], v[138:139], off offset:64
	global_load_dwordx2 v[214:215], v[138:139], off offset:96
	v_lshl_add_u64 v[138:139], v[138:139], 0, s[4:5]
	s_nop 7
	s_waitcnt vmcnt(31)
	v_lshlrev_b32_e32 v216, 16, v146
	v_and_b32_e32 v146, 0xffff0000, v146
	v_lshlrev_b32_e32 v217, 16, v147
	v_and_b32_e32 v147, 0xffff0000, v147
	v_fmac_f32_e32 v126, s44, v216
	v_fmac_f32_e32 v127, s44, v146
	v_fmac_f32_e32 v128, s44, v217
	v_fmac_f32_e32 v129, s44, v147
	global_store_dwordx4 v[140:141], v[126:129], off offset:0
	s_waitcnt vmcnt(31)
	v_lshlrev_b32_e32 v216, 16, v148
	v_and_b32_e32 v148, 0xffff0000, v148
	v_lshlrev_b32_e32 v217, 16, v149
	v_and_b32_e32 v149, 0xffff0000, v149
	v_fmac_f32_e32 v94, s44, v216
	v_fmac_f32_e32 v95, s44, v148
	v_fmac_f32_e32 v96, s44, v217
	v_fmac_f32_e32 v97, s44, v149
	global_store_dwordx4 v[140:141], v[94:97], off offset:64
	s_waitcnt vmcnt(31)
	v_lshlrev_b32_e32 v216, 16, v152
	v_and_b32_e32 v152, 0xffff0000, v152
	v_lshlrev_b32_e32 v217, 16, v153
	v_and_b32_e32 v153, 0xffff0000, v153
	v_fmac_f32_e32 v62, s44, v216
	v_fmac_f32_e32 v63, s44, v152
	v_fmac_f32_e32 v64, s44, v217
	v_fmac_f32_e32 v65, s44, v153
	global_store_dwordx4 v[140:141], v[62:65], off offset:128
	s_waitcnt vmcnt(31)
; DEVI float blo(unsigned u) { return __uint_as_float(u << 16); }
; DEVI float bhi(unsigned u) { return __uint_as_float(u & 0xffff0000u); }
;     ...
;       for (int nf = 0; nf < 4; nf++) {
;         const int col = n0 + wn * 64 + nf * 16 + quad * 4;
;         f32x4 a = acc[nf][mf];
;         if (EPI == EPI_RESID || EPI == EPI_RESID_ATOMIC) {
;           f32x4 x = a;
;           if (EPI == EPI_RESID || kpart == 0) {
;             const u32x2 xr = *(const u32x2*)((const u16*)(p.ws + WS_XB) + (size_t)row * 1024 + col);
;             x[0] += ALPHA * blo(xr[0]); x[1] += ALPHA * bhi(xr[0]); x[2] += ALPHA * blo(xr[1]); x[3] += ALPHA * bhi(xr[1]);
;           }
;           if (EPI == EPI_RESID) *(f32x4*)((float*)(p.ws + WS_XF) + (size_t)row * 1024 + col) = x;
	v_lshlrev_b32_e32 v216, 16, v154
	v_and_b32_e32 v154, 0xffff0000, v154
	v_lshlrev_b32_e32 v217, 16, v155
	v_and_b32_e32 v155, 0xffff0000, v155
	v_fmac_f32_e32 v30, s44, v216
	v_fmac_f32_e32 v31, s44, v154
	v_fmac_f32_e32 v32, s44, v217
	v_fmac_f32_e32 v33, s44, v155
	global_store_dwordx4 v[140:141], v[30:33], off offset:192
	v_lshl_add_u64 v[140:141], v[140:141], 0, s[10:11]
	s_waitcnt vmcnt(31)
	v_lshlrev_b32_e32 v216, 16, v156
	v_and_b32_e32 v156, 0xffff0000, v156
	v_lshlrev_b32_e32 v217, 16, v157
	v_and_b32_e32 v157, 0xffff0000, v157
	v_fmac_f32_e32 v122, s44, v216
	v_fmac_f32_e32 v123, s44, v156
	v_fmac_f32_e32 v124, s44, v217
	v_fmac_f32_e32 v125, s44, v157
	global_store_dwordx4 v[140:141], v[122:125], off offset:0
	s_waitcnt vmcnt(31)
	v_lshlrev_b32_e32 v216, 16, v158
	v_and_b32_e32 v158, 0xffff0000, v158
	v_lshlrev_b32_e32 v217, 16, v159
	v_and_b32_e32 v159, 0xffff0000, v159
	v_fmac_f32_e32 v90, s44, v216
	v_fmac_f32_e32 v91, s44, v158
	v_fmac_f32_e32 v92, s44, v217
	v_fmac_f32_e32 v93, s44, v159
	global_store_dwordx4 v[140:141], v[90:93], off offset:64
	s_waitcnt vmcnt(31)
	v_lshlrev_b32_e32 v216, 16, v162
	v_and_b32_e32 v162, 0xffff0000, v162
	v_lshlrev_b32_e32 v217, 16, v163
	v_and_b32_e32 v163, 0xffff0000, v163
	v_fmac_f32_e32 v58, s44, v216
	v_fmac_f32_e32 v59, s44, v162
	v_fmac_f32_e32 v60, s44, v217
	v_fmac_f32_e32 v61, s44, v163
	global_store_dwordx4 v[140:141], v[58:61], off offset:128
	s_waitcnt vmcnt(31)
	v_lshlrev_b32_e32 v216, 16, v164
	v_and_b32_e32 v164, 0xffff0000, v164
	v_lshlrev_b32_e32 v217, 16, v165
	v_and_b32_e32 v165, 0xffff0000, v165
	v_fmac_f32_e32 v26, s44, v216
	v_fmac_f32_e32 v27, s44, v164
	v_fmac_f32_e32 v28, s44, v217
	v_fmac_f32_e32 v29, s44, v165
	global_store_dwordx4 v[140:141], v[26:29], off offset:192
	v_lshl_add_u64 v[140:141], v[140:141], 0, s[10:11]
	s_waitcnt vmcnt(31)
	v_lshlrev_b32_e32 v216, 16, v166
	v_and_b32_e32 v166, 0xffff0000, v166
	v_lshlrev_b32_e32 v217, 16, v167
	v_and_b32_e32 v167, 0xffff0000, v167
	v_fmac_f32_e32 v118, s44, v216
	v_fmac_f32_e32 v119, s44, v166
	v_fmac_f32_e32 v120, s44, v217
	v_fmac_f32_e32 v121, s44, v167
	global_store_dwordx4 v[140:141], v[118:121], off offset:0
	s_waitcnt vmcnt(31)
	v_lshlrev_b32_e32 v216, 16, v168
	v_and_b32_e32 v168, 0xffff0000, v168
	v_lshlrev_b32_e32 v217, 16, v169
	v_and_b32_e32 v169, 0xffff0000, v169
	v_fmac_f32_e32 v86, s44, v216
	v_fmac_f32_e32 v87, s44, v168
	v_fmac_f32_e32 v88, s44, v217
	v_fmac_f32_e32 v89, s44, v169
	global_store_dwordx4 v[140:141], v[86:89], off offset:64
	s_waitcnt vmcnt(31)
	v_lshlrev_b32_e32 v216, 16, v170
	v_and_b32_e32 v170, 0xffff0000, v170
	v_lshlrev_b32_e32 v217, 16, v171
	v_and_b32_e32 v171, 0xffff0000, v171
	v_fmac_f32_e32 v54, s44, v216
	v_fmac_f32_e32 v55, s44, v170
	v_fmac_f32_e32 v56, s44, v217
	v_fmac_f32_e32 v57, s44, v171
	global_store_dwordx4 v[140:141], v[54:57], off offset:128
	s_waitcnt vmcnt(31)
	v_lshlrev_b32_e32 v216, 16, v172
	v_and_b32_e32 v172, 0xffff0000, v172
	v_lshlrev_b32_e32 v217, 16, v173
	v_and_b32_e32 v173, 0xffff0000, v173
	v_fmac_f32_e32 v22, s44, v216
	v_fmac_f32_e32 v23, s44, v172
	v_fmac_f32_e32 v24, s44, v217
	v_fmac_f32_e32 v25, s44, v173
	global_store_dwordx4 v[140:141], v[22:25], off offset:192
	v_lshl_add_u64 v[140:141], v[140:141], 0, s[10:11]
	s_waitcnt vmcnt(31)
	v_lshlrev_b32_e32 v216, 16, v176
	v_and_b32_e32 v176, 0xffff0000, v176
	v_lshlrev_b32_e32 v217, 16, v177
	v_and_b32_e32 v177, 0xffff0000, v177
	v_fmac_f32_e32 v114, s44, v216
	v_fmac_f32_e32 v115, s44, v176
	v_fmac_f32_e32 v116, s44, v217
	v_fmac_f32_e32 v117, s44, v177
	global_store_dwordx4 v[140:141], v[114:117], off offset:0
	s_waitcnt vmcnt(31)
	v_lshlrev_b32_e32 v216, 16, v178
	v_and_b32_e32 v178, 0xffff0000, v178
	v_lshlrev_b32_e32 v217, 16, v179
	v_and_b32_e32 v179, 0xffff0000, v179
	v_fmac_f32_e32 v82, s44, v216
	v_fmac_f32_e32 v83, s44, v178
	v_fmac_f32_e32 v84, s44, v217
	v_fmac_f32_e32 v85, s44, v179
	global_store_dwordx4 v[140:141], v[82:85], off offset:64
	s_waitcnt vmcnt(31)
	v_lshlrev_b32_e32 v216, 16, v180
	v_and_b32_e32 v180, 0xffff0000, v180
	v_lshlrev_b32_e32 v217, 16, v181
	v_and_b32_e32 v181, 0xffff0000, v181
	v_fmac_f32_e32 v50, s44, v216
	v_fmac_f32_e32 v51, s44, v180
	v_fmac_f32_e32 v52, s44, v217
	v_fmac_f32_e32 v53, s44, v181
	global_store_dwordx4 v[140:141], v[50:53], off offset:128
	s_waitcnt vmcnt(31)
	v_lshlrev_b32_e32 v216, 16, v182
	v_and_b32_e32 v182, 0xffff0000, v182
	v_lshlrev_b32_e32 v217, 16, v183
	v_and_b32_e32 v183, 0xffff0000, v183
	v_fmac_f32_e32 v18, s44, v216
	v_fmac_f32_e32 v19, s44, v182
	v_fmac_f32_e32 v20, s44, v217
	v_fmac_f32_e32 v21, s44, v183
	global_store_dwordx4 v[140:141], v[18:21], off offset:192
	v_lshl_add_u64 v[140:141], v[140:141], 0, s[10:11]
	s_waitcnt vmcnt(31)
	v_lshlrev_b32_e32 v216, 16, v184
	v_and_b32_e32 v184, 0xffff0000, v184
	v_lshlrev_b32_e32 v217, 16, v185
	v_and_b32_e32 v185, 0xffff0000, v185
	v_fmac_f32_e32 v110, s44, v216
	v_fmac_f32_e32 v111, s44, v184
	v_fmac_f32_e32 v112, s44, v217
	v_fmac_f32_e32 v113, s44, v185
	global_store_dwordx4 v[140:141], v[110:113], off offset:0
	s_waitcnt vmcnt(31)
; DEVI float blo(unsigned u) { return __uint_as_float(u << 16); }
; DEVI float bhi(unsigned u) { return __uint_as_float(u & 0xffff0000u); }
;     ...
;       for (int nf = 0; nf < 4; nf++) {
;         const int col = n0 + wn * 64 + nf * 16 + quad * 4;
;         f32x4 a = acc[nf][mf];
;         if (EPI == EPI_RESID || EPI == EPI_RESID_ATOMIC) {
;           f32x4 x = a;
;           if (EPI == EPI_RESID || kpart == 0) {
;             const u32x2 xr = *(const u32x2*)((const u16*)(p.ws + WS_XB) + (size_t)row * 1024 + col);
;             x[0] += ALPHA * blo(xr[0]); x[1] += ALPHA * bhi(xr[0]); x[2] += ALPHA * blo(xr[1]); x[3] += ALPHA * bhi(xr[1]);
;           }
;           if (EPI == EPI_RESID) *(f32x4*)((float*)(p.ws + WS_XF) + (size_t)row * 1024 + col) = x;
	v_lshlrev_b32_e32 v216, 16, v186
	v_and_b32_e32 v186, 0xffff0000, v186
	v_lshlrev_b32_e32 v217, 16, v187
	v_and_b32_e32 v187, 0xffff0000, v187
	v_fmac_f32_e32 v78, s44, v216
	v_fmac_f32_e32 v79, s44, v186
	v_fmac_f32_e32 v80, s44, v217
	v_fmac_f32_e32 v81, s44, v187
	global_store_dwordx4 v[140:141], v[78:81], off offset:64
	s_waitcnt vmcnt(31)
	v_lshlrev_b32_e32 v216, 16, v188
	v_and_b32_e32 v188, 0xffff0000, v188
	v_lshlrev_b32_e32 v217, 16, v189
	v_and_b32_e32 v189, 0xffff0000, v189
	v_fmac_f32_e32 v46, s44, v216
	v_fmac_f32_e32 v47, s44, v188
	v_fmac_f32_e32 v48, s44, v217
	v_fmac_f32_e32 v49, s44, v189
	global_store_dwordx4 v[140:141], v[46:49], off offset:128
	s_waitcnt vmcnt(31)
	v_lshlrev_b32_e32 v216, 16, v190
	v_and_b32_e32 v190, 0xffff0000, v190
	v_lshlrev_b32_e32 v217, 16, v191
	v_and_b32_e32 v191, 0xffff0000, v191
	v_fmac_f32_e32 v14, s44, v216
	v_fmac_f32_e32 v15, s44, v190
	v_fmac_f32_e32 v16, s44, v217
	v_fmac_f32_e32 v17, s44, v191
	global_store_dwordx4 v[140:141], v[14:17], off offset:192
	v_lshl_add_u64 v[140:141], v[140:141], 0, s[10:11]
	s_waitcnt vmcnt(31)
	v_lshlrev_b32_e32 v216, 16, v192
	v_and_b32_e32 v192, 0xffff0000, v192
	v_lshlrev_b32_e32 v217, 16, v193
	v_and_b32_e32 v193, 0xffff0000, v193
	v_fmac_f32_e32 v106, s44, v216
	v_fmac_f32_e32 v107, s44, v192
	v_fmac_f32_e32 v108, s44, v217
	v_fmac_f32_e32 v109, s44, v193
	global_store_dwordx4 v[140:141], v[106:109], off offset:0
	s_waitcnt vmcnt(31)
	v_lshlrev_b32_e32 v216, 16, v194
	v_and_b32_e32 v194, 0xffff0000, v194
	v_lshlrev_b32_e32 v217, 16, v195
	v_and_b32_e32 v195, 0xffff0000, v195
	v_fmac_f32_e32 v74, s44, v216
	v_fmac_f32_e32 v75, s44, v194
	v_fmac_f32_e32 v76, s44, v217
	v_fmac_f32_e32 v77, s44, v195
	global_store_dwordx4 v[140:141], v[74:77], off offset:64
	s_waitcnt vmcnt(31)
	v_lshlrev_b32_e32 v216, 16, v196
	v_and_b32_e32 v196, 0xffff0000, v196
	v_lshlrev_b32_e32 v217, 16, v197
	v_and_b32_e32 v197, 0xffff0000, v197
	v_fmac_f32_e32 v42, s44, v216
	v_fmac_f32_e32 v43, s44, v196
	v_fmac_f32_e32 v44, s44, v217
	v_fmac_f32_e32 v45, s44, v197
	global_store_dwordx4 v[140:141], v[42:45], off offset:128
	s_waitcnt vmcnt(31)
	v_lshlrev_b32_e32 v216, 16, v198
	v_and_b32_e32 v198, 0xffff0000, v198
	v_lshlrev_b32_e32 v217, 16, v199
	v_and_b32_e32 v199, 0xffff0000, v199
	v_fmac_f32_e32 v10, s44, v216
	v_fmac_f32_e32 v11, s44, v198
	v_fmac_f32_e32 v12, s44, v217
	v_fmac_f32_e32 v13, s44, v199
	global_store_dwordx4 v[140:141], v[10:13], off offset:192
	v_lshl_add_u64 v[140:141], v[140:141], 0, s[10:11]
	s_waitcnt vmcnt(31)
	v_lshlrev_b32_e32 v216, 16, v200
	v_and_b32_e32 v200, 0xffff0000, v200
	v_lshlrev_b32_e32 v217, 16, v201
	v_and_b32_e32 v201, 0xffff0000, v201
	v_fmac_f32_e32 v102, s44, v216
	v_fmac_f32_e32 v103, s44, v200
	v_fmac_f32_e32 v104, s44, v217
	v_fmac_f32_e32 v105, s44, v201
	global_store_dwordx4 v[140:141], v[102:105], off offset:0
	s_waitcnt vmcnt(31)
	v_lshlrev_b32_e32 v216, 16, v202
	v_and_b32_e32 v202, 0xffff0000, v202
	v_lshlrev_b32_e32 v217, 16, v203
	v_and_b32_e32 v203, 0xffff0000, v203
	v_fmac_f32_e32 v70, s44, v216
	v_fmac_f32_e32 v71, s44, v202
	v_fmac_f32_e32 v72, s44, v217
	v_fmac_f32_e32 v73, s44, v203
	global_store_dwordx4 v[140:141], v[70:73], off offset:64
	s_waitcnt vmcnt(31)
	v_lshlrev_b32_e32 v216, 16, v204
	v_and_b32_e32 v204, 0xffff0000, v204
	v_lshlrev_b32_e32 v217, 16, v205
	v_and_b32_e32 v205, 0xffff0000, v205
	v_fmac_f32_e32 v38, s44, v216
	v_fmac_f32_e32 v39, s44, v204
	v_fmac_f32_e32 v40, s44, v217
	v_fmac_f32_e32 v41, s44, v205
	global_store_dwordx4 v[140:141], v[38:41], off offset:128
	s_waitcnt vmcnt(31)
	v_lshlrev_b32_e32 v216, 16, v206
	v_and_b32_e32 v206, 0xffff0000, v206
	v_lshlrev_b32_e32 v217, 16, v207
	v_and_b32_e32 v207, 0xffff0000, v207
	v_fmac_f32_e32 v6, s44, v216
	v_fmac_f32_e32 v7, s44, v206
	v_fmac_f32_e32 v8, s44, v217
	v_fmac_f32_e32 v9, s44, v207
	global_store_dwordx4 v[140:141], v[6:9], off offset:192
	v_lshl_add_u64 v[140:141], v[140:141], 0, s[10:11]
	s_waitcnt vmcnt(31)
	v_lshlrev_b32_e32 v216, 16, v208
	v_and_b32_e32 v208, 0xffff0000, v208
	v_lshlrev_b32_e32 v217, 16, v209
	v_and_b32_e32 v209, 0xffff0000, v209
	v_fmac_f32_e32 v98, s44, v216
	v_fmac_f32_e32 v99, s44, v208
	v_fmac_f32_e32 v100, s44, v217
	v_fmac_f32_e32 v101, s44, v209
	global_store_dwordx4 v[140:141], v[98:101], off offset:0
	s_waitcnt vmcnt(31)
	v_lshlrev_b32_e32 v216, 16, v210
	v_and_b32_e32 v210, 0xffff0000, v210
	v_lshlrev_b32_e32 v217, 16, v211
	v_and_b32_e32 v211, 0xffff0000, v211
	v_fmac_f32_e32 v66, s44, v216
	v_fmac_f32_e32 v67, s44, v210
	v_fmac_f32_e32 v68, s44, v217
	v_fmac_f32_e32 v69, s44, v211
	global_store_dwordx4 v[140:141], v[66:69], off offset:64
	s_waitcnt vmcnt(31)
	v_lshlrev_b32_e32 v216, 16, v212
	v_and_b32_e32 v212, 0xffff0000, v212
	v_lshlrev_b32_e32 v217, 16, v213
	v_and_b32_e32 v213, 0xffff0000, v213
	v_fmac_f32_e32 v34, s44, v216
	v_fmac_f32_e32 v35, s44, v212
	v_fmac_f32_e32 v36, s44, v217
	v_fmac_f32_e32 v37, s44, v213
	global_store_dwordx4 v[140:141], v[34:37], off offset:128
	s_waitcnt vmcnt(31)
	v_lshlrev_b32_e32 v216, 16, v214
	v_and_b32_e32 v214, 0xffff0000, v214
	v_lshlrev_b32_e32 v217, 16, v215
	v_and_b32_e32 v215, 0xffff0000, v215
	v_fmac_f32_e32 v2, s44, v216
	v_fmac_f32_e32 v3, s44, v214
	v_fmac_f32_e32 v4, s44, v217
	v_fmac_f32_e32 v5, s44, v215
	global_store_dwordx4 v[140:141], v[2:5], off offset:192
	s_branch .LBB0_146
.LBB0_224:
	s_mov_b64 s[2:3], 0

; #define LAS __attribute__((address_space(3)))
;     ...
;   f32x4 acc[4][8];
; #pragma unroll
;   for (int i = 0; i < 4; i++)
; #pragma unroll
;     for (int j = 0; j < 8; j++) acc[i][j] = (f32x4){0.f, 0.f, 0.f, 0.f};
;   const int nk = (nk_part < 0) ? (K >> 5) : nk_part;
;   const int lrow = tid >> 2, lpc = tid & 3;
;   const int lch = lpc ^ ((0x78 >> (((lrow >> 2) & 3) * 2)) & 3);
;   const u16* ga = A + (size_t)(m0 + lrow) * lda + kbeg + lch * 8;
;   const u16* gb = Bt + (size_t)(n0 + lrow) * K + kbeg + lch * 8;
;   const size_t ga1 = (size_t)64 * lda, gb1 = (size_t)64 * K;
;   const unsigned lds0 = (unsigned)(uintptr_t)(LAS char*)smem + (unsigned)__builtin_amdgcn_readfirstlane(wid) * 1024u;
;     ...
;   __syncthreads();
;   G2_STAGE(0); G2_STAGE(1);
;   const int fsw = (0x78 >> (((r16 >> 2) & 3) * 2)) & 3;
;   const int aoff = (wm * 128 + r16) * 64 + ((quad ^ fsw) << 4);
;   const int boff = 16384 + (wn * 64 + r16) * 64 + ((quad ^ fsw) << 4);
; DEVI void run_phase(const Params& p, int ph, char* smem) {
;     ...
;         } else {
;           const int u_ = t - 512, tl_ = u_ / 8, q_ = u_ - tl_ * 8;
;           gemm_tile256<EPI_RESID_ATOMIC>(p, mix, 1024, Bt, 1024, (64 + (tl_ & 1)) * 256, (tl_ >> 1) * 128, nullptr, 0, smem, q_ * 128, 4, q_);
.LBB0_758:
	s_cmpk_gt_i32 s39, 0x1ff
	s_mov_b64 s[2:3], -1
	s_cbranch_scc0 .LBB0_812
	s_sub_i32 s43, s39, 512
	s_lshr_b32 s42, s43, 3
	s_and_b32 s98, s43, 7
	s_lshr_b32 s15, s42, 1
	s_and_b32 s42, s42, 1
	s_add_i32 s42, s42, 64
	v_readlane_b32 s2, v250, 5
	v_readlane_b32 s3, v250, 6
	v_readlane_b32 s43, v254, 62
	s_mul_i32 s1, s42, 0x80000
	s_add_u32 s4, s2, s1
	s_addc_u32 s5, s3, 0
	s_add_u32 s4, s4, 0xb580000
	s_addc_u32 s5, s5, 0
	s_mul_i32 s1, s43, 0x200000
	s_mul_i32 s14, s15, 0x40000
	s_add_i32 s1, s1, s14
	s_add_u32 s10, s2, s1
	s_addc_u32 s11, s3, 0
	s_add_u32 s10, s10, 0x15e00000
	s_addc_u32 s11, s11, 0
	s_mul_i32 s1, s98, 256
	s_add_u32 s4, s4, s1
	s_addc_u32 s5, s5, 0
	s_mul_i32 s1, s98, 512
	s_add_u32 s10, s10, s1
	s_addc_u32 s11, s11, 0
	s_movk_i32 s0, 0x78
	v_lshrrev_b32_e32 v0, 2, v145
	v_and_b32_e32 v131, 3, v145
	v_bfe_u32 v136, v145, 4, 2
	v_lshlrev_b32_e32 v136, 1, v136
	v_lshrrev_b32_e64 v136, v136, s0
	v_and_b32_e32 v136, 3, v136
	v_xor_b32_e32 v131, v131, v136
	v_lshlrev_b32_e32 v131, 4, v131
	s_movk_i32 s14, 0x800
	v_mad_u32_u24 v0, v0, s14, v131
	v_bfe_u32 v137, v145, 2, 1
	s_movk_i32 s14, 0x7c0
	v_mul_u32_u24_e32 v136, s14, v137
	v_sub_u32_e32 v136, v0, v136
	v_mov_b32_e32 v137, 0
	v_lshl_add_u64 v[134:135], s[10:11], 0, v[136:137]
	v_bfe_u32 v137, v145, 2, 1
	s_mov_b32 s12, 64
	s_mov_b32 s13, 0
	v_lshl_add_u64 v[132:133], s[4:5], 0, v[0:1]
	v_bfe_u32 v136, v145, 2, 2
	v_lshlrev_b32_e32 v136, 1, v136
	v_lshrrev_b32_e64 v136, v136, s0
	v_and_b32_e32 v136, 3, v136
	v_bfe_u32 v137, v145, 4, 2
	v_xor_b32_e32 v136, v136, v137
	v_lshlrev_b32_e32 v136, 4, v136
	v_and_b32_e32 v131, 15, v145
	v_lshl_or_b32 v136, v131, 6, v136
	v_bfe_u32 v137, v145, 6, 1
	v_lshl_or_b32 v137, v137, 12, v136
	v_lshrrev_b32_e32 v0, 7, v145
	v_lshl_or_b32 v136, v0, 13, v136
	v_and_b32_e32 v140, 1, v131
	v_lshl_or_b32 v131, v0, 7, v131
	v_bfe_u32 v0, v145, 4, 2
	v_lshlrev_b32_e32 v0, 3, v0
	v_bfe_u32 v141, v145, 6, 1
	s_lshl_b32 s1, s42, 19
	s_lshl_b32 s14, s15, 8
	s_add_i32 s1, s1, s14
	s_add_u32 s4, s2, s1
	s_addc_u32 s5, s3, 0
	s_add_u32 s4, s4, 0x4200000
	s_addc_u32 s5, s5, 0
	v_lshlrev_b32_e32 v138, 11, v131
	v_lshl_add_u32 v138, v141, 7, v138
	v_add_u32_e32 v138, v138, v0
	v_mov_b32_e32 v139, 0
	v_lshl_add_u64 v[138:139], s[4:5], 0, v[138:139]
	s_and_b32 s1, s42, 1
	s_lshl_b32 s1, s1, 20
	s_lshl_b32 s14, s98, 21
	s_add_i32 s1, s1, s14
	s_lshl_b32 s14, s15, 9
	s_add_i32 s1, s1, s14
	s_add_u32 s10, s2, s1
	s_addc_u32 s11, s3, 0
	s_add_u32 s10, s10, 0x1dcc0000
	s_addc_u32 s11, s11, 0
	v_lshlrev_b32_e32 v140, 12, v131
	v_lshl_add_u32 v140, v141, 8, v140
	v_lshl_add_u32 v140, v0, 1, v140
	v_mov_b32_e32 v141, 0
	v_lshl_add_u64 v[140:141], s[10:11], 0, v[140:141]
	s_mov_b32 s2, 0x20000
	s_mov_b32 s3, 0
	v_lshrrev_b32_e32 v0, 6, v145
	v_lshlrev_b32_e32 v0, 10, v0
	s_nop 0
	v_readfirstlane_b32 s43, v0
	s_mov_b32 s40, m0
	s_mov_b32 s4, 128
	s_mov_b32 s5, 0
	v_mov_b32_e32 v2, 0
	v_mov_b32_e32 v3, 0
	v_mov_b32_e32 v4, 0
	v_mov_b32_e32 v5, 0
	v_mov_b32_e32 v6, 0
	v_mov_b32_e32 v7, 0
	v_mov_b32_e32 v8, 0
	v_mov_b32_e32 v9, 0
	v_mov_b32_e32 v10, 0
	v_mov_b32_e32 v11, 0
	v_mov_b32_e32 v12, 0
	v_mov_b32_e32 v13, 0
	v_mov_b32_e32 v14, 0
	v_mov_b32_e32 v15, 0
	v_mov_b32_e32 v16, 0
	v_mov_b32_e32 v17, 0
	v_mov_b32_e32 v18, 0
	v_mov_b32_e32 v19, 0
	v_mov_b32_e32 v20, 0
	v_mov_b32_e32 v21, 0
	v_mov_b32_e32 v22, 0
	v_mov_b32_e32 v23, 0
	v_mov_b32_e32 v24, 0
	v_mov_b32_e32 v25, 0
	v_mov_b32_e32 v26, 0
	v_mov_b32_e32 v27, 0
	v_mov_b32_e32 v28, 0
	v_mov_b32_e32 v29, 0
	v_mov_b32_e32 v30, 0
	v_mov_b32_e32 v31, 0
	v_mov_b32_e32 v32, 0
	v_mov_b32_e32 v33, 0
	v_mov_b32_e32 v34, 0
	v_mov_b32_e32 v35, 0
	v_mov_b32_e32 v36, 0
	v_mov_b32_e32 v37, 0
	v_mov_b32_e32 v38, 0
	v_mov_b32_e32 v39, 0
	v_mov_b32_e32 v40, 0
	v_mov_b32_e32 v41, 0
	v_mov_b32_e32 v42, 0
	v_mov_b32_e32 v43, 0
	v_mov_b32_e32 v44, 0
	v_mov_b32_e32 v45, 0
	v_mov_b32_e32 v46, 0
	v_mov_b32_e32 v47, 0
	v_mov_b32_e32 v48, 0
	v_mov_b32_e32 v49, 0
	v_mov_b32_e32 v50, 0
	v_mov_b32_e32 v51, 0
	v_mov_b32_e32 v52, 0
	v_mov_b32_e32 v53, 0
	v_mov_b32_e32 v54, 0
	v_mov_b32_e32 v55, 0
	v_mov_b32_e32 v56, 0
	v_mov_b32_e32 v57, 0
	v_mov_b32_e32 v58, 0
	v_mov_b32_e32 v59, 0
	v_mov_b32_e32 v60, 0
	v_mov_b32_e32 v61, 0
	v_mov_b32_e32 v62, 0
	v_mov_b32_e32 v63, 0
	v_mov_b32_e32 v64, 0
	v_mov_b32_e32 v65, 0
	v_mov_b32_e32 v66, 0
	v_mov_b32_e32 v67, 0
	v_mov_b32_e32 v68, 0
	v_mov_b32_e32 v69, 0
	v_mov_b32_e32 v70, 0
	v_mov_b32_e32 v71, 0
	v_mov_b32_e32 v72, 0
	v_mov_b32_e32 v73, 0
	v_mov_b32_e32 v74, 0
	v_mov_b32_e32 v75, 0
	v_mov_b32_e32 v76, 0
	v_mov_b32_e32 v77, 0
	v_mov_b32_e32 v78, 0
	v_mov_b32_e32 v79, 0
	v_mov_b32_e32 v80, 0
	v_mov_b32_e32 v81, 0
	v_mov_b32_e32 v82, 0
	v_mov_b32_e32 v83, 0
	v_mov_b32_e32 v84, 0
	v_mov_b32_e32 v85, 0
	v_mov_b32_e32 v86, 0
	v_mov_b32_e32 v87, 0
	v_mov_b32_e32 v88, 0
	v_mov_b32_e32 v89, 0
	v_mov_b32_e32 v90, 0
	v_mov_b32_e32 v91, 0
	v_mov_b32_e32 v92, 0
	v_mov_b32_e32 v93, 0
	v_mov_b32_e32 v94, 0
	v_mov_b32_e32 v95, 0
	v_mov_b32_e32 v96, 0
	v_mov_b32_e32 v97, 0
	v_mov_b32_e32 v98, 0
	v_mov_b32_e32 v99, 0
	v_mov_b32_e32 v100, 0
	v_mov_b32_e32 v101, 0
	v_mov_b32_e32 v102, 0
	v_mov_b32_e32 v103, 0
	v_mov_b32_e32 v104, 0
	v_mov_b32_e32 v105, 0
	v_mov_b32_e32 v106, 0
	v_mov_b32_e32 v107, 0
	v_mov_b32_e32 v108, 0
	v_mov_b32_e32 v109, 0
	v_mov_b32_e32 v110, 0
	v_mov_b32_e32 v111, 0
	v_mov_b32_e32 v112, 0
	v_mov_b32_e32 v113, 0
	v_mov_b32_e32 v114, 0
	v_mov_b32_e32 v115, 0
	v_mov_b32_e32 v116, 0
	v_mov_b32_e32 v117, 0
	v_mov_b32_e32 v118, 0
	v_mov_b32_e32 v119, 0
	v_mov_b32_e32 v120, 0
	v_mov_b32_e32 v121, 0
	v_mov_b32_e32 v122, 0
	v_mov_b32_e32 v123, 0
	v_mov_b32_e32 v124, 0
	v_mov_b32_e32 v125, 0
	v_mov_b32_e32 v126, 0
	v_mov_b32_e32 v127, 0
	v_mov_b32_e32 v128, 0
	v_mov_b32_e32 v129, 0
	s_barrier
;     ...
;   __syncthreads();
;   G2_STAGE(0); G2_STAGE(1);
;   const int fsw = (0x78 >> (((r16 >> 2) & 3) * 2)) & 3;
;   const int aoff = (wm * 128 + r16) * 64 + ((quad ^ fsw) << 4);
;   const int boff = 16384 + (wn * 64 + r16) * 64 + ((quad ^ fsw) << 4);
;   for (int kt = 0; kt < nk; kt++) {
;     if (kt + 1 < nk) asm volatile("s_waitcnt vmcnt(6)" ::: "memory");
;     else asm volatile("s_waitcnt vmcnt(0)" ::: "memory");
;     __builtin_amdgcn_s_barrier();
;     asm volatile("" ::: "memory");
;     if (kt + 2 < nk) G2_STAGE(kt + 2);
;     const char* cS = smem + (kt % 3) * 24576;
;     bf16x8 xa[8], wb[4];
; #pragma unroll
;     for (int f = 0; f < 8; f++) xa[f] = *(const bf16x8*)(cS + aoff + f * 1024);
; #pragma unroll
;     for (int f = 0; f < 4; f++) wb[f] = *(const bf16x8*)(cS + boff + f * 1024);
; #pragma unroll
;     for (int nf = 0; nf < 4; nf++)
; #pragma unroll
;       for (int mf = 0; mf < 8; mf++)
;         acc[nf][mf] = __builtin_amdgcn_mfma_f32_16x16x32_bf16(wb[nf], xa[mf], acc[nf][mf], 0, 0, 0);
;   }
	s_add_i32 s15, s43, 0x0
	s_mov_b32 m0, s15
	v_lshl_add_u64 v[142:143], v[132:133], 0, s[2:3]
	global_load_lds_dwordx4 v[132:133], off
	s_addk_i32 m0, 0x1000
	s_nop 0
	global_load_lds_dwordx4 v[142:143], off
	v_lshl_add_u64 v[142:143], v[142:143], 0, s[2:3]
	s_addk_i32 m0, 0x1000
	s_nop 0
	global_load_lds_dwordx4 v[142:143], off
	v_lshl_add_u64 v[142:143], v[142:143], 0, s[2:3]
	s_addk_i32 m0, 0x1000
	s_nop 0
	global_load_lds_dwordx4 v[142:143], off
	s_addk_i32 m0, 0x1000
	v_lshl_add_u64 v[142:143], v[134:135], 0, s[2:3]
	s_nop 0
	global_load_lds_dwordx4 v[134:135], off
	s_addk_i32 m0, 0x1000
	v_lshl_add_u64 v[132:133], v[132:133], 0, s[12:13]
	s_nop 0
	global_load_lds_dwordx4 v[142:143], off
	v_lshl_add_u64 v[134:135], v[134:135], 0, s[4:5]
	s_nop 0
	s_add_i32 s15, s43, 0x6000
	s_mov_b32 m0, s15
	v_lshl_add_u64 v[142:143], v[132:133], 0, s[2:3]
	global_load_lds_dwordx4 v[132:133], off
	s_addk_i32 m0, 0x1000
	s_nop 0
	global_load_lds_dwordx4 v[142:143], off
	v_lshl_add_u64 v[142:143], v[142:143], 0, s[2:3]
	s_addk_i32 m0, 0x1000
	s_nop 0
	global_load_lds_dwordx4 v[142:143], off
	v_lshl_add_u64 v[142:143], v[142:143], 0, s[2:3]
	s_addk_i32 m0, 0x1000
	s_nop 0
	global_load_lds_dwordx4 v[142:143], off
	s_addk_i32 m0, 0x1000
	v_lshl_add_u64 v[142:143], v[134:135], 0, s[2:3]
	s_nop 0
	global_load_lds_dwordx4 v[134:135], off
	s_addk_i32 m0, 0x1000
	v_lshl_add_u64 v[132:133], v[132:133], 0, s[12:13]
	s_nop 0
	global_load_lds_dwordx4 v[142:143], off
	v_lshl_add_u64 v[134:135], v[134:135], 0, s[4:5]
	s_nop 0
	s_add_i32 s15, s43, 0xc000
	s_mov_b32 m0, s15
	v_lshl_add_u64 v[142:143], v[132:133], 0, s[2:3]
	global_load_lds_dwordx4 v[132:133], off
	s_addk_i32 m0, 0x1000
	s_nop 0
	global_load_lds_dwordx4 v[142:143], off
	v_lshl_add_u64 v[142:143], v[142:143], 0, s[2:3]
	s_addk_i32 m0, 0x1000
	s_nop 0
	global_load_lds_dwordx4 v[142:143], off
	v_lshl_add_u64 v[142:143], v[142:143], 0, s[2:3]
	s_addk_i32 m0, 0x1000
	s_nop 0
	global_load_lds_dwordx4 v[142:143], off
	s_addk_i32 m0, 0x1000
	v_lshl_add_u64 v[142:143], v[134:135], 0, s[2:3]
	s_nop 0
	global_load_lds_dwordx4 v[134:135], off
	s_addk_i32 m0, 0x1000
	v_lshl_add_u64 v[132:133], v[132:133], 0, s[12:13]
	s_nop 0
	global_load_lds_dwordx4 v[142:143], off
	v_lshl_add_u64 v[134:135], v[134:135], 0, s[4:5]
	s_nop 0
	s_waitcnt vmcnt(12)
	s_barrier
	ds_read_b128 v[146:149], v136 offset:0
	ds_read_b128 v[152:155], v136 offset:1024
	ds_read_b128 v[156:159], v136 offset:2048
	ds_read_b128 v[162:165], v136 offset:3072
	ds_read_b128 v[166:169], v136 offset:4096
	ds_read_b128 v[170:173], v136 offset:5120
	ds_read_b128 v[176:179], v136 offset:6144
	ds_read_b128 v[180:183], v136 offset:7168
	ds_read_b128 v[184:187], v137 offset:16384
	ds_read_b128 v[188:191], v137 offset:17408
	ds_read_b128 v[192:195], v137 offset:18432
	ds_read_b128 v[196:199], v137 offset:19456
	s_movk_i32 s1, 0x6000
	s_mov_b32 s14, 0
	s_waitcnt vmcnt(6) lgkmcnt(0)
	s_barrier
	v_add_u32_e32 v144, s1, v136
	v_mfma_f32_16x16x32_bf16 v[126:129], v[184:187], v[146:149], v[126:129]
	ds_read_b128 v[200:203], v144 offset:0
	v_mfma_f32_16x16x32_bf16 v[122:125], v[184:187], v[152:155], v[122:125]
	ds_read_b128 v[204:207], v144 offset:1024
	v_mfma_f32_16x16x32_bf16 v[118:121], v[184:187], v[156:159], v[118:121]
	ds_read_b128 v[208:211], v144 offset:2048
	v_mfma_f32_16x16x32_bf16 v[114:117], v[184:187], v[162:165], v[114:117]
	ds_read_b128 v[212:215], v144 offset:3072
	v_mfma_f32_16x16x32_bf16 v[110:113], v[184:187], v[166:169], v[110:113]
	ds_read_b128 v[216:219], v144 offset:4096
	v_mfma_f32_16x16x32_bf16 v[106:109], v[184:187], v[170:173], v[106:109]
	ds_read_b128 v[220:223], v144 offset:5120
	v_mfma_f32_16x16x32_bf16 v[102:105], v[184:187], v[176:179], v[102:105]
	ds_read_b128 v[224:227], v144 offset:6144
	v_mfma_f32_16x16x32_bf16 v[98:101], v[184:187], v[180:183], v[98:101]
	ds_read_b128 v[228:231], v144 offset:7168
	v_mfma_f32_16x16x32_bf16 v[94:97], v[188:191], v[146:149], v[94:97]
	v_add_u32_e32 v144, s1, v137
	v_mfma_f32_16x16x32_bf16 v[90:93], v[188:191], v[152:155], v[90:93]
	v_mfma_f32_16x16x32_bf16 v[86:89], v[188:191], v[156:159], v[86:89]
	ds_read_b128 v[232:235], v144 offset:16384
	v_mfma_f32_16x16x32_bf16 v[82:85], v[188:191], v[162:165], v[82:85]
	ds_read_b128 v[236:239], v144 offset:17408
	v_mfma_f32_16x16x32_bf16 v[78:81], v[188:191], v[166:169], v[78:81]
	ds_read_b128 v[240:243], v144 offset:18432
	v_mfma_f32_16x16x32_bf16 v[74:77], v[188:191], v[170:173], v[74:77]
	ds_read_b128 v[244:247], v144 offset:19456
	s_add_i32 s15, s43, s14
	v_mfma_f32_16x16x32_bf16 v[70:73], v[188:191], v[176:179], v[70:73]
	s_mov_b32 m0, s15
	v_lshl_add_u64 v[142:143], v[132:133], 0, s[2:3]
	v_mfma_f32_16x16x32_bf16 v[66:69], v[188:191], v[180:183], v[66:69]
	global_load_lds_dwordx4 v[132:133], off
	s_addk_i32 m0, 0x1000
	v_mfma_f32_16x16x32_bf16 v[62:65], v[192:195], v[146:149], v[62:65]
	v_mfma_f32_16x16x32_bf16 v[58:61], v[192:195], v[152:155], v[58:61]
	v_mfma_f32_16x16x32_bf16 v[54:57], v[192:195], v[156:159], v[54:57]
	global_load_lds_dwordx4 v[142:143], off
	v_lshl_add_u64 v[142:143], v[142:143], 0, s[2:3]
	s_addk_i32 m0, 0x1000
	v_mfma_f32_16x16x32_bf16 v[50:53], v[192:195], v[162:165], v[50:53]
	v_mfma_f32_16x16x32_bf16 v[46:49], v[192:195], v[166:169], v[46:49]
	v_mfma_f32_16x16x32_bf16 v[42:45], v[192:195], v[170:173], v[42:45]
	global_load_lds_dwordx4 v[142:143], off
	v_lshl_add_u64 v[142:143], v[142:143], 0, s[2:3]
	s_addk_i32 m0, 0x1000
	v_mfma_f32_16x16x32_bf16 v[38:41], v[192:195], v[176:179], v[38:41]
	v_mfma_f32_16x16x32_bf16 v[34:37], v[192:195], v[180:183], v[34:37]
	v_mfma_f32_16x16x32_bf16 v[30:33], v[196:199], v[146:149], v[30:33]
	global_load_lds_dwordx4 v[142:143], off
	s_addk_i32 m0, 0x1000
	v_lshl_add_u64 v[142:143], v[134:135], 0, s[2:3]
	v_mfma_f32_16x16x32_bf16 v[26:29], v[196:199], v[152:155], v[26:29]
	v_mfma_f32_16x16x32_bf16 v[22:25], v[196:199], v[156:159], v[22:25]
	v_mfma_f32_16x16x32_bf16 v[18:21], v[196:199], v[162:165], v[18:21]
	global_load_lds_dwordx4 v[134:135], off
	s_addk_i32 m0, 0x1000
	v_lshl_add_u64 v[132:133], v[132:133], 0, s[12:13]
	v_mfma_f32_16x16x32_bf16 v[14:17], v[196:199], v[166:169], v[14:17]
	v_mfma_f32_16x16x32_bf16 v[10:13], v[196:199], v[170:173], v[10:13]
	v_mfma_f32_16x16x32_bf16 v[6:9], v[196:199], v[176:179], v[6:9]
	global_load_lds_dwordx4 v[142:143], off
	v_lshl_add_u64 v[134:135], v[134:135], 0, s[4:5]
	v_mfma_f32_16x16x32_bf16 v[2:5], v[196:199], v[180:183], v[2:5]
	s_mov_b32 s14, s1
	s_add_i32 s1, s1, 0x6000
	s_cmp_eq_u32 s1, 0x12000
	s_cselect_b32 s1, 0, s1
	s_waitcnt vmcnt(6) lgkmcnt(0)
	s_barrier
;     ...
;   for (int kt = 0; kt < nk; kt++) {
;     if (kt + 1 < nk) asm volatile("s_waitcnt vmcnt(6)" ::: "memory");
;     else asm volatile("s_waitcnt vmcnt(0)" ::: "memory");
;     __builtin_amdgcn_s_barrier();
;     asm volatile("" ::: "memory");
;     if (kt + 2 < nk) G2_STAGE(kt + 2);
;     const char* cS = smem + (kt % 3) * 24576;
;     bf16x8 xa[8], wb[4];
; #pragma unroll
;     for (int f = 0; f < 8; f++) xa[f] = *(const bf16x8*)(cS + aoff + f * 1024);
; #pragma unroll
;     for (int f = 0; f < 4; f++) wb[f] = *(const bf16x8*)(cS + boff + f * 1024);
; #pragma unroll
;     for (int nf = 0; nf < 4; nf++)
; #pragma unroll
;       for (int mf = 0; mf < 8; mf++)
;         acc[nf][mf] = __builtin_amdgcn_mfma_f32_16x16x32_bf16(wb[nf], xa[mf], acc[nf][mf], 0, 0, 0);
;   }
	v_add_u32_e32 v144, s1, v136
	v_mfma_f32_16x16x32_bf16 v[126:129], v[232:235], v[200:203], v[126:129]
	ds_read_b128 v[146:149], v144 offset:0
	v_mfma_f32_16x16x32_bf16 v[122:125], v[232:235], v[204:207], v[122:125]
	ds_read_b128 v[152:155], v144 offset:1024
	v_mfma_f32_16x16x32_bf16 v[118:121], v[232:235], v[208:211], v[118:121]
	ds_read_b128 v[156:159], v144 offset:2048
	v_mfma_f32_16x16x32_bf16 v[114:117], v[232:235], v[212:215], v[114:117]
	ds_read_b128 v[162:165], v144 offset:3072
	v_mfma_f32_16x16x32_bf16 v[110:113], v[232:235], v[216:219], v[110:113]
	ds_read_b128 v[166:169], v144 offset:4096
	v_mfma_f32_16x16x32_bf16 v[106:109], v[232:235], v[220:223], v[106:109]
	ds_read_b128 v[170:173], v144 offset:5120
	v_mfma_f32_16x16x32_bf16 v[102:105], v[232:235], v[224:227], v[102:105]
	ds_read_b128 v[176:179], v144 offset:6144
	v_mfma_f32_16x16x32_bf16 v[98:101], v[232:235], v[228:231], v[98:101]
	ds_read_b128 v[180:183], v144 offset:7168
	v_mfma_f32_16x16x32_bf16 v[94:97], v[236:239], v[200:203], v[94:97]
	v_add_u32_e32 v144, s1, v137
	v_mfma_f32_16x16x32_bf16 v[90:93], v[236:239], v[204:207], v[90:93]
	v_mfma_f32_16x16x32_bf16 v[86:89], v[236:239], v[208:211], v[86:89]
	ds_read_b128 v[184:187], v144 offset:16384
	v_mfma_f32_16x16x32_bf16 v[82:85], v[236:239], v[212:215], v[82:85]
	ds_read_b128 v[188:191], v144 offset:17408
	v_mfma_f32_16x16x32_bf16 v[78:81], v[236:239], v[216:219], v[78:81]
	ds_read_b128 v[192:195], v144 offset:18432
	v_mfma_f32_16x16x32_bf16 v[74:77], v[236:239], v[220:223], v[74:77]
	ds_read_b128 v[196:199], v144 offset:19456
	v_mfma_f32_16x16x32_bf16 v[70:73], v[236:239], v[224:227], v[70:73]
	v_mfma_f32_16x16x32_bf16 v[66:69], v[236:239], v[228:231], v[66:69]
	v_mfma_f32_16x16x32_bf16 v[62:65], v[240:243], v[200:203], v[62:65]
	v_mfma_f32_16x16x32_bf16 v[58:61], v[240:243], v[204:207], v[58:61]
	v_mfma_f32_16x16x32_bf16 v[54:57], v[240:243], v[208:211], v[54:57]
	v_mfma_f32_16x16x32_bf16 v[50:53], v[240:243], v[212:215], v[50:53]
	v_mfma_f32_16x16x32_bf16 v[46:49], v[240:243], v[216:219], v[46:49]
	v_mfma_f32_16x16x32_bf16 v[42:45], v[240:243], v[220:223], v[42:45]
	v_mfma_f32_16x16x32_bf16 v[38:41], v[240:243], v[224:227], v[38:41]
	v_mfma_f32_16x16x32_bf16 v[34:37], v[240:243], v[228:231], v[34:37]
	v_mfma_f32_16x16x32_bf16 v[30:33], v[244:247], v[200:203], v[30:33]
	v_mfma_f32_16x16x32_bf16 v[26:29], v[244:247], v[204:207], v[26:29]
	v_mfma_f32_16x16x32_bf16 v[22:25], v[244:247], v[208:211], v[22:25]
	v_mfma_f32_16x16x32_bf16 v[18:21], v[244:247], v[212:215], v[18:21]
	v_mfma_f32_16x16x32_bf16 v[14:17], v[244:247], v[216:219], v[14:17]
	v_mfma_f32_16x16x32_bf16 v[10:13], v[244:247], v[220:223], v[10:13]
	v_mfma_f32_16x16x32_bf16 v[6:9], v[244:247], v[224:227], v[6:9]
	v_mfma_f32_16x16x32_bf16 v[2:5], v[244:247], v[228:231], v[2:5]
	s_mov_b32 s14, s1
	s_add_i32 s1, s1, 0x6000
	s_cmp_eq_u32 s1, 0x12000
	s_cselect_b32 s1, 0, s1
	s_waitcnt vmcnt(0) lgkmcnt(0)
	s_barrier
	v_add_u32_e32 v144, s1, v136
	v_mfma_f32_16x16x32_bf16 v[126:129], v[184:187], v[146:149], v[126:129]
	ds_read_b128 v[200:203], v144 offset:0
	v_mfma_f32_16x16x32_bf16 v[122:125], v[184:187], v[152:155], v[122:125]
	ds_read_b128 v[204:207], v144 offset:1024
	v_mfma_f32_16x16x32_bf16 v[118:121], v[184:187], v[156:159], v[118:121]
	ds_read_b128 v[208:211], v144 offset:2048
	v_mfma_f32_16x16x32_bf16 v[114:117], v[184:187], v[162:165], v[114:117]
	ds_read_b128 v[212:215], v144 offset:3072
	v_mfma_f32_16x16x32_bf16 v[110:113], v[184:187], v[166:169], v[110:113]
	ds_read_b128 v[216:219], v144 offset:4096
	v_mfma_f32_16x16x32_bf16 v[106:109], v[184:187], v[170:173], v[106:109]
	ds_read_b128 v[220:223], v144 offset:5120
	v_mfma_f32_16x16x32_bf16 v[102:105], v[184:187], v[176:179], v[102:105]
	ds_read_b128 v[224:227], v144 offset:6144
	v_mfma_f32_16x16x32_bf16 v[98:101], v[184:187], v[180:183], v[98:101]
	ds_read_b128 v[228:231], v144 offset:7168
	v_mfma_f32_16x16x32_bf16 v[94:97], v[188:191], v[146:149], v[94:97]
	v_add_u32_e32 v144, s1, v137
	v_mfma_f32_16x16x32_bf16 v[90:93], v[188:191], v[152:155], v[90:93]
	v_mfma_f32_16x16x32_bf16 v[86:89], v[188:191], v[156:159], v[86:89]
	ds_read_b128 v[232:235], v144 offset:16384
	v_mfma_f32_16x16x32_bf16 v[82:85], v[188:191], v[162:165], v[82:85]
	ds_read_b128 v[236:239], v144 offset:17408
	v_mfma_f32_16x16x32_bf16 v[78:81], v[188:191], v[166:169], v[78:81]
	ds_read_b128 v[240:243], v144 offset:18432
	v_mfma_f32_16x16x32_bf16 v[74:77], v[188:191], v[170:173], v[74:77]
	ds_read_b128 v[244:247], v144 offset:19456
	v_mfma_f32_16x16x32_bf16 v[70:73], v[188:191], v[176:179], v[70:73]
	v_mfma_f32_16x16x32_bf16 v[66:69], v[188:191], v[180:183], v[66:69]
	v_mfma_f32_16x16x32_bf16 v[62:65], v[192:195], v[146:149], v[62:65]
	v_mfma_f32_16x16x32_bf16 v[58:61], v[192:195], v[152:155], v[58:61]
	v_mfma_f32_16x16x32_bf16 v[54:57], v[192:195], v[156:159], v[54:57]
	v_mfma_f32_16x16x32_bf16 v[50:53], v[192:195], v[162:165], v[50:53]
	v_mfma_f32_16x16x32_bf16 v[46:49], v[192:195], v[166:169], v[46:49]
	v_mfma_f32_16x16x32_bf16 v[42:45], v[192:195], v[170:173], v[42:45]
	v_mfma_f32_16x16x32_bf16 v[38:41], v[192:195], v[176:179], v[38:41]
	v_mfma_f32_16x16x32_bf16 v[34:37], v[192:195], v[180:183], v[34:37]
	v_mfma_f32_16x16x32_bf16 v[30:33], v[196:199], v[146:149], v[30:33]
	v_mfma_f32_16x16x32_bf16 v[26:29], v[196:199], v[152:155], v[26:29]
	v_mfma_f32_16x16x32_bf16 v[22:25], v[196:199], v[156:159], v[22:25]
	v_mfma_f32_16x16x32_bf16 v[18:21], v[196:199], v[162:165], v[18:21]
	v_mfma_f32_16x16x32_bf16 v[14:17], v[196:199], v[166:169], v[14:17]
	v_mfma_f32_16x16x32_bf16 v[10:13], v[196:199], v[170:173], v[10:13]
	v_mfma_f32_16x16x32_bf16 v[6:9], v[196:199], v[176:179], v[6:9]
	v_mfma_f32_16x16x32_bf16 v[2:5], v[196:199], v[180:183], v[2:5]
	s_mov_b32 s14, s1
	s_add_i32 s1, s1, 0x6000
	s_cmp_eq_u32 s1, 0x12000
	s_cselect_b32 s1, 0, s1
	s_mov_b32 s4, 0x8000
	s_mov_b32 s5, 0
	s_mov_b32 s10, 0x10000
	s_mov_b32 s11, 0
	s_mov_b32 s41, 0x3fd744fd
	s_waitcnt lgkmcnt(0)
; DEVI unsigned pack2(float a, float b) { return __builtin_bit_cast(unsigned, __builtin_convertvector((f32x2_t){a, b}, bf16x2_t)); }
; DEVI float blo(unsigned u) { return __uint_as_float(u << 16); }
; DEVI float bhi(unsigned u) { return __uint_as_float(u & 0xffff0000u); }
; DEVI float siluf_(float x) { return x * __builtin_amdgcn_rcpf(1.f + __expf(-x)); }
;     ...
;     for (int nf = 0; nf < 4; nf++)
; #pragma unroll
;       for (int mf = 0; mf < 8; mf++)
;         acc[nf][mf] = __builtin_amdgcn_mfma_f32_16x16x32_bf16(wb[nf], xa[mf], acc[nf][mf], 0, 0, 0);
;   }
;     ...
; #pragma unroll
;   for (int mf = 0; mf < 8; mf++) {
;     const int row = m0 + wm * 128 + mf * 16 + r16;
;     if (EPI == EPI_SWIGLU) {
; #pragma unroll
;       for (int nf = 0; nf < 2; nf++) {
;         const int hcol = (n0 >> 1) + wn * 32 + nf * 16 + quad * 4;
;         f32x4 g = acc[nf][mf], u = acc[nf + 2][mf];
;         u32x2 pk;
;         pk[0] = pack2(siluf_(g[0]) * u[0], siluf_(g[1]) * u[1]);
;         pk[1] = pack2(siluf_(g[2]) * u[2], siluf_(g[3]) * u[3]);
;         *(u32x2*)(outb + (size_t)row * DFF + hcol) = pk;
;       }
;     } else {
; #pragma unroll
;       for (int nf = 0; nf < 4; nf++) {
;         const int col = n0 + wn * 64 + nf * 16 + quad * 4;
;         f32x4 a = acc[nf][mf];
;         if (EPI == EPI_RESID || EPI == EPI_RESID_ATOMIC) {
;           f32x4 x = a;
;           if (EPI == EPI_RESID || kpart == 0) {
;             const u32x2 xr = *(const u32x2*)((const u16*)(p.ws + WS_XB) + (size_t)row * 1024 + col);
;             x[0] += ALPHA * blo(xr[0]); x[1] += ALPHA * bhi(xr[0]); x[2] += ALPHA * blo(xr[1]); x[3] += ALPHA * bhi(xr[1]);
;           }
;           if (EPI == EPI_RESID) *(f32x4*)((float*)(p.ws + WS_XF) + (size_t)row * 1024 + col) = x;
;           else *(f32x4*)((float*)(p.ws + WS_SLAB) + ((size_t)kpart * 512 + (row - T_P)) * 1024 + col) = x;
	v_mfma_f32_16x16x32_bf16 v[126:129], v[232:235], v[200:203], v[126:129]
	v_mfma_f32_16x16x32_bf16 v[122:125], v[232:235], v[204:207], v[122:125]
	v_mfma_f32_16x16x32_bf16 v[118:121], v[232:235], v[208:211], v[118:121]
	v_mfma_f32_16x16x32_bf16 v[114:117], v[232:235], v[212:215], v[114:117]
	v_mfma_f32_16x16x32_bf16 v[110:113], v[232:235], v[216:219], v[110:113]
	v_mfma_f32_16x16x32_bf16 v[106:109], v[232:235], v[220:223], v[106:109]
	v_mfma_f32_16x16x32_bf16 v[102:105], v[232:235], v[224:227], v[102:105]
	v_mfma_f32_16x16x32_bf16 v[98:101], v[232:235], v[228:231], v[98:101]
	v_mfma_f32_16x16x32_bf16 v[94:97], v[236:239], v[200:203], v[94:97]
	v_mfma_f32_16x16x32_bf16 v[90:93], v[236:239], v[204:207], v[90:93]
	v_mfma_f32_16x16x32_bf16 v[86:89], v[236:239], v[208:211], v[86:89]
	v_mfma_f32_16x16x32_bf16 v[82:85], v[236:239], v[212:215], v[82:85]
	v_mfma_f32_16x16x32_bf16 v[78:81], v[236:239], v[216:219], v[78:81]
	v_mfma_f32_16x16x32_bf16 v[74:77], v[236:239], v[220:223], v[74:77]
	v_mfma_f32_16x16x32_bf16 v[70:73], v[236:239], v[224:227], v[70:73]
	v_mfma_f32_16x16x32_bf16 v[66:69], v[236:239], v[228:231], v[66:69]
	v_mfma_f32_16x16x32_bf16 v[62:65], v[240:243], v[200:203], v[62:65]
	v_mfma_f32_16x16x32_bf16 v[58:61], v[240:243], v[204:207], v[58:61]
	v_mfma_f32_16x16x32_bf16 v[54:57], v[240:243], v[208:211], v[54:57]
	v_mfma_f32_16x16x32_bf16 v[50:53], v[240:243], v[212:215], v[50:53]
	v_mfma_f32_16x16x32_bf16 v[46:49], v[240:243], v[216:219], v[46:49]
	v_mfma_f32_16x16x32_bf16 v[42:45], v[240:243], v[220:223], v[42:45]
	v_mfma_f32_16x16x32_bf16 v[38:41], v[240:243], v[224:227], v[38:41]
	v_mfma_f32_16x16x32_bf16 v[34:37], v[240:243], v[228:231], v[34:37]
	v_mfma_f32_16x16x32_bf16 v[30:33], v[244:247], v[200:203], v[30:33]
	v_mfma_f32_16x16x32_bf16 v[26:29], v[244:247], v[204:207], v[26:29]
	v_mfma_f32_16x16x32_bf16 v[22:25], v[244:247], v[208:211], v[22:25]
	v_mfma_f32_16x16x32_bf16 v[18:21], v[244:247], v[212:215], v[18:21]
	v_mfma_f32_16x16x32_bf16 v[14:17], v[244:247], v[216:219], v[14:17]
	v_mfma_f32_16x16x32_bf16 v[10:13], v[244:247], v[220:223], v[10:13]
	v_mfma_f32_16x16x32_bf16 v[6:9], v[244:247], v[224:227], v[6:9]
	v_mfma_f32_16x16x32_bf16 v[2:5], v[244:247], v[228:231], v[2:5]
	s_mov_b32 m0, s40
	s_cmp_eq_u32 s98, 0
	s_cbranch_scc1 .Lta4_first
	s_nop 7
	global_store_dwordx4 v[140:141], v[126:129], off offset:0
	global_store_dwordx4 v[140:141], v[94:97], off offset:64
	global_store_dwordx4 v[140:141], v[62:65], off offset:128
	global_store_dwordx4 v[140:141], v[30:33], off offset:192
	v_lshl_add_u64 v[140:141], v[140:141], 0, s[10:11]
	global_store_dwordx4 v[140:141], v[122:125], off offset:0
	global_store_dwordx4 v[140:141], v[90:93], off offset:64
	global_store_dwordx4 v[140:141], v[58:61], off offset:128
	global_store_dwordx4 v[140:141], v[26:29], off offset:192
	v_lshl_add_u64 v[140:141], v[140:141], 0, s[10:11]
	global_store_dwordx4 v[140:141], v[118:121], off offset:0
	global_store_dwordx4 v[140:141], v[86:89], off offset:64
	global_store_dwordx4 v[140:141], v[54:57], off offset:128
	global_store_dwordx4 v[140:141], v[22:25], off offset:192
	v_lshl_add_u64 v[140:141], v[140:141], 0, s[10:11]
	global_store_dwordx4 v[140:141], v[114:117], off offset:0
	global_store_dwordx4 v[140:141], v[82:85], off offset:64
	global_store_dwordx4 v[140:141], v[50:53], off offset:128
	global_store_dwordx4 v[140:141], v[18:21], off offset:192
	v_lshl_add_u64 v[140:141], v[140:141], 0, s[10:11]
	global_store_dwordx4 v[140:141], v[110:113], off offset:0
	global_store_dwordx4 v[140:141], v[78:81], off offset:64
	global_store_dwordx4 v[140:141], v[46:49], off offset:128
	global_store_dwordx4 v[140:141], v[14:17], off offset:192
	v_lshl_add_u64 v[140:141], v[140:141], 0, s[10:11]
	global_store_dwordx4 v[140:141], v[106:109], off offset:0
	global_store_dwordx4 v[140:141], v[74:77], off offset:64
	global_store_dwordx4 v[140:141], v[42:45], off offset:128
	global_store_dwordx4 v[140:141], v[10:13], off offset:192
	v_lshl_add_u64 v[140:141], v[140:141], 0, s[10:11]
	global_store_dwordx4 v[140:141], v[102:105], off offset:0
	global_store_dwordx4 v[140:141], v[70:73], off offset:64
	global_store_dwordx4 v[140:141], v[38:41], off offset:128
	global_store_dwordx4 v[140:141], v[6:9], off offset:192
	v_lshl_add_u64 v[140:141], v[140:141], 0, s[10:11]
	global_store_dwordx4 v[140:141], v[98:101], off offset:0
	global_store_dwordx4 v[140:141], v[66:69], off offset:64
	global_store_dwordx4 v[140:141], v[34:37], off offset:128
	global_store_dwordx4 v[140:141], v[2:5], off offset:192
	s_branch .LBB0_757
; DEVI float blo(unsigned u) { return __uint_as_float(u << 16); }
; DEVI float bhi(unsigned u) { return __uint_as_float(u & 0xffff0000u); }
;     ...
;         if (EPI == EPI_RESID || EPI == EPI_RESID_ATOMIC) {
;           f32x4 x = a;
;           if (EPI == EPI_RESID || kpart == 0) {
;             const u32x2 xr = *(const u32x2*)((const u16*)(p.ws + WS_XB) + (size_t)row * 1024 + col);
;             x[0] += ALPHA * blo(xr[0]); x[1] += ALPHA * bhi(xr[0]); x[2] += ALPHA * blo(xr[1]); x[3] += ALPHA * bhi(xr[1]);
;           }
;           if (EPI == EPI_RESID) *(f32x4*)((float*)(p.ws + WS_XF) + (size_t)row * 1024 + col) = x;
;           else *(f32x4*)((float*)(p.ws + WS_SLAB) + ((size_t)kpart * 512 + (row - T_P)) * 1024 + col) = x;
.Lta4_first:
	global_load_dwordx2 v[146:147], v[138:139], off offset:0
	global_load_dwordx2 v[148:149], v[138:139], off offset:32
	global_load_dwordx2 v[152:153], v[138:139], off offset:64
	global_load_dwordx2 v[154:155], v[138:139], off offset:96
	v_lshl_add_u64 v[138:139], v[138:139], 0, s[4:5]
	global_load_dwordx2 v[156:157], v[138:139], off offset:0
	global_load_dwordx2 v[158:159], v[138:139], off offset:32
	global_load_dwordx2 v[162:163], v[138:139], off offset:64
	global_load_dwordx2 v[164:165], v[138:139], off offset:96
	v_lshl_add_u64 v[138:139], v[138:139], 0, s[4:5]
	global_load_dwordx2 v[166:167], v[138:139], off offset:0
	global_load_dwordx2 v[168:169], v[138:139], off offset:32
	global_load_dwordx2 v[170:171], v[138:139], off offset:64
	global_load_dwordx2 v[172:173], v[138:139], off offset:96
	v_lshl_add_u64 v[138:139], v[138:139], 0, s[4:5]
	global_load_dwordx2 v[176:177], v[138:139], off offset:0
	global_load_dwordx2 v[178:179], v[138:139], off offset:32
	global_load_dwordx2 v[180:181], v[138:139], off offset:64
	global_load_dwordx2 v[182:183], v[138:139], off offset:96
	v_lshl_add_u64 v[138:139], v[138:139], 0, s[4:5]
	global_load_dwordx2 v[184:185], v[138:139], off offset:0
	global_load_dwordx2 v[186:187], v[138:139], off offset:32
	global_load_dwordx2 v[188:189], v[138:139], off offset:64
	global_load_dwordx2 v[190:191], v[138:139], off offset:96
	v_lshl_add_u64 v[138:139], v[138:139], 0, s[4:5]
	global_load_dwordx2 v[192:193], v[138:139], off offset:0
	global_load_dwordx2 v[194:195], v[138:139], off offset:32
	global_load_dwordx2 v[196:197], v[138:139], off offset:64
	global_load_dwordx2 v[198:199], v[138:139], off offset:96
	v_lshl_add_u64 v[138:139], v[138:139], 0, s[4:5]
	global_load_dwordx2 v[200:201], v[138:139], off offset:0
	global_load_dwordx2 v[202:203], v[138:139], off offset:32
	global_load_dwordx2 v[204:205], v[138:139], off offset:64
	global_load_dwordx2 v[206:207], v[138:139], off offset:96
	v_lshl_add_u64 v[138:139], v[138:139], 0, s[4:5]
	global_load_dwordx2 v[208:209], v[138:139], off offset:0
	global_load_dwordx2 v[210:211], v[138:139], off offset:32
	global_load_dwordx2 v[212:213], v[138:139], off offset:64
	global_load_dwordx2 v[214:215], v[138:139], off offset:96
	v_lshl_add_u64 v[138:139], v[138:139], 0, s[4:5]
	s_nop 7
	s_waitcnt vmcnt(31)
	v_lshlrev_b32_e32 v216, 16, v146
	v_and_b32_e32 v146, 0xffff0000, v146
	v_lshlrev_b32_e32 v217, 16, v147
	v_and_b32_e32 v147, 0xffff0000, v147
	v_fmac_f32_e32 v126, s41, v216
	v_fmac_f32_e32 v127, s41, v146
	v_fmac_f32_e32 v128, s41, v217
	v_fmac_f32_e32 v129, s41, v147
	global_store_dwordx4 v[140:141], v[126:129], off offset:0
	s_waitcnt vmcnt(31)
	v_lshlrev_b32_e32 v216, 16, v148
	v_and_b32_e32 v148, 0xffff0000, v148
	v_lshlrev_b32_e32 v217, 16, v149
	v_and_b32_e32 v149, 0xffff0000, v149
	v_fmac_f32_e32 v94, s41, v216
	v_fmac_f32_e32 v95, s41, v148
	v_fmac_f32_e32 v96, s41, v217
	v_fmac_f32_e32 v97, s41, v149
	global_store_dwordx4 v[140:141], v[94:97], off offset:64
	s_waitcnt vmcnt(31)
	v_lshlrev_b32_e32 v216, 16, v152
	v_and_b32_e32 v152, 0xffff0000, v152
	v_lshlrev_b32_e32 v217, 16, v153
	v_and_b32_e32 v153, 0xffff0000, v153
	v_fmac_f32_e32 v62, s41, v216
	v_fmac_f32_e32 v63, s41, v152
	v_fmac_f32_e32 v64, s41, v217
	v_fmac_f32_e32 v65, s41, v153
	global_store_dwordx4 v[140:141], v[62:65], off offset:128
	s_waitcnt vmcnt(31)
	v_lshlrev_b32_e32 v216, 16, v154
	v_and_b32_e32 v154, 0xffff0000, v154
	v_lshlrev_b32_e32 v217, 16, v155
	v_and_b32_e32 v155, 0xffff0000, v155
	v_fmac_f32_e32 v30, s41, v216
	v_fmac_f32_e32 v31, s41, v154
	v_fmac_f32_e32 v32, s41, v217
	v_fmac_f32_e32 v33, s41, v155
	global_store_dwordx4 v[140:141], v[30:33], off offset:192
	v_lshl_add_u64 v[140:141], v[140:141], 0, s[10:11]
	s_waitcnt vmcnt(31)
	v_lshlrev_b32_e32 v216, 16, v156
	v_and_b32_e32 v156, 0xffff0000, v156
	v_lshlrev_b32_e32 v217, 16, v157
	v_and_b32_e32 v157, 0xffff0000, v157
	v_fmac_f32_e32 v122, s41, v216
	v_fmac_f32_e32 v123, s41, v156
	v_fmac_f32_e32 v124, s41, v217
	v_fmac_f32_e32 v125, s41, v157
	global_store_dwordx4 v[140:141], v[122:125], off offset:0
	s_waitcnt vmcnt(31)
	v_lshlrev_b32_e32 v216, 16, v158
	v_and_b32_e32 v158, 0xffff0000, v158
	v_lshlrev_b32_e32 v217, 16, v159
	v_and_b32_e32 v159, 0xffff0000, v159
	v_fmac_f32_e32 v90, s41, v216
	v_fmac_f32_e32 v91, s41, v158
	v_fmac_f32_e32 v92, s41, v217
	v_fmac_f32_e32 v93, s41, v159
	global_store_dwordx4 v[140:141], v[90:93], off offset:64
	s_waitcnt vmcnt(31)
	v_lshlrev_b32_e32 v216, 16, v162
	v_and_b32_e32 v162, 0xffff0000, v162
	v_lshlrev_b32_e32 v217, 16, v163
	v_and_b32_e32 v163, 0xffff0000, v163
	v_fmac_f32_e32 v58, s41, v216
	v_fmac_f32_e32 v59, s41, v162
	v_fmac_f32_e32 v60, s41, v217
	v_fmac_f32_e32 v61, s41, v163
	global_store_dwordx4 v[140:141], v[58:61], off offset:128
	s_waitcnt vmcnt(31)
	v_lshlrev_b32_e32 v216, 16, v164
	v_and_b32_e32 v164, 0xffff0000, v164
	v_lshlrev_b32_e32 v217, 16, v165
	v_and_b32_e32 v165, 0xffff0000, v165
	v_fmac_f32_e32 v26, s41, v216
	v_fmac_f32_e32 v27, s41, v164
	v_fmac_f32_e32 v28, s41, v217
	v_fmac_f32_e32 v29, s41, v165
	global_store_dwordx4 v[140:141], v[26:29], off offset:192
	v_lshl_add_u64 v[140:141], v[140:141], 0, s[10:11]
	s_waitcnt vmcnt(31)
	v_lshlrev_b32_e32 v216, 16, v166
	v_and_b32_e32 v166, 0xffff0000, v166
	v_lshlrev_b32_e32 v217, 16, v167
	v_and_b32_e32 v167, 0xffff0000, v167
	v_fmac_f32_e32 v118, s41, v216
	v_fmac_f32_e32 v119, s41, v166
	v_fmac_f32_e32 v120, s41, v217
	v_fmac_f32_e32 v121, s41, v167
	global_store_dwordx4 v[140:141], v[118:121], off offset:0
	s_waitcnt vmcnt(31)
; DEVI float blo(unsigned u) { return __uint_as_float(u << 16); }
; DEVI float bhi(unsigned u) { return __uint_as_float(u & 0xffff0000u); }
;     ...
;         if (EPI == EPI_RESID || EPI == EPI_RESID_ATOMIC) {
;           f32x4 x = a;
;           if (EPI == EPI_RESID || kpart == 0) {
;             const u32x2 xr = *(const u32x2*)((const u16*)(p.ws + WS_XB) + (size_t)row * 1024 + col);
;             x[0] += ALPHA * blo(xr[0]); x[1] += ALPHA * bhi(xr[0]); x[2] += ALPHA * blo(xr[1]); x[3] += ALPHA * bhi(xr[1]);
;           }
;           if (EPI == EPI_RESID) *(f32x4*)((float*)(p.ws + WS_XF) + (size_t)row * 1024 + col) = x;
;           else *(f32x4*)((float*)(p.ws + WS_SLAB) + ((size_t)kpart * 512 + (row - T_P)) * 1024 + col) = x;
	v_lshlrev_b32_e32 v216, 16, v168
	v_and_b32_e32 v168, 0xffff0000, v168
	v_lshlrev_b32_e32 v217, 16, v169
	v_and_b32_e32 v169, 0xffff0000, v169
	v_fmac_f32_e32 v86, s41, v216
	v_fmac_f32_e32 v87, s41, v168
	v_fmac_f32_e32 v88, s41, v217
	v_fmac_f32_e32 v89, s41, v169
	global_store_dwordx4 v[140:141], v[86:89], off offset:64
	s_waitcnt vmcnt(31)
	v_lshlrev_b32_e32 v216, 16, v170
	v_and_b32_e32 v170, 0xffff0000, v170
	v_lshlrev_b32_e32 v217, 16, v171
	v_and_b32_e32 v171, 0xffff0000, v171
	v_fmac_f32_e32 v54, s41, v216
	v_fmac_f32_e32 v55, s41, v170
	v_fmac_f32_e32 v56, s41, v217
	v_fmac_f32_e32 v57, s41, v171
	global_store_dwordx4 v[140:141], v[54:57], off offset:128
	s_waitcnt vmcnt(31)
	v_lshlrev_b32_e32 v216, 16, v172
	v_and_b32_e32 v172, 0xffff0000, v172
	v_lshlrev_b32_e32 v217, 16, v173
	v_and_b32_e32 v173, 0xffff0000, v173
	v_fmac_f32_e32 v22, s41, v216
	v_fmac_f32_e32 v23, s41, v172
	v_fmac_f32_e32 v24, s41, v217
	v_fmac_f32_e32 v25, s41, v173
	global_store_dwordx4 v[140:141], v[22:25], off offset:192
	v_lshl_add_u64 v[140:141], v[140:141], 0, s[10:11]
	s_waitcnt vmcnt(31)
	v_lshlrev_b32_e32 v216, 16, v176
	v_and_b32_e32 v176, 0xffff0000, v176
	v_lshlrev_b32_e32 v217, 16, v177
	v_and_b32_e32 v177, 0xffff0000, v177
	v_fmac_f32_e32 v114, s41, v216
	v_fmac_f32_e32 v115, s41, v176
	v_fmac_f32_e32 v116, s41, v217
	v_fmac_f32_e32 v117, s41, v177
	global_store_dwordx4 v[140:141], v[114:117], off offset:0
	s_waitcnt vmcnt(31)
	v_lshlrev_b32_e32 v216, 16, v178
	v_and_b32_e32 v178, 0xffff0000, v178
	v_lshlrev_b32_e32 v217, 16, v179
	v_and_b32_e32 v179, 0xffff0000, v179
	v_fmac_f32_e32 v82, s41, v216
	v_fmac_f32_e32 v83, s41, v178
	v_fmac_f32_e32 v84, s41, v217
	v_fmac_f32_e32 v85, s41, v179
	global_store_dwordx4 v[140:141], v[82:85], off offset:64
	s_waitcnt vmcnt(31)
	v_lshlrev_b32_e32 v216, 16, v180
	v_and_b32_e32 v180, 0xffff0000, v180
	v_lshlrev_b32_e32 v217, 16, v181
	v_and_b32_e32 v181, 0xffff0000, v181
	v_fmac_f32_e32 v50, s41, v216
	v_fmac_f32_e32 v51, s41, v180
	v_fmac_f32_e32 v52, s41, v217
	v_fmac_f32_e32 v53, s41, v181
	global_store_dwordx4 v[140:141], v[50:53], off offset:128
	s_waitcnt vmcnt(31)
	v_lshlrev_b32_e32 v216, 16, v182
	v_and_b32_e32 v182, 0xffff0000, v182
	v_lshlrev_b32_e32 v217, 16, v183
	v_and_b32_e32 v183, 0xffff0000, v183
	v_fmac_f32_e32 v18, s41, v216
	v_fmac_f32_e32 v19, s41, v182
	v_fmac_f32_e32 v20, s41, v217
	v_fmac_f32_e32 v21, s41, v183
	global_store_dwordx4 v[140:141], v[18:21], off offset:192
	v_lshl_add_u64 v[140:141], v[140:141], 0, s[10:11]
	s_waitcnt vmcnt(31)
	v_lshlrev_b32_e32 v216, 16, v184
	v_and_b32_e32 v184, 0xffff0000, v184
	v_lshlrev_b32_e32 v217, 16, v185
	v_and_b32_e32 v185, 0xffff0000, v185
	v_fmac_f32_e32 v110, s41, v216
	v_fmac_f32_e32 v111, s41, v184
	v_fmac_f32_e32 v112, s41, v217
	v_fmac_f32_e32 v113, s41, v185
	global_store_dwordx4 v[140:141], v[110:113], off offset:0
	s_waitcnt vmcnt(31)
	v_lshlrev_b32_e32 v216, 16, v186
	v_and_b32_e32 v186, 0xffff0000, v186
	v_lshlrev_b32_e32 v217, 16, v187
	v_and_b32_e32 v187, 0xffff0000, v187
	v_fmac_f32_e32 v78, s41, v216
	v_fmac_f32_e32 v79, s41, v186
	v_fmac_f32_e32 v80, s41, v217
	v_fmac_f32_e32 v81, s41, v187
	global_store_dwordx4 v[140:141], v[78:81], off offset:64
	s_waitcnt vmcnt(31)
	v_lshlrev_b32_e32 v216, 16, v188
	v_and_b32_e32 v188, 0xffff0000, v188
	v_lshlrev_b32_e32 v217, 16, v189
	v_and_b32_e32 v189, 0xffff0000, v189
	v_fmac_f32_e32 v46, s41, v216
	v_fmac_f32_e32 v47, s41, v188
	v_fmac_f32_e32 v48, s41, v217
	v_fmac_f32_e32 v49, s41, v189
	global_store_dwordx4 v[140:141], v[46:49], off offset:128
	s_waitcnt vmcnt(31)
	v_lshlrev_b32_e32 v216, 16, v190
	v_and_b32_e32 v190, 0xffff0000, v190
	v_lshlrev_b32_e32 v217, 16, v191
	v_and_b32_e32 v191, 0xffff0000, v191
	v_fmac_f32_e32 v14, s41, v216
	v_fmac_f32_e32 v15, s41, v190
	v_fmac_f32_e32 v16, s41, v217
	v_fmac_f32_e32 v17, s41, v191
	global_store_dwordx4 v[140:141], v[14:17], off offset:192
	v_lshl_add_u64 v[140:141], v[140:141], 0, s[10:11]
	s_waitcnt vmcnt(31)
	v_lshlrev_b32_e32 v216, 16, v192
	v_and_b32_e32 v192, 0xffff0000, v192
	v_lshlrev_b32_e32 v217, 16, v193
	v_and_b32_e32 v193, 0xffff0000, v193
	v_fmac_f32_e32 v106, s41, v216
	v_fmac_f32_e32 v107, s41, v192
	v_fmac_f32_e32 v108, s41, v217
	v_fmac_f32_e32 v109, s41, v193
	global_store_dwordx4 v[140:141], v[106:109], off offset:0
	s_waitcnt vmcnt(31)
	v_lshlrev_b32_e32 v216, 16, v194
	v_and_b32_e32 v194, 0xffff0000, v194
	v_lshlrev_b32_e32 v217, 16, v195
	v_and_b32_e32 v195, 0xffff0000, v195
	v_fmac_f32_e32 v74, s41, v216
	v_fmac_f32_e32 v75, s41, v194
	v_fmac_f32_e32 v76, s41, v217
	v_fmac_f32_e32 v77, s41, v195
	global_store_dwordx4 v[140:141], v[74:77], off offset:64
	s_waitcnt vmcnt(31)
	v_lshlrev_b32_e32 v216, 16, v196
	v_and_b32_e32 v196, 0xffff0000, v196
	v_lshlrev_b32_e32 v217, 16, v197
	v_and_b32_e32 v197, 0xffff0000, v197
	v_fmac_f32_e32 v42, s41, v216
	v_fmac_f32_e32 v43, s41, v196
	v_fmac_f32_e32 v44, s41, v217
	v_fmac_f32_e32 v45, s41, v197
	global_store_dwordx4 v[140:141], v[42:45], off offset:128
	s_waitcnt vmcnt(31)
	v_lshlrev_b32_e32 v216, 16, v198
	v_and_b32_e32 v198, 0xffff0000, v198
	v_lshlrev_b32_e32 v217, 16, v199
	v_and_b32_e32 v199, 0xffff0000, v199
	v_fmac_f32_e32 v10, s41, v216
	v_fmac_f32_e32 v11, s41, v198
	v_fmac_f32_e32 v12, s41, v217
	v_fmac_f32_e32 v13, s41, v199
	global_store_dwordx4 v[140:141], v[10:13], off offset:192
	v_lshl_add_u64 v[140:141], v[140:141], 0, s[10:11]
	s_waitcnt vmcnt(31)
	v_lshlrev_b32_e32 v216, 16, v200
	v_and_b32_e32 v200, 0xffff0000, v200
	v_lshlrev_b32_e32 v217, 16, v201
	v_and_b32_e32 v201, 0xffff0000, v201
	v_fmac_f32_e32 v102, s41, v216
	v_fmac_f32_e32 v103, s41, v200
	v_fmac_f32_e32 v104, s41, v217
	v_fmac_f32_e32 v105, s41, v201
	global_store_dwordx4 v[140:141], v[102:105], off offset:0
	s_waitcnt vmcnt(31)
; #define LAS __attribute__((address_space(3)))
; DEVI float blo(unsigned u) { return __uint_as_float(u << 16); }
; DEVI float bhi(unsigned u) { return __uint_as_float(u & 0xffff0000u); }
;     ...
;   const int nk = (nk_part < 0) ? (K >> 5) : nk_part;
;   const int lrow = tid >> 2, lpc = tid & 3;
;   const int lch = lpc ^ ((0x78 >> (((lrow >> 2) & 3) * 2)) & 3);
;   const u16* ga = A + (size_t)(m0 + lrow) * lda + kbeg + lch * 8;
;   const u16* gb = Bt + (size_t)(n0 + lrow) * K + kbeg + lch * 8;
;   const size_t ga1 = (size_t)64 * lda, gb1 = (size_t)64 * K;
;   const unsigned lds0 = (unsigned)(uintptr_t)(LAS char*)smem + (unsigned)__builtin_amdgcn_readfirstlane(wid) * 1024u;
;     ...
;   __syncthreads();
;   G2_STAGE(0); G2_STAGE(1);
;   const int fsw = (0x78 >> (((r16 >> 2) & 3) * 2)) & 3;
;   const int aoff = (wm * 128 + r16) * 64 + ((quad ^ fsw) << 4);
;   const int boff = 16384 + (wn * 64 + r16) * 64 + ((quad ^ fsw) << 4);
;     ...
;         if (EPI == EPI_RESID || EPI == EPI_RESID_ATOMIC) {
;           f32x4 x = a;
;           if (EPI == EPI_RESID || kpart == 0) {
;             const u32x2 xr = *(const u32x2*)((const u16*)(p.ws + WS_XB) + (size_t)row * 1024 + col);
;             x[0] += ALPHA * blo(xr[0]); x[1] += ALPHA * bhi(xr[0]); x[2] += ALPHA * blo(xr[1]); x[3] += ALPHA * bhi(xr[1]);
;           }
;           if (EPI == EPI_RESID) *(f32x4*)((float*)(p.ws + WS_XF) + (size_t)row * 1024 + col) = x;
;           else *(f32x4*)((float*)(p.ws + WS_SLAB) + ((size_t)kpart * 512 + (row - T_P)) * 1024 + col) = x;
	v_lshlrev_b32_e32 v216, 16, v202
	v_and_b32_e32 v202, 0xffff0000, v202
	v_lshlrev_b32_e32 v217, 16, v203
	v_and_b32_e32 v203, 0xffff0000, v203
	v_fmac_f32_e32 v70, s41, v216
	v_fmac_f32_e32 v71, s41, v202
	v_fmac_f32_e32 v72, s41, v217
	v_fmac_f32_e32 v73, s41, v203
	global_store_dwordx4 v[140:141], v[70:73], off offset:64
	s_waitcnt vmcnt(31)
	v_lshlrev_b32_e32 v216, 16, v204
	v_and_b32_e32 v204, 0xffff0000, v204
	v_lshlrev_b32_e32 v217, 16, v205
	v_and_b32_e32 v205, 0xffff0000, v205
	v_fmac_f32_e32 v38, s41, v216
	v_fmac_f32_e32 v39, s41, v204
	v_fmac_f32_e32 v40, s41, v217
	v_fmac_f32_e32 v41, s41, v205
	global_store_dwordx4 v[140:141], v[38:41], off offset:128
	s_waitcnt vmcnt(31)
	v_lshlrev_b32_e32 v216, 16, v206
	v_and_b32_e32 v206, 0xffff0000, v206
	v_lshlrev_b32_e32 v217, 16, v207
	v_and_b32_e32 v207, 0xffff0000, v207
	v_fmac_f32_e32 v6, s41, v216
	v_fmac_f32_e32 v7, s41, v206
	v_fmac_f32_e32 v8, s41, v217
	v_fmac_f32_e32 v9, s41, v207
	global_store_dwordx4 v[140:141], v[6:9], off offset:192
	v_lshl_add_u64 v[140:141], v[140:141], 0, s[10:11]
	s_waitcnt vmcnt(31)
	v_lshlrev_b32_e32 v216, 16, v208
	v_and_b32_e32 v208, 0xffff0000, v208
	v_lshlrev_b32_e32 v217, 16, v209
	v_and_b32_e32 v209, 0xffff0000, v209
	v_fmac_f32_e32 v98, s41, v216
	v_fmac_f32_e32 v99, s41, v208
	v_fmac_f32_e32 v100, s41, v217
	v_fmac_f32_e32 v101, s41, v209
	global_store_dwordx4 v[140:141], v[98:101], off offset:0
	s_waitcnt vmcnt(31)
	v_lshlrev_b32_e32 v216, 16, v210
	v_and_b32_e32 v210, 0xffff0000, v210
	v_lshlrev_b32_e32 v217, 16, v211
	v_and_b32_e32 v211, 0xffff0000, v211
	v_fmac_f32_e32 v66, s41, v216
	v_fmac_f32_e32 v67, s41, v210
	v_fmac_f32_e32 v68, s41, v217
	v_fmac_f32_e32 v69, s41, v211
	global_store_dwordx4 v[140:141], v[66:69], off offset:64
	s_waitcnt vmcnt(31)
	v_lshlrev_b32_e32 v216, 16, v212
	v_and_b32_e32 v212, 0xffff0000, v212
	v_lshlrev_b32_e32 v217, 16, v213
	v_and_b32_e32 v213, 0xffff0000, v213
	v_fmac_f32_e32 v34, s41, v216
	v_fmac_f32_e32 v35, s41, v212
	v_fmac_f32_e32 v36, s41, v217
	v_fmac_f32_e32 v37, s41, v213
	global_store_dwordx4 v[140:141], v[34:37], off offset:128
	s_waitcnt vmcnt(31)
	v_lshlrev_b32_e32 v216, 16, v214
	v_and_b32_e32 v214, 0xffff0000, v214
	v_lshlrev_b32_e32 v217, 16, v215
	v_and_b32_e32 v215, 0xffff0000, v215
	v_fmac_f32_e32 v2, s41, v216
	v_fmac_f32_e32 v3, s41, v214
	v_fmac_f32_e32 v4, s41, v217
	v_fmac_f32_e32 v5, s41, v215
	global_store_dwordx4 v[140:141], v[2:5], off offset:192
	s_branch .LBB0_757
.LBB0_812:
	s_and_b64 vcc, exec, s[2:3]
	s_cbranch_vccz .LBB0_757
	s_lshr_b32 s46, s39, 6
	s_and_b32 s47, s39, 63
	s_lshr_b32 s43, s47, 3
	s_and_b32 s47, s47, 7
	s_lshl_b32 s46, s46, 3
	s_add_i32 s46, s46, s47
	v_readlane_b32 s2, v250, 5
	v_readlane_b32 s3, v250, 6
	v_readlane_b32 s47, v254, 62
	s_mul_i32 s41, s46, 0x80000
	s_add_u32 s4, s2, s41
	s_addc_u32 s5, s3, 0
	s_add_u32 s4, s4, 0xb580000
	s_addc_u32 s5, s5, 0
	s_mul_i32 s41, s47, 0x200000
	s_mul_i32 s42, s43, 0x40000
	s_add_i32 s41, s41, s42
	s_add_u32 s10, s2, s41
	s_addc_u32 s11, s3, 0
	s_add_u32 s10, s10, 0x15e00000
	s_addc_u32 s11, s11, 0
	s_movk_i32 s40, 0x78
	v_lshrrev_b32_e32 v0, 2, v145
	v_and_b32_e32 v131, 3, v145
	v_bfe_u32 v136, v145, 4, 2
	v_lshlrev_b32_e32 v136, 1, v136
	v_lshrrev_b32_e64 v136, v136, s40
	v_and_b32_e32 v136, 3, v136
	v_xor_b32_e32 v131, v131, v136
	v_lshlrev_b32_e32 v131, 4, v131
	s_movk_i32 s42, 0x800
	v_mad_u32_u24 v0, v0, s42, v131
	v_bfe_u32 v137, v145, 2, 1
	s_movk_i32 s42, 0x7c0
	v_mul_u32_u24_e32 v136, s42, v137
	v_sub_u32_e32 v136, v0, v136
	v_mov_b32_e32 v137, 0
	v_lshl_add_u64 v[134:135], s[10:11], 0, v[136:137]
	v_bfe_u32 v137, v145, 2, 1
	s_mov_b32 s12, 64
	s_mov_b32 s13, 0
	v_lshl_add_u64 v[132:133], s[4:5], 0, v[0:1]
	v_bfe_u32 v136, v145, 2, 2
	v_lshlrev_b32_e32 v136, 1, v136
	v_lshrrev_b32_e64 v136, v136, s40
	v_and_b32_e32 v136, 3, v136
	v_bfe_u32 v137, v145, 4, 2
	v_xor_b32_e32 v136, v136, v137
	v_lshlrev_b32_e32 v136, 4, v136
	v_and_b32_e32 v131, 15, v145
	v_lshl_or_b32 v136, v131, 6, v136
	v_bfe_u32 v137, v145, 6, 1
	v_lshl_or_b32 v137, v137, 12, v136
	v_lshrrev_b32_e32 v0, 7, v145
	v_lshl_or_b32 v136, v0, 13, v136
	v_and_b32_e32 v140, 1, v131
	v_lshl_or_b32 v131, v0, 7, v131
	v_bfe_u32 v0, v145, 4, 2
	v_lshlrev_b32_e32 v0, 3, v0
	v_bfe_u32 v141, v145, 6, 1
	s_lshl_b32 s41, s46, 19
	s_lshl_b32 s42, s43, 9
	s_add_i32 s41, s41, s42
	s_add_u32 s4, s2, s41
	s_addc_u32 s5, s3, 0
	s_add_u32 s4, s4, 0x4200000
	s_addc_u32 s5, s5, 0
	v_lshlrev_b32_e32 v138, 11, v131
	v_lshl_add_u32 v138, v141, 8, v138
	v_add_u32_e32 v138, v138, v0
	s_movk_i32 s42, 1984
	v_mul_u32_u24_e32 v139, s42, v140
	v_sub_u32_e32 v138, v138, v139
	v_mov_b32_e32 v139, 0
	v_lshl_add_u64 v[138:139], s[4:5], 0, v[138:139]
	s_lshl_b32 s41, s46, 20
	s_lshl_b32 s42, s43, 9
	s_add_i32 s41, s41, s42
	s_add_u32 s10, s2, s41
	s_addc_u32 s11, s3, 0
	v_lshlrev_b32_e32 v140, 12, v131
	v_lshl_add_u32 v140, v141, 8, v140
	v_lshl_add_u32 v140, v0, 1, v140
	v_mov_b32_e32 v141, 0
	v_lshl_add_u64 v[140:141], s[10:11], 0, v[140:141]
	s_mov_b32 s2, 0x20000
	s_mov_b32 s3, 0
	v_lshrrev_b32_e32 v0, 6, v145
	v_lshlrev_b32_e32 v0, 10, v0
	s_nop 0
	v_readfirstlane_b32 s47, v0
	s_mov_b32 s44, m0
	s_mov_b32 s4, 128
	s_mov_b32 s5, 0
	v_mov_b32_e32 v2, 0
	v_mov_b32_e32 v3, 0
	v_mov_b32_e32 v4, 0
	v_mov_b32_e32 v5, 0
	v_mov_b32_e32 v6, 0
	v_mov_b32_e32 v7, 0
	v_mov_b32_e32 v8, 0
	v_mov_b32_e32 v9, 0
	v_mov_b32_e32 v10, 0
	v_mov_b32_e32 v11, 0
	v_mov_b32_e32 v12, 0
	v_mov_b32_e32 v13, 0
	v_mov_b32_e32 v14, 0
	v_mov_b32_e32 v15, 0
	v_mov_b32_e32 v16, 0
	v_mov_b32_e32 v17, 0
	v_mov_b32_e32 v18, 0
	v_mov_b32_e32 v19, 0
	v_mov_b32_e32 v20, 0
	v_mov_b32_e32 v21, 0
	v_mov_b32_e32 v22, 0
; #define LAS __attribute__((address_space(3)))
;     ...
;   f32x4 acc[4][8];
; #pragma unroll
;   for (int i = 0; i < 4; i++)
; #pragma unroll
;     for (int j = 0; j < 8; j++) acc[i][j] = (f32x4){0.f, 0.f, 0.f, 0.f};
;   const int nk = (nk_part < 0) ? (K >> 5) : nk_part;
;   const int lrow = tid >> 2, lpc = tid & 3;
;   const int lch = lpc ^ ((0x78 >> (((lrow >> 2) & 3) * 2)) & 3);
;   const u16* ga = A + (size_t)(m0 + lrow) * lda + kbeg + lch * 8;
;   const u16* gb = Bt + (size_t)(n0 + lrow) * K + kbeg + lch * 8;
;   const size_t ga1 = (size_t)64 * lda, gb1 = (size_t)64 * K;
;   const unsigned lds0 = (unsigned)(uintptr_t)(LAS char*)smem + (unsigned)__builtin_amdgcn_readfirstlane(wid) * 1024u;
;     ...
;   __syncthreads();
;   G2_STAGE(0); G2_STAGE(1);
	v_mov_b32_e32 v23, 0
	v_mov_b32_e32 v24, 0
	v_mov_b32_e32 v25, 0
	v_mov_b32_e32 v26, 0
	v_mov_b32_e32 v27, 0
	v_mov_b32_e32 v28, 0
	v_mov_b32_e32 v29, 0
	v_mov_b32_e32 v30, 0
	v_mov_b32_e32 v31, 0
	v_mov_b32_e32 v32, 0
	v_mov_b32_e32 v33, 0
	v_mov_b32_e32 v34, 0
	v_mov_b32_e32 v35, 0
	v_mov_b32_e32 v36, 0
	v_mov_b32_e32 v37, 0
	v_mov_b32_e32 v38, 0
	v_mov_b32_e32 v39, 0
	v_mov_b32_e32 v40, 0
	v_mov_b32_e32 v41, 0
	v_mov_b32_e32 v42, 0
	v_mov_b32_e32 v43, 0
	v_mov_b32_e32 v44, 0
	v_mov_b32_e32 v45, 0
	v_mov_b32_e32 v46, 0
	v_mov_b32_e32 v47, 0
	v_mov_b32_e32 v48, 0
	v_mov_b32_e32 v49, 0
	v_mov_b32_e32 v50, 0
	v_mov_b32_e32 v51, 0
	v_mov_b32_e32 v52, 0
	v_mov_b32_e32 v53, 0
	v_mov_b32_e32 v54, 0
	v_mov_b32_e32 v55, 0
	v_mov_b32_e32 v56, 0
	v_mov_b32_e32 v57, 0
	v_mov_b32_e32 v58, 0
	v_mov_b32_e32 v59, 0
	v_mov_b32_e32 v60, 0
	v_mov_b32_e32 v61, 0
	v_mov_b32_e32 v62, 0
	v_mov_b32_e32 v63, 0
	v_mov_b32_e32 v64, 0
	v_mov_b32_e32 v65, 0
	v_mov_b32_e32 v66, 0
	v_mov_b32_e32 v67, 0
	v_mov_b32_e32 v68, 0
	v_mov_b32_e32 v69, 0
	v_mov_b32_e32 v70, 0
	v_mov_b32_e32 v71, 0
	v_mov_b32_e32 v72, 0
	v_mov_b32_e32 v73, 0
	v_mov_b32_e32 v74, 0
	v_mov_b32_e32 v75, 0
	v_mov_b32_e32 v76, 0
	v_mov_b32_e32 v77, 0
	v_mov_b32_e32 v78, 0
	v_mov_b32_e32 v79, 0
	v_mov_b32_e32 v80, 0
	v_mov_b32_e32 v81, 0
	v_mov_b32_e32 v82, 0
	v_mov_b32_e32 v83, 0
	v_mov_b32_e32 v84, 0
	v_mov_b32_e32 v85, 0
	v_mov_b32_e32 v86, 0
	v_mov_b32_e32 v87, 0
	v_mov_b32_e32 v88, 0
	v_mov_b32_e32 v89, 0
	v_mov_b32_e32 v90, 0
	v_mov_b32_e32 v91, 0
	v_mov_b32_e32 v92, 0
	v_mov_b32_e32 v93, 0
	v_mov_b32_e32 v94, 0
	v_mov_b32_e32 v95, 0
	v_mov_b32_e32 v96, 0
	v_mov_b32_e32 v97, 0
	v_mov_b32_e32 v98, 0
	v_mov_b32_e32 v99, 0
	v_mov_b32_e32 v100, 0
	v_mov_b32_e32 v101, 0
	v_mov_b32_e32 v102, 0
	v_mov_b32_e32 v103, 0
	v_mov_b32_e32 v104, 0
	v_mov_b32_e32 v105, 0
	v_mov_b32_e32 v106, 0
	v_mov_b32_e32 v107, 0
	v_mov_b32_e32 v108, 0
	v_mov_b32_e32 v109, 0
	v_mov_b32_e32 v110, 0
	v_mov_b32_e32 v111, 0
	v_mov_b32_e32 v112, 0
	v_mov_b32_e32 v113, 0
	v_mov_b32_e32 v114, 0
	v_mov_b32_e32 v115, 0
	v_mov_b32_e32 v116, 0
	v_mov_b32_e32 v117, 0
	v_mov_b32_e32 v118, 0
	v_mov_b32_e32 v119, 0
	v_mov_b32_e32 v120, 0
	v_mov_b32_e32 v121, 0
	v_mov_b32_e32 v122, 0
	v_mov_b32_e32 v123, 0
	v_mov_b32_e32 v124, 0
	v_mov_b32_e32 v125, 0
	v_mov_b32_e32 v126, 0
	v_mov_b32_e32 v127, 0
	v_mov_b32_e32 v128, 0
	v_mov_b32_e32 v129, 0
	s_barrier
	s_add_i32 s43, s47, 0x0
	s_mov_b32 m0, s43
	v_lshl_add_u64 v[142:143], v[132:133], 0, s[2:3]
	global_load_lds_dwordx4 v[132:133], off
	s_addk_i32 m0, 0x1000
	s_nop 0
	global_load_lds_dwordx4 v[142:143], off
	v_lshl_add_u64 v[142:143], v[142:143], 0, s[2:3]
	s_addk_i32 m0, 0x1000
	s_nop 0
	global_load_lds_dwordx4 v[142:143], off
	v_lshl_add_u64 v[142:143], v[142:143], 0, s[2:3]
	s_addk_i32 m0, 0x1000
	s_nop 0
	global_load_lds_dwordx4 v[142:143], off
	s_addk_i32 m0, 0x1000
	v_lshl_add_u64 v[142:143], v[134:135], 0, s[2:3]
	s_nop 0
	global_load_lds_dwordx4 v[134:135], off
	s_addk_i32 m0, 0x1000
	v_lshl_add_u64 v[132:133], v[132:133], 0, s[12:13]
	s_nop 0
	global_load_lds_dwordx4 v[142:143], off
	v_lshl_add_u64 v[134:135], v[134:135], 0, s[4:5]
	s_nop 0
	s_add_i32 s43, s47, 0x6000
	s_mov_b32 m0, s43
	v_lshl_add_u64 v[142:143], v[132:133], 0, s[2:3]
	global_load_lds_dwordx4 v[132:133], off
	s_addk_i32 m0, 0x1000
	s_nop 0
	global_load_lds_dwordx4 v[142:143], off
	v_lshl_add_u64 v[142:143], v[142:143], 0, s[2:3]
	s_addk_i32 m0, 0x1000
	s_nop 0
	global_load_lds_dwordx4 v[142:143], off
	v_lshl_add_u64 v[142:143], v[142:143], 0, s[2:3]
	s_addk_i32 m0, 0x1000
	s_nop 0
	global_load_lds_dwordx4 v[142:143], off
	s_addk_i32 m0, 0x1000
	v_lshl_add_u64 v[142:143], v[134:135], 0, s[2:3]
	s_nop 0
	global_load_lds_dwordx4 v[134:135], off
	s_addk_i32 m0, 0x1000
	v_lshl_add_u64 v[132:133], v[132:133], 0, s[12:13]
	s_nop 0
	global_load_lds_dwordx4 v[142:143], off
	v_lshl_add_u64 v[134:135], v[134:135], 0, s[4:5]
	s_nop 0
	s_add_i32 s43, s47, 0xc000
	s_mov_b32 m0, s43
	v_lshl_add_u64 v[142:143], v[132:133], 0, s[2:3]
	global_load_lds_dwordx4 v[132:133], off
	s_addk_i32 m0, 0x1000
	s_nop 0
	global_load_lds_dwordx4 v[142:143], off
	v_lshl_add_u64 v[142:143], v[142:143], 0, s[2:3]
	s_addk_i32 m0, 0x1000
	s_nop 0
	global_load_lds_dwordx4 v[142:143], off
	v_lshl_add_u64 v[142:143], v[142:143], 0, s[2:3]
	s_addk_i32 m0, 0x1000
	s_nop 0
	global_load_lds_dwordx4 v[142:143], off
	s_addk_i32 m0, 0x1000
	v_lshl_add_u64 v[142:143], v[134:135], 0, s[2:3]
	s_nop 0
	global_load_lds_dwordx4 v[134:135], off
	s_addk_i32 m0, 0x1000
	v_lshl_add_u64 v[132:133], v[132:133], 0, s[12:13]
	s_nop 0
	global_load_lds_dwordx4 v[142:143], off
	v_lshl_add_u64 v[134:135], v[134:135], 0, s[4:5]
	s_nop 0
	s_waitcnt vmcnt(12)
	s_barrier
	ds_read_b128 v[146:149], v136 offset:0
	ds_read_b128 v[152:155], v136 offset:1024
	ds_read_b128 v[156:159], v136 offset:2048
	ds_read_b128 v[162:165], v136 offset:3072
	ds_read_b128 v[166:169], v136 offset:4096
	ds_read_b128 v[170:173], v136 offset:5120
	ds_read_b128 v[176:179], v136 offset:6144
	ds_read_b128 v[180:183], v136 offset:7168
	ds_read_b128 v[184:187], v137 offset:16384
	ds_read_b128 v[188:191], v137 offset:17408
	ds_read_b128 v[192:195], v137 offset:18432
	ds_read_b128 v[196:199], v137 offset:19456
	s_movk_i32 s41, 0x6000
	s_mov_b32 s42, 0
	s_movk_i32 s40, 14
;     ...
;   for (int kt = 0; kt < nk; kt++) {
;     if (kt + 1 < nk) asm volatile("s_waitcnt vmcnt(6)" ::: "memory");
;     else asm volatile("s_waitcnt vmcnt(0)" ::: "memory");
;     __builtin_amdgcn_s_barrier();
;     asm volatile("" ::: "memory");
;     if (kt + 2 < nk) G2_STAGE(kt + 2);
;     const char* cS = smem + (kt % 3) * 24576;
;     bf16x8 xa[8], wb[4];
; #pragma unroll
;     for (int f = 0; f < 8; f++) xa[f] = *(const bf16x8*)(cS + aoff + f * 1024);
; #pragma unroll
;     for (int f = 0; f < 4; f++) wb[f] = *(const bf16x8*)(cS + boff + f * 1024);
; #pragma unroll
;     for (int nf = 0; nf < 4; nf++)
; #pragma unroll
;       for (int mf = 0; mf < 8; mf++)
;         acc[nf][mf] = __builtin_amdgcn_mfma_f32_16x16x32_bf16(wb[nf], xa[mf], acc[nf][mf], 0, 0, 0);
;   }
.Lt4_loop:
	s_waitcnt vmcnt(6) lgkmcnt(0)
	s_barrier
	v_add_u32_e32 v144, s41, v136
	v_mfma_f32_16x16x32_bf16 v[126:129], v[184:187], v[146:149], v[126:129]
	ds_read_b128 v[200:203], v144 offset:0
	v_mfma_f32_16x16x32_bf16 v[122:125], v[184:187], v[152:155], v[122:125]
	ds_read_b128 v[204:207], v144 offset:1024
	v_mfma_f32_16x16x32_bf16 v[118:121], v[184:187], v[156:159], v[118:121]
	ds_read_b128 v[208:211], v144 offset:2048
	v_mfma_f32_16x16x32_bf16 v[114:117], v[184:187], v[162:165], v[114:117]
	ds_read_b128 v[212:215], v144 offset:3072
	v_mfma_f32_16x16x32_bf16 v[110:113], v[184:187], v[166:169], v[110:113]
	ds_read_b128 v[216:219], v144 offset:4096
	v_mfma_f32_16x16x32_bf16 v[106:109], v[184:187], v[170:173], v[106:109]
	ds_read_b128 v[220:223], v144 offset:5120
	v_mfma_f32_16x16x32_bf16 v[102:105], v[184:187], v[176:179], v[102:105]
	ds_read_b128 v[224:227], v144 offset:6144
	v_mfma_f32_16x16x32_bf16 v[98:101], v[184:187], v[180:183], v[98:101]
	ds_read_b128 v[228:231], v144 offset:7168
	v_mfma_f32_16x16x32_bf16 v[94:97], v[188:191], v[146:149], v[94:97]
	v_add_u32_e32 v144, s41, v137
	v_mfma_f32_16x16x32_bf16 v[90:93], v[188:191], v[152:155], v[90:93]
	v_mfma_f32_16x16x32_bf16 v[86:89], v[188:191], v[156:159], v[86:89]
	ds_read_b128 v[232:235], v144 offset:16384
	v_mfma_f32_16x16x32_bf16 v[82:85], v[188:191], v[162:165], v[82:85]
	ds_read_b128 v[236:239], v144 offset:17408
	v_mfma_f32_16x16x32_bf16 v[78:81], v[188:191], v[166:169], v[78:81]
	ds_read_b128 v[240:243], v144 offset:18432
	v_mfma_f32_16x16x32_bf16 v[74:77], v[188:191], v[170:173], v[74:77]
	ds_read_b128 v[244:247], v144 offset:19456
	s_add_i32 s43, s47, s42
	v_mfma_f32_16x16x32_bf16 v[70:73], v[188:191], v[176:179], v[70:73]
	s_mov_b32 m0, s43
	v_lshl_add_u64 v[142:143], v[132:133], 0, s[2:3]
	v_mfma_f32_16x16x32_bf16 v[66:69], v[188:191], v[180:183], v[66:69]
	global_load_lds_dwordx4 v[132:133], off
	s_addk_i32 m0, 0x1000
	v_mfma_f32_16x16x32_bf16 v[62:65], v[192:195], v[146:149], v[62:65]
	v_mfma_f32_16x16x32_bf16 v[58:61], v[192:195], v[152:155], v[58:61]
	v_mfma_f32_16x16x32_bf16 v[54:57], v[192:195], v[156:159], v[54:57]
	global_load_lds_dwordx4 v[142:143], off
	v_lshl_add_u64 v[142:143], v[142:143], 0, s[2:3]
	s_addk_i32 m0, 0x1000
	v_mfma_f32_16x16x32_bf16 v[50:53], v[192:195], v[162:165], v[50:53]
	v_mfma_f32_16x16x32_bf16 v[46:49], v[192:195], v[166:169], v[46:49]
	v_mfma_f32_16x16x32_bf16 v[42:45], v[192:195], v[170:173], v[42:45]
	global_load_lds_dwordx4 v[142:143], off
	v_lshl_add_u64 v[142:143], v[142:143], 0, s[2:3]
	s_addk_i32 m0, 0x1000
	v_mfma_f32_16x16x32_bf16 v[38:41], v[192:195], v[176:179], v[38:41]
	v_mfma_f32_16x16x32_bf16 v[34:37], v[192:195], v[180:183], v[34:37]
	v_mfma_f32_16x16x32_bf16 v[30:33], v[196:199], v[146:149], v[30:33]
	global_load_lds_dwordx4 v[142:143], off
	s_addk_i32 m0, 0x1000
	v_lshl_add_u64 v[142:143], v[134:135], 0, s[2:3]
	v_mfma_f32_16x16x32_bf16 v[26:29], v[196:199], v[152:155], v[26:29]
	v_mfma_f32_16x16x32_bf16 v[22:25], v[196:199], v[156:159], v[22:25]
	v_mfma_f32_16x16x32_bf16 v[18:21], v[196:199], v[162:165], v[18:21]
	global_load_lds_dwordx4 v[134:135], off
	s_addk_i32 m0, 0x1000
	v_lshl_add_u64 v[132:133], v[132:133], 0, s[12:13]
	v_mfma_f32_16x16x32_bf16 v[14:17], v[196:199], v[166:169], v[14:17]
	v_mfma_f32_16x16x32_bf16 v[10:13], v[196:199], v[170:173], v[10:13]
	v_mfma_f32_16x16x32_bf16 v[6:9], v[196:199], v[176:179], v[6:9]
	global_load_lds_dwordx4 v[142:143], off
	v_lshl_add_u64 v[134:135], v[134:135], 0, s[4:5]
	v_mfma_f32_16x16x32_bf16 v[2:5], v[196:199], v[180:183], v[2:5]
	s_mov_b32 s42, s41
	s_add_i32 s41, s41, 0x6000
	s_cmp_eq_u32 s41, 0x12000
	s_cselect_b32 s41, 0, s41
	s_waitcnt vmcnt(6) lgkmcnt(0)
	s_barrier
	v_add_u32_e32 v144, s41, v136
	v_mfma_f32_16x16x32_bf16 v[126:129], v[232:235], v[200:203], v[126:129]
	ds_read_b128 v[146:149], v144 offset:0
	v_mfma_f32_16x16x32_bf16 v[122:125], v[232:235], v[204:207], v[122:125]
	ds_read_b128 v[152:155], v144 offset:1024
	v_mfma_f32_16x16x32_bf16 v[118:121], v[232:235], v[208:211], v[118:121]
	ds_read_b128 v[156:159], v144 offset:2048
	v_mfma_f32_16x16x32_bf16 v[114:117], v[232:235], v[212:215], v[114:117]
	ds_read_b128 v[162:165], v144 offset:3072
	v_mfma_f32_16x16x32_bf16 v[110:113], v[232:235], v[216:219], v[110:113]
	ds_read_b128 v[166:169], v144 offset:4096
	v_mfma_f32_16x16x32_bf16 v[106:109], v[232:235], v[220:223], v[106:109]
	ds_read_b128 v[170:173], v144 offset:5120
	v_mfma_f32_16x16x32_bf16 v[102:105], v[232:235], v[224:227], v[102:105]
	ds_read_b128 v[176:179], v144 offset:6144
	v_mfma_f32_16x16x32_bf16 v[98:101], v[232:235], v[228:231], v[98:101]
	ds_read_b128 v[180:183], v144 offset:7168
	v_mfma_f32_16x16x32_bf16 v[94:97], v[236:239], v[200:203], v[94:97]
	v_add_u32_e32 v144, s41, v137
	v_mfma_f32_16x16x32_bf16 v[90:93], v[236:239], v[204:207], v[90:93]
	v_mfma_f32_16x16x32_bf16 v[86:89], v[236:239], v[208:211], v[86:89]
	ds_read_b128 v[184:187], v144 offset:16384
	v_mfma_f32_16x16x32_bf16 v[82:85], v[236:239], v[212:215], v[82:85]
	ds_read_b128 v[188:191], v144 offset:17408
	v_mfma_f32_16x16x32_bf16 v[78:81], v[236:239], v[216:219], v[78:81]
	ds_read_b128 v[192:195], v144 offset:18432
	v_mfma_f32_16x16x32_bf16 v[74:77], v[236:239], v[220:223], v[74:77]
	ds_read_b128 v[196:199], v144 offset:19456
	s_add_i32 s43, s47, s42
	v_mfma_f32_16x16x32_bf16 v[70:73], v[236:239], v[224:227], v[70:73]
	s_mov_b32 m0, s43
	v_lshl_add_u64 v[142:143], v[132:133], 0, s[2:3]
	v_mfma_f32_16x16x32_bf16 v[66:69], v[236:239], v[228:231], v[66:69]
	global_load_lds_dwordx4 v[132:133], off
	s_addk_i32 m0, 0x1000
	v_mfma_f32_16x16x32_bf16 v[62:65], v[240:243], v[200:203], v[62:65]
;     ...
;   for (int kt = 0; kt < nk; kt++) {
;     if (kt + 1 < nk) asm volatile("s_waitcnt vmcnt(6)" ::: "memory");
;     else asm volatile("s_waitcnt vmcnt(0)" ::: "memory");
;     __builtin_amdgcn_s_barrier();
;     asm volatile("" ::: "memory");
;     if (kt + 2 < nk) G2_STAGE(kt + 2);
;     const char* cS = smem + (kt % 3) * 24576;
;     bf16x8 xa[8], wb[4];
; #pragma unroll
;     for (int f = 0; f < 8; f++) xa[f] = *(const bf16x8*)(cS + aoff + f * 1024);
; #pragma unroll
;     for (int f = 0; f < 4; f++) wb[f] = *(const bf16x8*)(cS + boff + f * 1024);
; #pragma unroll
;     for (int nf = 0; nf < 4; nf++)
; #pragma unroll
;       for (int mf = 0; mf < 8; mf++)
;         acc[nf][mf] = __builtin_amdgcn_mfma_f32_16x16x32_bf16(wb[nf], xa[mf], acc[nf][mf], 0, 0, 0);
;   }
	v_mfma_f32_16x16x32_bf16 v[58:61], v[240:243], v[204:207], v[58:61]
	v_mfma_f32_16x16x32_bf16 v[54:57], v[240:243], v[208:211], v[54:57]
	global_load_lds_dwordx4 v[142:143], off
	v_lshl_add_u64 v[142:143], v[142:143], 0, s[2:3]
	s_addk_i32 m0, 0x1000
	v_mfma_f32_16x16x32_bf16 v[50:53], v[240:243], v[212:215], v[50:53]
	v_mfma_f32_16x16x32_bf16 v[46:49], v[240:243], v[216:219], v[46:49]
	v_mfma_f32_16x16x32_bf16 v[42:45], v[240:243], v[220:223], v[42:45]
	global_load_lds_dwordx4 v[142:143], off
	v_lshl_add_u64 v[142:143], v[142:143], 0, s[2:3]
	s_addk_i32 m0, 0x1000
	v_mfma_f32_16x16x32_bf16 v[38:41], v[240:243], v[224:227], v[38:41]
	v_mfma_f32_16x16x32_bf16 v[34:37], v[240:243], v[228:231], v[34:37]
	v_mfma_f32_16x16x32_bf16 v[30:33], v[244:247], v[200:203], v[30:33]
	global_load_lds_dwordx4 v[142:143], off
	s_addk_i32 m0, 0x1000
	v_lshl_add_u64 v[142:143], v[134:135], 0, s[2:3]
	v_mfma_f32_16x16x32_bf16 v[26:29], v[244:247], v[204:207], v[26:29]
	v_mfma_f32_16x16x32_bf16 v[22:25], v[244:247], v[208:211], v[22:25]
	v_mfma_f32_16x16x32_bf16 v[18:21], v[244:247], v[212:215], v[18:21]
	global_load_lds_dwordx4 v[134:135], off
	s_addk_i32 m0, 0x1000
	v_lshl_add_u64 v[132:133], v[132:133], 0, s[12:13]
	v_mfma_f32_16x16x32_bf16 v[14:17], v[244:247], v[216:219], v[14:17]
	v_mfma_f32_16x16x32_bf16 v[10:13], v[244:247], v[220:223], v[10:13]
	v_mfma_f32_16x16x32_bf16 v[6:9], v[244:247], v[224:227], v[6:9]
	global_load_lds_dwordx4 v[142:143], off
	v_lshl_add_u64 v[134:135], v[134:135], 0, s[4:5]
	v_mfma_f32_16x16x32_bf16 v[2:5], v[244:247], v[228:231], v[2:5]
	s_mov_b32 s42, s41
	s_add_i32 s41, s41, 0x6000
	s_cmp_eq_u32 s41, 0x12000
	s_cselect_b32 s41, 0, s41
	s_sub_i32 s40, s40, 1
	s_cmp_lg_u32 s40, 0
	s_cbranch_scc1 .Lt4_loop
	s_waitcnt vmcnt(6) lgkmcnt(0)
	s_barrier
	v_add_u32_e32 v144, s41, v136
	v_mfma_f32_16x16x32_bf16 v[126:129], v[184:187], v[146:149], v[126:129]
	ds_read_b128 v[200:203], v144 offset:0
	v_mfma_f32_16x16x32_bf16 v[122:125], v[184:187], v[152:155], v[122:125]
	ds_read_b128 v[204:207], v144 offset:1024
	v_mfma_f32_16x16x32_bf16 v[118:121], v[184:187], v[156:159], v[118:121]
	ds_read_b128 v[208:211], v144 offset:2048
	v_mfma_f32_16x16x32_bf16 v[114:117], v[184:187], v[162:165], v[114:117]
	ds_read_b128 v[212:215], v144 offset:3072
	v_mfma_f32_16x16x32_bf16 v[110:113], v[184:187], v[166:169], v[110:113]
	ds_read_b128 v[216:219], v144 offset:4096
	v_mfma_f32_16x16x32_bf16 v[106:109], v[184:187], v[170:173], v[106:109]
	ds_read_b128 v[220:223], v144 offset:5120
	v_mfma_f32_16x16x32_bf16 v[102:105], v[184:187], v[176:179], v[102:105]
	ds_read_b128 v[224:227], v144 offset:6144
	v_mfma_f32_16x16x32_bf16 v[98:101], v[184:187], v[180:183], v[98:101]
	ds_read_b128 v[228:231], v144 offset:7168
	v_mfma_f32_16x16x32_bf16 v[94:97], v[188:191], v[146:149], v[94:97]
	v_add_u32_e32 v144, s41, v137
	v_mfma_f32_16x16x32_bf16 v[90:93], v[188:191], v[152:155], v[90:93]
	v_mfma_f32_16x16x32_bf16 v[86:89], v[188:191], v[156:159], v[86:89]
	ds_read_b128 v[232:235], v144 offset:16384
	v_mfma_f32_16x16x32_bf16 v[82:85], v[188:191], v[162:165], v[82:85]
	ds_read_b128 v[236:239], v144 offset:17408
	v_mfma_f32_16x16x32_bf16 v[78:81], v[188:191], v[166:169], v[78:81]
	ds_read_b128 v[240:243], v144 offset:18432
	v_mfma_f32_16x16x32_bf16 v[74:77], v[188:191], v[170:173], v[74:77]
	ds_read_b128 v[244:247], v144 offset:19456
	s_add_i32 s43, s47, s42
	v_mfma_f32_16x16x32_bf16 v[70:73], v[188:191], v[176:179], v[70:73]
	s_mov_b32 m0, s43
	v_lshl_add_u64 v[142:143], v[132:133], 0, s[2:3]
	v_mfma_f32_16x16x32_bf16 v[66:69], v[188:191], v[180:183], v[66:69]
	global_load_lds_dwordx4 v[132:133], off
	s_addk_i32 m0, 0x1000
	v_mfma_f32_16x16x32_bf16 v[62:65], v[192:195], v[146:149], v[62:65]
	v_mfma_f32_16x16x32_bf16 v[58:61], v[192:195], v[152:155], v[58:61]
	v_mfma_f32_16x16x32_bf16 v[54:57], v[192:195], v[156:159], v[54:57]
	global_load_lds_dwordx4 v[142:143], off
	v_lshl_add_u64 v[142:143], v[142:143], 0, s[2:3]
	s_addk_i32 m0, 0x1000
	v_mfma_f32_16x16x32_bf16 v[50:53], v[192:195], v[162:165], v[50:53]
	v_mfma_f32_16x16x32_bf16 v[46:49], v[192:195], v[166:169], v[46:49]
	v_mfma_f32_16x16x32_bf16 v[42:45], v[192:195], v[170:173], v[42:45]
	global_load_lds_dwordx4 v[142:143], off
	v_lshl_add_u64 v[142:143], v[142:143], 0, s[2:3]
	s_addk_i32 m0, 0x1000
	v_mfma_f32_16x16x32_bf16 v[38:41], v[192:195], v[176:179], v[38:41]
	v_mfma_f32_16x16x32_bf16 v[34:37], v[192:195], v[180:183], v[34:37]
	v_mfma_f32_16x16x32_bf16 v[30:33], v[196:199], v[146:149], v[30:33]
	global_load_lds_dwordx4 v[142:143], off
	s_addk_i32 m0, 0x1000
	v_lshl_add_u64 v[142:143], v[134:135], 0, s[2:3]
	v_mfma_f32_16x16x32_bf16 v[26:29], v[196:199], v[152:155], v[26:29]
	v_mfma_f32_16x16x32_bf16 v[22:25], v[196:199], v[156:159], v[22:25]
	v_mfma_f32_16x16x32_bf16 v[18:21], v[196:199], v[162:165], v[18:21]
	global_load_lds_dwordx4 v[134:135], off
	s_addk_i32 m0, 0x1000
	v_lshl_add_u64 v[132:133], v[132:133], 0, s[12:13]
	v_mfma_f32_16x16x32_bf16 v[14:17], v[196:199], v[166:169], v[14:17]
	v_mfma_f32_16x16x32_bf16 v[10:13], v[196:199], v[170:173], v[10:13]
	v_mfma_f32_16x16x32_bf16 v[6:9], v[196:199], v[176:179], v[6:9]
	global_load_lds_dwordx4 v[142:143], off
	v_lshl_add_u64 v[134:135], v[134:135], 0, s[4:5]
	v_mfma_f32_16x16x32_bf16 v[2:5], v[196:199], v[180:183], v[2:5]
	s_mov_b32 s42, s41
	s_add_i32 s41, s41, 0x6000
	s_cmp_eq_u32 s41, 0x12000
	s_cselect_b32 s41, 0, s41
	s_waitcnt vmcnt(6) lgkmcnt(0)
	s_barrier
;     ...
;   for (int kt = 0; kt < nk; kt++) {
;     if (kt + 1 < nk) asm volatile("s_waitcnt vmcnt(6)" ::: "memory");
;     else asm volatile("s_waitcnt vmcnt(0)" ::: "memory");
;     __builtin_amdgcn_s_barrier();
;     asm volatile("" ::: "memory");
;     if (kt + 2 < nk) G2_STAGE(kt + 2);
;     const char* cS = smem + (kt % 3) * 24576;
;     bf16x8 xa[8], wb[4];
; #pragma unroll
;     for (int f = 0; f < 8; f++) xa[f] = *(const bf16x8*)(cS + aoff + f * 1024);
; #pragma unroll
;     for (int f = 0; f < 4; f++) wb[f] = *(const bf16x8*)(cS + boff + f * 1024);
; #pragma unroll
;     for (int nf = 0; nf < 4; nf++)
; #pragma unroll
;       for (int mf = 0; mf < 8; mf++)
;         acc[nf][mf] = __builtin_amdgcn_mfma_f32_16x16x32_bf16(wb[nf], xa[mf], acc[nf][mf], 0, 0, 0);
;   }
	v_add_u32_e32 v144, s41, v136
	v_mfma_f32_16x16x32_bf16 v[126:129], v[232:235], v[200:203], v[126:129]
	ds_read_b128 v[146:149], v144 offset:0
	v_mfma_f32_16x16x32_bf16 v[122:125], v[232:235], v[204:207], v[122:125]
	ds_read_b128 v[152:155], v144 offset:1024
	v_mfma_f32_16x16x32_bf16 v[118:121], v[232:235], v[208:211], v[118:121]
	ds_read_b128 v[156:159], v144 offset:2048
	v_mfma_f32_16x16x32_bf16 v[114:117], v[232:235], v[212:215], v[114:117]
	ds_read_b128 v[162:165], v144 offset:3072
	v_mfma_f32_16x16x32_bf16 v[110:113], v[232:235], v[216:219], v[110:113]
	ds_read_b128 v[166:169], v144 offset:4096
	v_mfma_f32_16x16x32_bf16 v[106:109], v[232:235], v[220:223], v[106:109]
	ds_read_b128 v[170:173], v144 offset:5120
	v_mfma_f32_16x16x32_bf16 v[102:105], v[232:235], v[224:227], v[102:105]
	ds_read_b128 v[176:179], v144 offset:6144
	v_mfma_f32_16x16x32_bf16 v[98:101], v[232:235], v[228:231], v[98:101]
	ds_read_b128 v[180:183], v144 offset:7168
	v_mfma_f32_16x16x32_bf16 v[94:97], v[236:239], v[200:203], v[94:97]
	v_add_u32_e32 v144, s41, v137
	v_mfma_f32_16x16x32_bf16 v[90:93], v[236:239], v[204:207], v[90:93]
	v_mfma_f32_16x16x32_bf16 v[86:89], v[236:239], v[208:211], v[86:89]
	ds_read_b128 v[184:187], v144 offset:16384
	v_mfma_f32_16x16x32_bf16 v[82:85], v[236:239], v[212:215], v[82:85]
	ds_read_b128 v[188:191], v144 offset:17408
	v_mfma_f32_16x16x32_bf16 v[78:81], v[236:239], v[216:219], v[78:81]
	ds_read_b128 v[192:195], v144 offset:18432
	v_mfma_f32_16x16x32_bf16 v[74:77], v[236:239], v[220:223], v[74:77]
	ds_read_b128 v[196:199], v144 offset:19456
	v_mfma_f32_16x16x32_bf16 v[70:73], v[236:239], v[224:227], v[70:73]
	v_mfma_f32_16x16x32_bf16 v[66:69], v[236:239], v[228:231], v[66:69]
	v_mfma_f32_16x16x32_bf16 v[62:65], v[240:243], v[200:203], v[62:65]
	v_mfma_f32_16x16x32_bf16 v[58:61], v[240:243], v[204:207], v[58:61]
	v_mfma_f32_16x16x32_bf16 v[54:57], v[240:243], v[208:211], v[54:57]
	v_mfma_f32_16x16x32_bf16 v[50:53], v[240:243], v[212:215], v[50:53]
	v_mfma_f32_16x16x32_bf16 v[46:49], v[240:243], v[216:219], v[46:49]
	v_mfma_f32_16x16x32_bf16 v[42:45], v[240:243], v[220:223], v[42:45]
	v_mfma_f32_16x16x32_bf16 v[38:41], v[240:243], v[224:227], v[38:41]
	v_mfma_f32_16x16x32_bf16 v[34:37], v[240:243], v[228:231], v[34:37]
	v_mfma_f32_16x16x32_bf16 v[30:33], v[244:247], v[200:203], v[30:33]
	v_mfma_f32_16x16x32_bf16 v[26:29], v[244:247], v[204:207], v[26:29]
	v_mfma_f32_16x16x32_bf16 v[22:25], v[244:247], v[208:211], v[22:25]
	v_mfma_f32_16x16x32_bf16 v[18:21], v[244:247], v[212:215], v[18:21]
	v_mfma_f32_16x16x32_bf16 v[14:17], v[244:247], v[216:219], v[14:17]
	v_mfma_f32_16x16x32_bf16 v[10:13], v[244:247], v[220:223], v[10:13]
	v_mfma_f32_16x16x32_bf16 v[6:9], v[244:247], v[224:227], v[6:9]
	v_mfma_f32_16x16x32_bf16 v[2:5], v[244:247], v[228:231], v[2:5]
	s_mov_b32 s42, s41
	s_add_i32 s41, s41, 0x6000
	s_cmp_eq_u32 s41, 0x12000
	s_cselect_b32 s41, 0, s41
	s_waitcnt vmcnt(0) lgkmcnt(0)
	s_barrier
	v_add_u32_e32 v144, s41, v136
	v_mfma_f32_16x16x32_bf16 v[126:129], v[184:187], v[146:149], v[126:129]
	ds_read_b128 v[200:203], v144 offset:0
	v_mfma_f32_16x16x32_bf16 v[122:125], v[184:187], v[152:155], v[122:125]
	ds_read_b128 v[204:207], v144 offset:1024
	v_mfma_f32_16x16x32_bf16 v[118:121], v[184:187], v[156:159], v[118:121]
	ds_read_b128 v[208:211], v144 offset:2048
	v_mfma_f32_16x16x32_bf16 v[114:117], v[184:187], v[162:165], v[114:117]
	ds_read_b128 v[212:215], v144 offset:3072
	v_mfma_f32_16x16x32_bf16 v[110:113], v[184:187], v[166:169], v[110:113]
	ds_read_b128 v[216:219], v144 offset:4096
	v_mfma_f32_16x16x32_bf16 v[106:109], v[184:187], v[170:173], v[106:109]
	ds_read_b128 v[220:223], v144 offset:5120
	v_mfma_f32_16x16x32_bf16 v[102:105], v[184:187], v[176:179], v[102:105]
	ds_read_b128 v[224:227], v144 offset:6144
	v_mfma_f32_16x16x32_bf16 v[98:101], v[184:187], v[180:183], v[98:101]
	ds_read_b128 v[228:231], v144 offset:7168
	v_mfma_f32_16x16x32_bf16 v[94:97], v[188:191], v[146:149], v[94:97]
	v_add_u32_e32 v144, s41, v137
	v_mfma_f32_16x16x32_bf16 v[90:93], v[188:191], v[152:155], v[90:93]
	v_mfma_f32_16x16x32_bf16 v[86:89], v[188:191], v[156:159], v[86:89]
	ds_read_b128 v[232:235], v144 offset:16384
	v_mfma_f32_16x16x32_bf16 v[82:85], v[188:191], v[162:165], v[82:85]
	ds_read_b128 v[236:239], v144 offset:17408
	v_mfma_f32_16x16x32_bf16 v[78:81], v[188:191], v[166:169], v[78:81]
	ds_read_b128 v[240:243], v144 offset:18432
	v_mfma_f32_16x16x32_bf16 v[74:77], v[188:191], v[170:173], v[74:77]
	ds_read_b128 v[244:247], v144 offset:19456
	v_mfma_f32_16x16x32_bf16 v[70:73], v[188:191], v[176:179], v[70:73]
	v_mfma_f32_16x16x32_bf16 v[66:69], v[188:191], v[180:183], v[66:69]
	v_mfma_f32_16x16x32_bf16 v[62:65], v[192:195], v[146:149], v[62:65]
	v_mfma_f32_16x16x32_bf16 v[58:61], v[192:195], v[152:155], v[58:61]
	v_mfma_f32_16x16x32_bf16 v[54:57], v[192:195], v[156:159], v[54:57]
	v_mfma_f32_16x16x32_bf16 v[50:53], v[192:195], v[162:165], v[50:53]
	v_mfma_f32_16x16x32_bf16 v[46:49], v[192:195], v[166:169], v[46:49]
	v_mfma_f32_16x16x32_bf16 v[42:45], v[192:195], v[170:173], v[42:45]
	v_mfma_f32_16x16x32_bf16 v[38:41], v[192:195], v[176:179], v[38:41]
	v_mfma_f32_16x16x32_bf16 v[34:37], v[192:195], v[180:183], v[34:37]
	v_mfma_f32_16x16x32_bf16 v[30:33], v[196:199], v[146:149], v[30:33]
	v_mfma_f32_16x16x32_bf16 v[26:29], v[196:199], v[152:155], v[26:29]
	v_mfma_f32_16x16x32_bf16 v[22:25], v[196:199], v[156:159], v[22:25]
	v_mfma_f32_16x16x32_bf16 v[18:21], v[196:199], v[162:165], v[18:21]
	v_mfma_f32_16x16x32_bf16 v[14:17], v[196:199], v[166:169], v[14:17]
	v_mfma_f32_16x16x32_bf16 v[10:13], v[196:199], v[170:173], v[10:13]
	v_mfma_f32_16x16x32_bf16 v[6:9], v[196:199], v[176:179], v[6:9]
	v_mfma_f32_16x16x32_bf16 v[2:5], v[196:199], v[180:183], v[2:5]
	s_mov_b32 s42, s41
	s_add_i32 s41, s41, 0x6000
	s_cmp_eq_u32 s41, 0x12000
	s_cselect_b32 s41, 0, s41
	s_mov_b32 s4, 0x8000
	s_mov_b32 s5, 0
	s_mov_b32 s10, 0x10000
	s_mov_b32 s11, 0
	s_mov_b32 s45, 0x3fd744fd
	s_waitcnt lgkmcnt(0)
; DEVI unsigned pack2(float a, float b) { return __builtin_bit_cast(unsigned, __builtin_convertvector((f32x2_t){a, b}, bf16x2_t)); }
; DEVI float blo(unsigned u) { return __uint_as_float(u << 16); }
; DEVI float bhi(unsigned u) { return __uint_as_float(u & 0xffff0000u); }
; DEVI float siluf_(float x) { return x * __builtin_amdgcn_rcpf(1.f + __expf(-x)); }
;     ...
;     for (int nf = 0; nf < 4; nf++)
; #pragma unroll
;       for (int mf = 0; mf < 8; mf++)
;         acc[nf][mf] = __builtin_amdgcn_mfma_f32_16x16x32_bf16(wb[nf], xa[mf], acc[nf][mf], 0, 0, 0);
;   }
;     ...
; #pragma unroll
;   for (int mf = 0; mf < 8; mf++) {
;     const int row = m0 + wm * 128 + mf * 16 + r16;
;     if (EPI == EPI_SWIGLU) {
; #pragma unroll
;       for (int nf = 0; nf < 2; nf++) {
;         const int hcol = (n0 >> 1) + wn * 32 + nf * 16 + quad * 4;
;         f32x4 g = acc[nf][mf], u = acc[nf + 2][mf];
;         u32x2 pk;
;         pk[0] = pack2(siluf_(g[0]) * u[0], siluf_(g[1]) * u[1]);
;         pk[1] = pack2(siluf_(g[2]) * u[2], siluf_(g[3]) * u[3]);
;         *(u32x2*)(outb + (size_t)row * DFF + hcol) = pk;
;       }
;     } else {
; #pragma unroll
;       for (int nf = 0; nf < 4; nf++) {
;         const int col = n0 + wn * 64 + nf * 16 + quad * 4;
;         f32x4 a = acc[nf][mf];
;         if (EPI == EPI_RESID || EPI == EPI_RESID_ATOMIC) {
;           f32x4 x = a;
;           if (EPI == EPI_RESID || kpart == 0) {
;             const u32x2 xr = *(const u32x2*)((const u16*)(p.ws + WS_XB) + (size_t)row * 1024 + col);
;             x[0] += ALPHA * blo(xr[0]); x[1] += ALPHA * bhi(xr[0]); x[2] += ALPHA * blo(xr[1]); x[3] += ALPHA * bhi(xr[1]);
;           }
;           if (EPI == EPI_RESID) *(f32x4*)((float*)(p.ws + WS_XF) + (size_t)row * 1024 + col) = x;
	v_mfma_f32_16x16x32_bf16 v[126:129], v[232:235], v[200:203], v[126:129]
	v_mfma_f32_16x16x32_bf16 v[122:125], v[232:235], v[204:207], v[122:125]
	v_mfma_f32_16x16x32_bf16 v[118:121], v[232:235], v[208:211], v[118:121]
	v_mfma_f32_16x16x32_bf16 v[114:117], v[232:235], v[212:215], v[114:117]
	v_mfma_f32_16x16x32_bf16 v[110:113], v[232:235], v[216:219], v[110:113]
	global_load_dwordx2 v[146:147], v[138:139], off offset:0
	v_mfma_f32_16x16x32_bf16 v[106:109], v[232:235], v[220:223], v[106:109]
	global_load_dwordx2 v[148:149], v[138:139], off offset:32
	v_mfma_f32_16x16x32_bf16 v[102:105], v[232:235], v[224:227], v[102:105]
	global_load_dwordx2 v[152:153], v[138:139], off offset:128
	v_mfma_f32_16x16x32_bf16 v[98:101], v[232:235], v[228:231], v[98:101]
	global_load_dwordx2 v[154:155], v[138:139], off offset:160
	v_lshl_add_u64 v[138:139], v[138:139], 0, s[4:5]
	v_mfma_f32_16x16x32_bf16 v[94:97], v[236:239], v[200:203], v[94:97]
	global_load_dwordx2 v[156:157], v[138:139], off offset:0
	v_mfma_f32_16x16x32_bf16 v[90:93], v[236:239], v[204:207], v[90:93]
	global_load_dwordx2 v[158:159], v[138:139], off offset:32
	v_mfma_f32_16x16x32_bf16 v[86:89], v[236:239], v[208:211], v[86:89]
	global_load_dwordx2 v[162:163], v[138:139], off offset:128
	v_mfma_f32_16x16x32_bf16 v[82:85], v[236:239], v[212:215], v[82:85]
	global_load_dwordx2 v[164:165], v[138:139], off offset:160
	v_lshl_add_u64 v[138:139], v[138:139], 0, s[4:5]
	v_mfma_f32_16x16x32_bf16 v[78:81], v[236:239], v[216:219], v[78:81]
	global_load_dwordx2 v[166:167], v[138:139], off offset:0
	v_mfma_f32_16x16x32_bf16 v[74:77], v[236:239], v[220:223], v[74:77]
	global_load_dwordx2 v[168:169], v[138:139], off offset:32
	v_mfma_f32_16x16x32_bf16 v[70:73], v[236:239], v[224:227], v[70:73]
	global_load_dwordx2 v[170:171], v[138:139], off offset:128
	v_mfma_f32_16x16x32_bf16 v[66:69], v[236:239], v[228:231], v[66:69]
	global_load_dwordx2 v[172:173], v[138:139], off offset:160
	v_lshl_add_u64 v[138:139], v[138:139], 0, s[4:5]
	v_mfma_f32_16x16x32_bf16 v[62:65], v[240:243], v[200:203], v[62:65]
	global_load_dwordx2 v[176:177], v[138:139], off offset:0
	v_mfma_f32_16x16x32_bf16 v[58:61], v[240:243], v[204:207], v[58:61]
	global_load_dwordx2 v[178:179], v[138:139], off offset:32
	v_mfma_f32_16x16x32_bf16 v[54:57], v[240:243], v[208:211], v[54:57]
	global_load_dwordx2 v[180:181], v[138:139], off offset:128
	v_mfma_f32_16x16x32_bf16 v[50:53], v[240:243], v[212:215], v[50:53]
	global_load_dwordx2 v[182:183], v[138:139], off offset:160
	v_lshl_add_u64 v[138:139], v[138:139], 0, s[4:5]
	v_mfma_f32_16x16x32_bf16 v[46:49], v[240:243], v[216:219], v[46:49]
	global_load_dwordx2 v[184:185], v[138:139], off offset:0
	v_mfma_f32_16x16x32_bf16 v[42:45], v[240:243], v[220:223], v[42:45]
	global_load_dwordx2 v[186:187], v[138:139], off offset:32
	v_mfma_f32_16x16x32_bf16 v[38:41], v[240:243], v[224:227], v[38:41]
	global_load_dwordx2 v[188:189], v[138:139], off offset:128
	v_mfma_f32_16x16x32_bf16 v[34:37], v[240:243], v[228:231], v[34:37]
	global_load_dwordx2 v[190:191], v[138:139], off offset:160
	v_lshl_add_u64 v[138:139], v[138:139], 0, s[4:5]
	v_mfma_f32_16x16x32_bf16 v[30:33], v[244:247], v[200:203], v[30:33]
	global_load_dwordx2 v[192:193], v[138:139], off offset:0
	v_mfma_f32_16x16x32_bf16 v[26:29], v[244:247], v[204:207], v[26:29]
	global_load_dwordx2 v[194:195], v[138:139], off offset:32
	v_mfma_f32_16x16x32_bf16 v[22:25], v[244:247], v[208:211], v[22:25]
	global_load_dwordx2 v[196:197], v[138:139], off offset:128
	v_mfma_f32_16x16x32_bf16 v[18:21], v[244:247], v[212:215], v[18:21]
	global_load_dwordx2 v[198:199], v[138:139], off offset:160
	v_lshl_add_u64 v[138:139], v[138:139], 0, s[4:5]
	v_mfma_f32_16x16x32_bf16 v[14:17], v[244:247], v[216:219], v[14:17]
	v_mfma_f32_16x16x32_bf16 v[10:13], v[244:247], v[220:223], v[10:13]
	v_mfma_f32_16x16x32_bf16 v[6:9], v[244:247], v[224:227], v[6:9]
	v_mfma_f32_16x16x32_bf16 v[2:5], v[244:247], v[228:231], v[2:5]
	s_mov_b32 m0, s44
	global_load_dwordx2 v[200:201], v[138:139], off offset:0
	global_load_dwordx2 v[202:203], v[138:139], off offset:32
	global_load_dwordx2 v[204:205], v[138:139], off offset:128
	global_load_dwordx2 v[206:207], v[138:139], off offset:160
	v_lshl_add_u64 v[138:139], v[138:139], 0, s[4:5]
	global_load_dwordx2 v[208:209], v[138:139], off offset:0
	global_load_dwordx2 v[210:211], v[138:139], off offset:32
	global_load_dwordx2 v[212:213], v[138:139], off offset:128
	global_load_dwordx2 v[214:215], v[138:139], off offset:160
	v_lshl_add_u64 v[138:139], v[138:139], 0, s[4:5]
	s_nop 7
	s_waitcnt vmcnt(31)
	v_lshlrev_b32_e32 v216, 16, v146
	v_and_b32_e32 v146, 0xffff0000, v146
	v_lshlrev_b32_e32 v217, 16, v147
	v_and_b32_e32 v147, 0xffff0000, v147
	v_fmac_f32_e32 v126, s45, v216
	v_fmac_f32_e32 v127, s45, v146
	v_fmac_f32_e32 v128, s45, v217
	v_fmac_f32_e32 v129, s45, v147
	global_store_dwordx4 v[140:141], v[126:129], off offset:0
	s_waitcnt vmcnt(31)
	v_lshlrev_b32_e32 v216, 16, v148
	v_and_b32_e32 v148, 0xffff0000, v148
	v_lshlrev_b32_e32 v217, 16, v149
	v_and_b32_e32 v149, 0xffff0000, v149
	v_fmac_f32_e32 v94, s45, v216
	v_fmac_f32_e32 v95, s45, v148
	v_fmac_f32_e32 v96, s45, v217
	v_fmac_f32_e32 v97, s45, v149
	global_store_dwordx4 v[140:141], v[94:97], off offset:64
	s_waitcnt vmcnt(31)
	v_lshlrev_b32_e32 v216, 16, v152
	v_and_b32_e32 v152, 0xffff0000, v152
	v_lshlrev_b32_e32 v217, 16, v153
	v_and_b32_e32 v153, 0xffff0000, v153
	v_fmac_f32_e32 v62, s45, v216
	v_fmac_f32_e32 v63, s45, v152
	v_fmac_f32_e32 v64, s45, v217
	v_fmac_f32_e32 v65, s45, v153
	global_store_dwordx4 v[140:141], v[62:65], off offset:128
	s_waitcnt vmcnt(31)
; DEVI float blo(unsigned u) { return __uint_as_float(u << 16); }
; DEVI float bhi(unsigned u) { return __uint_as_float(u & 0xffff0000u); }
;     ...
;         if (EPI == EPI_RESID || EPI == EPI_RESID_ATOMIC) {
;           f32x4 x = a;
;           if (EPI == EPI_RESID || kpart == 0) {
;             const u32x2 xr = *(const u32x2*)((const u16*)(p.ws + WS_XB) + (size_t)row * 1024 + col);
;             x[0] += ALPHA * blo(xr[0]); x[1] += ALPHA * bhi(xr[0]); x[2] += ALPHA * blo(xr[1]); x[3] += ALPHA * bhi(xr[1]);
;           }
;           if (EPI == EPI_RESID) *(f32x4*)((float*)(p.ws + WS_XF) + (size_t)row * 1024 + col) = x;
;           else *(f32x4*)((float*)(p.ws + WS_SLAB) + ((size_t)kpart * 512 + (row - T_P)) * 1024 + col) = x;
	v_lshlrev_b32_e32 v216, 16, v154
	v_and_b32_e32 v154, 0xffff0000, v154
	v_lshlrev_b32_e32 v217, 16, v155
	v_and_b32_e32 v155, 0xffff0000, v155
	v_fmac_f32_e32 v30, s45, v216
	v_fmac_f32_e32 v31, s45, v154
	v_fmac_f32_e32 v32, s45, v217
	v_fmac_f32_e32 v33, s45, v155
	global_store_dwordx4 v[140:141], v[30:33], off offset:192
	v_lshl_add_u64 v[140:141], v[140:141], 0, s[10:11]
	s_waitcnt vmcnt(31)
	v_lshlrev_b32_e32 v216, 16, v156
	v_and_b32_e32 v156, 0xffff0000, v156
	v_lshlrev_b32_e32 v217, 16, v157
	v_and_b32_e32 v157, 0xffff0000, v157
	v_fmac_f32_e32 v122, s45, v216
	v_fmac_f32_e32 v123, s45, v156
	v_fmac_f32_e32 v124, s45, v217
	v_fmac_f32_e32 v125, s45, v157
	global_store_dwordx4 v[140:141], v[122:125], off offset:0
	s_waitcnt vmcnt(31)
	v_lshlrev_b32_e32 v216, 16, v158
	v_and_b32_e32 v158, 0xffff0000, v158
	v_lshlrev_b32_e32 v217, 16, v159
	v_and_b32_e32 v159, 0xffff0000, v159
	v_fmac_f32_e32 v90, s45, v216
	v_fmac_f32_e32 v91, s45, v158
	v_fmac_f32_e32 v92, s45, v217
	v_fmac_f32_e32 v93, s45, v159
	global_store_dwordx4 v[140:141], v[90:93], off offset:64
	s_waitcnt vmcnt(31)
	v_lshlrev_b32_e32 v216, 16, v162
	v_and_b32_e32 v162, 0xffff0000, v162
	v_lshlrev_b32_e32 v217, 16, v163
	v_and_b32_e32 v163, 0xffff0000, v163
	v_fmac_f32_e32 v58, s45, v216
	v_fmac_f32_e32 v59, s45, v162
	v_fmac_f32_e32 v60, s45, v217
	v_fmac_f32_e32 v61, s45, v163
	global_store_dwordx4 v[140:141], v[58:61], off offset:128
	s_waitcnt vmcnt(31)
	v_lshlrev_b32_e32 v216, 16, v164
	v_and_b32_e32 v164, 0xffff0000, v164
	v_lshlrev_b32_e32 v217, 16, v165
	v_and_b32_e32 v165, 0xffff0000, v165
	v_fmac_f32_e32 v26, s45, v216
	v_fmac_f32_e32 v27, s45, v164
	v_fmac_f32_e32 v28, s45, v217
	v_fmac_f32_e32 v29, s45, v165
	global_store_dwordx4 v[140:141], v[26:29], off offset:192
	v_lshl_add_u64 v[140:141], v[140:141], 0, s[10:11]
	s_waitcnt vmcnt(31)
	v_lshlrev_b32_e32 v216, 16, v166
	v_and_b32_e32 v166, 0xffff0000, v166
	v_lshlrev_b32_e32 v217, 16, v167
	v_and_b32_e32 v167, 0xffff0000, v167
	v_fmac_f32_e32 v118, s45, v216
	v_fmac_f32_e32 v119, s45, v166
	v_fmac_f32_e32 v120, s45, v217
	v_fmac_f32_e32 v121, s45, v167
	global_store_dwordx4 v[140:141], v[118:121], off offset:0
	s_waitcnt vmcnt(31)
	v_lshlrev_b32_e32 v216, 16, v168
	v_and_b32_e32 v168, 0xffff0000, v168
	v_lshlrev_b32_e32 v217, 16, v169
	v_and_b32_e32 v169, 0xffff0000, v169
	v_fmac_f32_e32 v86, s45, v216
	v_fmac_f32_e32 v87, s45, v168
	v_fmac_f32_e32 v88, s45, v217
	v_fmac_f32_e32 v89, s45, v169
	global_store_dwordx4 v[140:141], v[86:89], off offset:64
	s_waitcnt vmcnt(31)
	v_lshlrev_b32_e32 v216, 16, v170
	v_and_b32_e32 v170, 0xffff0000, v170
	v_lshlrev_b32_e32 v217, 16, v171
	v_and_b32_e32 v171, 0xffff0000, v171
	v_fmac_f32_e32 v54, s45, v216
	v_fmac_f32_e32 v55, s45, v170
	v_fmac_f32_e32 v56, s45, v217
	v_fmac_f32_e32 v57, s45, v171
	global_store_dwordx4 v[140:141], v[54:57], off offset:128
	s_waitcnt vmcnt(31)
	v_lshlrev_b32_e32 v216, 16, v172
	v_and_b32_e32 v172, 0xffff0000, v172
	v_lshlrev_b32_e32 v217, 16, v173
	v_and_b32_e32 v173, 0xffff0000, v173
	v_fmac_f32_e32 v22, s45, v216
	v_fmac_f32_e32 v23, s45, v172
	v_fmac_f32_e32 v24, s45, v217
	v_fmac_f32_e32 v25, s45, v173
	global_store_dwordx4 v[140:141], v[22:25], off offset:192
	v_lshl_add_u64 v[140:141], v[140:141], 0, s[10:11]
	s_waitcnt vmcnt(31)
	v_lshlrev_b32_e32 v216, 16, v176
	v_and_b32_e32 v176, 0xffff0000, v176
	v_lshlrev_b32_e32 v217, 16, v177
	v_and_b32_e32 v177, 0xffff0000, v177
	v_fmac_f32_e32 v114, s45, v216
	v_fmac_f32_e32 v115, s45, v176
	v_fmac_f32_e32 v116, s45, v217
	v_fmac_f32_e32 v117, s45, v177
	global_store_dwordx4 v[140:141], v[114:117], off offset:0
	s_waitcnt vmcnt(31)
	v_lshlrev_b32_e32 v216, 16, v178
	v_and_b32_e32 v178, 0xffff0000, v178
	v_lshlrev_b32_e32 v217, 16, v179
	v_and_b32_e32 v179, 0xffff0000, v179
	v_fmac_f32_e32 v82, s45, v216
	v_fmac_f32_e32 v83, s45, v178
	v_fmac_f32_e32 v84, s45, v217
	v_fmac_f32_e32 v85, s45, v179
	global_store_dwordx4 v[140:141], v[82:85], off offset:64
	s_waitcnt vmcnt(31)
	v_lshlrev_b32_e32 v216, 16, v180
	v_and_b32_e32 v180, 0xffff0000, v180
	v_lshlrev_b32_e32 v217, 16, v181
	v_and_b32_e32 v181, 0xffff0000, v181
	v_fmac_f32_e32 v50, s45, v216
	v_fmac_f32_e32 v51, s45, v180
	v_fmac_f32_e32 v52, s45, v217
	v_fmac_f32_e32 v53, s45, v181
	global_store_dwordx4 v[140:141], v[50:53], off offset:128
	s_waitcnt vmcnt(31)
	v_lshlrev_b32_e32 v216, 16, v182
	v_and_b32_e32 v182, 0xffff0000, v182
	v_lshlrev_b32_e32 v217, 16, v183
	v_and_b32_e32 v183, 0xffff0000, v183
	v_fmac_f32_e32 v18, s45, v216
	v_fmac_f32_e32 v19, s45, v182
	v_fmac_f32_e32 v20, s45, v217
	v_fmac_f32_e32 v21, s45, v183
	global_store_dwordx4 v[140:141], v[18:21], off offset:192
	v_lshl_add_u64 v[140:141], v[140:141], 0, s[10:11]
	s_waitcnt vmcnt(31)
	v_lshlrev_b32_e32 v216, 16, v184
	v_and_b32_e32 v184, 0xffff0000, v184
	v_lshlrev_b32_e32 v217, 16, v185
	v_and_b32_e32 v185, 0xffff0000, v185
	v_fmac_f32_e32 v110, s45, v216
	v_fmac_f32_e32 v111, s45, v184
	v_fmac_f32_e32 v112, s45, v217
	v_fmac_f32_e32 v113, s45, v185
	global_store_dwordx4 v[140:141], v[110:113], off offset:0
	s_waitcnt vmcnt(31)
; DEVI float blo(unsigned u) { return __uint_as_float(u << 16); }
; DEVI float bhi(unsigned u) { return __uint_as_float(u & 0xffff0000u); }
;     ...
;         if (EPI == EPI_RESID || EPI == EPI_RESID_ATOMIC) {
;           f32x4 x = a;
;           if (EPI == EPI_RESID || kpart == 0) {
;             const u32x2 xr = *(const u32x2*)((const u16*)(p.ws + WS_XB) + (size_t)row * 1024 + col);
;             x[0] += ALPHA * blo(xr[0]); x[1] += ALPHA * bhi(xr[0]); x[2] += ALPHA * blo(xr[1]); x[3] += ALPHA * bhi(xr[1]);
;           }
;           if (EPI == EPI_RESID) *(f32x4*)((float*)(p.ws + WS_XF) + (size_t)row * 1024 + col) = x;
;           else *(f32x4*)((float*)(p.ws + WS_SLAB) + ((size_t)kpart * 512 + (row - T_P)) * 1024 + col) = x;
	v_lshlrev_b32_e32 v216, 16, v186
	v_and_b32_e32 v186, 0xffff0000, v186
	v_lshlrev_b32_e32 v217, 16, v187
	v_and_b32_e32 v187, 0xffff0000, v187
	v_fmac_f32_e32 v78, s45, v216
	v_fmac_f32_e32 v79, s45, v186
	v_fmac_f32_e32 v80, s45, v217
	v_fmac_f32_e32 v81, s45, v187
	global_store_dwordx4 v[140:141], v[78:81], off offset:64
	s_waitcnt vmcnt(31)
	v_lshlrev_b32_e32 v216, 16, v188
	v_and_b32_e32 v188, 0xffff0000, v188
	v_lshlrev_b32_e32 v217, 16, v189
	v_and_b32_e32 v189, 0xffff0000, v189
	v_fmac_f32_e32 v46, s45, v216
	v_fmac_f32_e32 v47, s45, v188
	v_fmac_f32_e32 v48, s45, v217
	v_fmac_f32_e32 v49, s45, v189
	global_store_dwordx4 v[140:141], v[46:49], off offset:128
	s_waitcnt vmcnt(31)
	v_lshlrev_b32_e32 v216, 16, v190
	v_and_b32_e32 v190, 0xffff0000, v190
	v_lshlrev_b32_e32 v217, 16, v191
	v_and_b32_e32 v191, 0xffff0000, v191
	v_fmac_f32_e32 v14, s45, v216
	v_fmac_f32_e32 v15, s45, v190
	v_fmac_f32_e32 v16, s45, v217
	v_fmac_f32_e32 v17, s45, v191
	global_store_dwordx4 v[140:141], v[14:17], off offset:192
	v_lshl_add_u64 v[140:141], v[140:141], 0, s[10:11]
	s_waitcnt vmcnt(31)
	v_lshlrev_b32_e32 v216, 16, v192
	v_and_b32_e32 v192, 0xffff0000, v192
	v_lshlrev_b32_e32 v217, 16, v193
	v_and_b32_e32 v193, 0xffff0000, v193
	v_fmac_f32_e32 v106, s45, v216
	v_fmac_f32_e32 v107, s45, v192
	v_fmac_f32_e32 v108, s45, v217
	v_fmac_f32_e32 v109, s45, v193
	global_store_dwordx4 v[140:141], v[106:109], off offset:0
	s_waitcnt vmcnt(31)
	v_lshlrev_b32_e32 v216, 16, v194
	v_and_b32_e32 v194, 0xffff0000, v194
	v_lshlrev_b32_e32 v217, 16, v195
	v_and_b32_e32 v195, 0xffff0000, v195
	v_fmac_f32_e32 v74, s45, v216
	v_fmac_f32_e32 v75, s45, v194
	v_fmac_f32_e32 v76, s45, v217
	v_fmac_f32_e32 v77, s45, v195
	global_store_dwordx4 v[140:141], v[74:77], off offset:64
	s_waitcnt vmcnt(31)
	v_lshlrev_b32_e32 v216, 16, v196
	v_and_b32_e32 v196, 0xffff0000, v196
	v_lshlrev_b32_e32 v217, 16, v197
	v_and_b32_e32 v197, 0xffff0000, v197
	v_fmac_f32_e32 v42, s45, v216
	v_fmac_f32_e32 v43, s45, v196
	v_fmac_f32_e32 v44, s45, v217
	v_fmac_f32_e32 v45, s45, v197
	global_store_dwordx4 v[140:141], v[42:45], off offset:128
	s_waitcnt vmcnt(31)
	v_lshlrev_b32_e32 v216, 16, v198
	v_and_b32_e32 v198, 0xffff0000, v198
	v_lshlrev_b32_e32 v217, 16, v199
	v_and_b32_e32 v199, 0xffff0000, v199
	v_fmac_f32_e32 v10, s45, v216
	v_fmac_f32_e32 v11, s45, v198
	v_fmac_f32_e32 v12, s45, v217
	v_fmac_f32_e32 v13, s45, v199
	global_store_dwordx4 v[140:141], v[10:13], off offset:192
	v_lshl_add_u64 v[140:141], v[140:141], 0, s[10:11]
	s_waitcnt vmcnt(31)
	v_lshlrev_b32_e32 v216, 16, v200
	v_and_b32_e32 v200, 0xffff0000, v200
	v_lshlrev_b32_e32 v217, 16, v201
	v_and_b32_e32 v201, 0xffff0000, v201
	v_fmac_f32_e32 v102, s45, v216
	v_fmac_f32_e32 v103, s45, v200
	v_fmac_f32_e32 v104, s45, v217
	v_fmac_f32_e32 v105, s45, v201
	global_store_dwordx4 v[140:141], v[102:105], off offset:0
	s_waitcnt vmcnt(31)
	v_lshlrev_b32_e32 v216, 16, v202
	v_and_b32_e32 v202, 0xffff0000, v202
	v_lshlrev_b32_e32 v217, 16, v203
	v_and_b32_e32 v203, 0xffff0000, v203
	v_fmac_f32_e32 v70, s45, v216
	v_fmac_f32_e32 v71, s45, v202
	v_fmac_f32_e32 v72, s45, v217
	v_fmac_f32_e32 v73, s45, v203
	global_store_dwordx4 v[140:141], v[70:73], off offset:64
	s_waitcnt vmcnt(31)
	v_lshlrev_b32_e32 v216, 16, v204
	v_and_b32_e32 v204, 0xffff0000, v204
	v_lshlrev_b32_e32 v217, 16, v205
	v_and_b32_e32 v205, 0xffff0000, v205
	v_fmac_f32_e32 v38, s45, v216
	v_fmac_f32_e32 v39, s45, v204
	v_fmac_f32_e32 v40, s45, v217
	v_fmac_f32_e32 v41, s45, v205
	global_store_dwordx4 v[140:141], v[38:41], off offset:128
	s_waitcnt vmcnt(31)
	v_lshlrev_b32_e32 v216, 16, v206
	v_and_b32_e32 v206, 0xffff0000, v206
	v_lshlrev_b32_e32 v217, 16, v207
	v_and_b32_e32 v207, 0xffff0000, v207
	v_fmac_f32_e32 v6, s45, v216
	v_fmac_f32_e32 v7, s45, v206
	v_fmac_f32_e32 v8, s45, v217
	v_fmac_f32_e32 v9, s45, v207
	global_store_dwordx4 v[140:141], v[6:9], off offset:192
	v_lshl_add_u64 v[140:141], v[140:141], 0, s[10:11]
	s_waitcnt vmcnt(31)
	v_lshlrev_b32_e32 v216, 16, v208
	v_and_b32_e32 v208, 0xffff0000, v208
	v_lshlrev_b32_e32 v217, 16, v209
	v_and_b32_e32 v209, 0xffff0000, v209
	v_fmac_f32_e32 v98, s45, v216
	v_fmac_f32_e32 v99, s45, v208
	v_fmac_f32_e32 v100, s45, v217
	v_fmac_f32_e32 v101, s45, v209
	global_store_dwordx4 v[140:141], v[98:101], off offset:0
	s_waitcnt vmcnt(31)
	v_lshlrev_b32_e32 v216, 16, v210
	v_and_b32_e32 v210, 0xffff0000, v210
	v_lshlrev_b32_e32 v217, 16, v211
	v_and_b32_e32 v211, 0xffff0000, v211
	v_fmac_f32_e32 v66, s45, v216
	v_fmac_f32_e32 v67, s45, v210
	v_fmac_f32_e32 v68, s45, v217
	v_fmac_f32_e32 v69, s45, v211
	global_store_dwordx4 v[140:141], v[66:69], off offset:64
	s_waitcnt vmcnt(31)
	v_lshlrev_b32_e32 v216, 16, v212
	v_and_b32_e32 v212, 0xffff0000, v212
	v_lshlrev_b32_e32 v217, 16, v213
	v_and_b32_e32 v213, 0xffff0000, v213
	v_fmac_f32_e32 v34, s45, v216
	v_fmac_f32_e32 v35, s45, v212
	v_fmac_f32_e32 v36, s45, v217
	v_fmac_f32_e32 v37, s45, v213
	global_store_dwordx4 v[140:141], v[34:37], off offset:128
	s_waitcnt vmcnt(31)
	v_lshlrev_b32_e32 v216, 16, v214
	v_and_b32_e32 v214, 0xffff0000, v214
	v_lshlrev_b32_e32 v217, 16, v215
	v_and_b32_e32 v215, 0xffff0000, v215
	v_fmac_f32_e32 v2, s45, v216
	v_fmac_f32_e32 v3, s45, v214
	v_fmac_f32_e32 v4, s45, v217
	v_fmac_f32_e32 v5, s45, v215
	global_store_dwordx4 v[140:141], v[2:5], off offset:192
	s_branch .LBB0_757
.LBB0_837:
	s_mov_b64 s[2:3], 0

; DEVI unsigned pack2(float a, float b) { return __builtin_bit_cast(unsigned, __builtin_convertvector((f32x2_t){a, b}, bf16x2_t)); }
; DEVI void prologue_phase(const Params& p, char* smem) {
;     ...
;       for (int i = 0; i < 16; i++) { int idx = tid + i * 256; tile[(idx >> 6) * 65 + (idx & 63)] = rc[i]; }
;       __syncthreads();
; #pragma unroll
;       for (int i = 0; i < 2; i++) {
;         int idx = tid + i * 256; int nr = idx >> 3, kc = (idx & 7) * 8;
;         int n = jc.n0 + nr;
;         int drow = (jc.mode == 0) ? n : ((n >> 5) * 64 + (n & 31) + (jc.mode == 2 ? 32 : 0));
;         uint4 o;
;         o.x = pack2(tile[(kc + 0) * 65 + nr], tile[(kc + 1) * 65 + nr]);
;         o.y = pack2(tile[(kc + 2) * 65 + nr], tile[(kc + 3) * 65 + nr]);
;         o.z = pack2(tile[(kc + 4) * 65 + nr], tile[(kc + 5) * 65 + nr]);
;         o.w = pack2(tile[(kc + 6) * 65 + nr], tile[(kc + 7) * 65 + nr]);
;         *(uint4*)(jc.dst + (size_t)drow * jc.K + jc.k0 + kc) = o;
;       }
;       __syncthreads();
;       jc = jn;
; #pragma unroll
;       for (int i = 0; i < 16; i++) rc[i] = rn[i];
.LBB0_1913:
	s_cmp_eq_u32 s37, 0
	s_cselect_b64 vcc, -1, 0
	s_cmp_eq_u32 s37, 2
	s_cselect_b32 s3, 32, 0
	s_ashr_i32 s9, s8, 31
	s_lshl_b64 s[8:9], s[8:9], 1
	s_add_u32 s4, s4, s8
	s_waitcnt vmcnt(15)
	ds_write_b32 v24, v3
	s_waitcnt vmcnt(14)
	ds_write_b32 v25, v38
	s_waitcnt vmcnt(13)
	ds_write_b32 v26, v41
	s_waitcnt vmcnt(12)
	ds_write_b32 v27, v42
	s_waitcnt vmcnt(11)
	ds_write_b32 v28, v43
	s_waitcnt vmcnt(10)
	ds_write_b32 v29, v44
	s_waitcnt vmcnt(9)
	ds_write_b32 v30, v45
	s_waitcnt vmcnt(8)
	ds_write_b32 v31, v46
	s_waitcnt vmcnt(7)
	ds_write_b32 v32, v47
	s_waitcnt vmcnt(6)
	ds_write_b32 v33, v48
	s_waitcnt vmcnt(5)
	ds_write_b32 v34, v49
	s_waitcnt vmcnt(4)
	ds_write_b32 v35, v50
	s_waitcnt vmcnt(3)
	ds_write_b32 v36, v51
	s_waitcnt vmcnt(2)
	ds_write_b32 v37, v52
	s_waitcnt vmcnt(1)
	ds_write_b32 v39, v53
	s_waitcnt vmcnt(0)
	ds_write_b32 v40, v54
	s_addc_u32 s5, s5, s9
	v_readlane_b32 s99, v250, 5
	s_sub_u32 s98, s4, s99
	s_sub_u32 s99, s98, 0x14a00000
	s_cmp_lt_u32 s99, 0x1c00000
	s_cselect_b32 s99, 1, 0
	s_sub_u32 s98, s98, 0x16c00000
	s_cmp_lt_u32 s98, 0x4400000
	s_cselect_b32 s98, 1, s99
	s_and_b32 s99, s8, 0xffffffc0
	s_mul_i32 s99, s99, s98
	s_sub_i32 s9, s0, 32
	s_mul_i32 s9, s9, s98
	s_lshl_b32 s98, s98, 6
	v_mov_b32_e32 v3, v1
	s_waitcnt lgkmcnt(0)
	s_barrier
	v_lshl_add_u64 v[46:47], s[4:5], 0, v[2:3]
	v_and_b32_e32 v76, s98, v2
	v_add_u32_e32 v76, s99, v76
	v_mov_b32_e32 v77, 0
	v_lshl_add_u64 v[46:47], v[46:47], 0, v[76:77]
	v_add_u32_e32 v3, s6, v20
	ds_read2_b32 v[42:43], v21 offset1:65
	ds_read2_b32 v[44:45], v21 offset0:130 offset1:195
	v_lshlrev_b32_e32 v38, 1, v3
	v_and_b32_e32 v38, 0xffffffc0, v38
	v_and_b32_e32 v41, 31, v3
	v_or3_b32 v38, v41, v38, s3
	v_cndmask_b32_e32 v3, v38, v3, vcc
	v_add_u32_e32 v38, 0x400, v21
	s_waitcnt lgkmcnt(1)
	v_cvt_pk_bf16_f32 v42, v42, v43
	s_waitcnt lgkmcnt(0)
	v_cvt_pk_bf16_f32 v43, v44, v45
	ds_read2_b32 v[44:45], v38 offset0:4 offset1:69
	ds_read2_b32 v[48:49], v38 offset0:134 offset1:199
	v_ashrrev_i32_e32 v41, 31, v3
	s_mov_b32 s37, s42
	s_mov_b32 s8, s2
	s_waitcnt lgkmcnt(1)
	v_cvt_pk_bf16_f32 v44, v44, v45
	s_waitcnt lgkmcnt(0)
	v_cvt_pk_bf16_f32 v45, v48, v49
	v_mad_u64_u32 v[48:49], s[4:5], v3, s0, 0
	v_mov_b32_e32 v38, v49
	v_mad_u64_u32 v[50:51], s[4:5], v41, s0, v[38:39]
	v_mov_b32_e32 v49, v50
	v_and_b32_e32 v78, 1, v3
	v_mul_u32_u24_e32 v78, s9, v78
	v_sub_u32_e32 v48, v48, v78
	v_lshl_add_u64 v[48:49], v[48:49], 1, v[46:47]
	global_store_dwordx4 v[48:49], v[42:45], off
	v_add_u32_e32 v3, s6, v22
	ds_read2_b32 v[42:43], v23 offset1:65
	ds_read2_b32 v[44:45], v23 offset0:130 offset1:195
	v_lshlrev_b32_e32 v38, 1, v3
	v_and_b32_e32 v38, 0xffffffc0, v38
	v_and_b32_e32 v41, 31, v3
	v_or3_b32 v38, v41, v38, s3
	v_cndmask_b32_e32 v3, v38, v3, vcc
	v_add_u32_e32 v38, 0x400, v23
	s_waitcnt lgkmcnt(1)
	v_cvt_pk_bf16_f32 v42, v42, v43
	s_waitcnt lgkmcnt(0)
	v_cvt_pk_bf16_f32 v43, v44, v45
	ds_read2_b32 v[44:45], v38 offset0:4 offset1:69
	ds_read2_b32 v[48:49], v38 offset0:134 offset1:199
	v_ashrrev_i32_e32 v41, 31, v3
	s_andn2_b64 vcc, exec, s[12:13]
	s_mov_b32 s6, s38
	s_waitcnt lgkmcnt(1)
	v_cvt_pk_bf16_f32 v44, v44, v45
	s_waitcnt lgkmcnt(0)
	v_cvt_pk_bf16_f32 v45, v48, v49
	v_mad_u64_u32 v[48:49], s[4:5], v3, s0, 0
	v_mov_b32_e32 v38, v49
	v_mad_u64_u32 v[50:51], s[4:5], v41, s0, v[38:39]
	v_mov_b32_e32 v49, v50
	v_and_b32_e32 v78, 1, v3
	v_mul_u32_u24_e32 v78, s9, v78
	v_sub_u32_e32 v48, v48, v78
	v_lshl_add_u64 v[46:47], v[48:49], 1, v[46:47]
	global_store_dwordx4 v[46:47], v[42:45], off
	s_mov_b64 s[4:5], s[10:11]
	s_mov_b32 s0, s36
	v_mov_b32_e32 v3, v55
	v_mov_b32_e32 v38, v56
	v_mov_b32_e32 v41, v57
	v_mov_b32_e32 v42, v58
	v_mov_b32_e32 v43, v59
	v_mov_b32_e32 v44, v60
	v_mov_b32_e32 v45, v61
	v_mov_b32_e32 v46, v62
	v_mov_b32_e32 v47, v63
	v_mov_b32_e32 v48, v64
	v_mov_b32_e32 v49, v65
	v_mov_b32_e32 v50, v66
	v_mov_b32_e32 v51, v67
	v_mov_b32_e32 v52, v68
	v_mov_b32_e32 v53, v69
	v_mov_b32_e32 v54, v70
	s_barrier
	s_cbranch_vccz .LBB0_1947
